# residual epilogue: per-row-group sum of 16 squares accumulated with v_pk_mul + 7 v_pk_fma + 1 v_add (f32) instead of 8 v_pk_mul + 15 serial v_add
# speedup vs baseline: 1.0029x; 1.0029x over previous
.LBB0_31:
	s_add_u32 s46, s50, 0x100
	s_addc_u32 s47, s51, 0
	s_add_i32 s6, 0, 0x10000
	v_add_u32_e32 v146, s6, v206
	ds_read_b128 v[128:131], v146
	ds_read_b128 v[132:135], v146 offset:1024
	ds_read_b128 v[136:139], v146 offset:2048
	ds_read_b128 v[146:149], v146 offset:3072
	s_cmp_eq_u32 s12, 40
	s_cselect_b32 s53, s31, s47
	s_cselect_b32 s52, s30, s46
	s_cselect_b32 s49, s35, s11
	s_cselect_b32 s48, s34, s10
	v_lshl_add_u64 v[214:215], s[50:51], 0, v[158:159]
	s_add_i32 m0, s58, 0xc000
	ds_read_b128 v[162:165], v208
	ds_read_b128 v[166:169], v208 offset:1024
	ds_read_b128 v[170:173], v208 offset:2048
	ds_read_b128 v[174:177], v208 offset:3072
	ds_read_b128 v[178:181], v208 offset:4096
	ds_read_b128 v[182:185], v208 offset:5120
	ds_read_b128 v[194:197], v208 offset:6144
	ds_read_b128 v[210:213], v208 offset:7168
	global_load_lds_dwordx4 v[214:215], off
	v_lshl_add_u64 v[214:215], s[50:51], 0, v[160:161]
	s_add_i32 m0, s58, 0xe000
	s_nop 0
	global_load_lds_dwordx4 v[214:215], off
	s_add_i32 s19, 0, 0x14000
	v_add_u32_e32 v192, s19, v206
	ds_read_b128 v[214:217], v192
	ds_read_b128 v[218:221], v192 offset:1024
	ds_read_b128 v[222:225], v192 offset:2048
	ds_read_b128 v[226:229], v192 offset:3072
	s_nop 0
	s_waitcnt vmcnt(8)
	s_waitcnt lgkmcnt(0)
	s_barrier
	v_mfma_f32_16x16x32_bf16 v[124:127], v[128:131], v[162:165], v[124:127]
	v_mfma_f32_16x16x32_bf16 v[120:123], v[136:139], v[162:165], v[120:123]
	v_mfma_f32_16x16x32_bf16 v[108:111], v[128:131], v[170:173], v[108:111]
	v_mfma_f32_16x16x32_bf16 v[104:107], v[136:139], v[170:173], v[104:107]
	v_mfma_f32_16x16x32_bf16 v[96:99], v[128:131], v[178:181], v[96:99]
	v_mfma_f32_16x16x32_bf16 v[88:91], v[136:139], v[178:181], v[88:91]
	v_mfma_f32_16x16x32_bf16 v[84:87], v[128:131], v[194:197], v[84:87]
	v_mfma_f32_16x16x32_bf16 v[80:83], v[136:139], v[194:197], v[80:83]
	v_mfma_f32_16x16x32_bf16 v[124:127], v[132:135], v[166:169], v[124:127]
	v_mfma_f32_16x16x32_bf16 v[120:123], v[146:149], v[166:169], v[120:123]
	v_mfma_f32_16x16x32_bf16 v[108:111], v[132:135], v[174:177], v[108:111]
	v_mfma_f32_16x16x32_bf16 v[104:107], v[146:149], v[174:177], v[104:107]
	v_mfma_f32_16x16x32_bf16 v[96:99], v[132:135], v[182:185], v[96:99]
	v_mfma_f32_16x16x32_bf16 v[88:91], v[146:149], v[182:185], v[88:91]
	v_mfma_f32_16x16x32_bf16 v[84:87], v[132:135], v[210:213], v[84:87]
	v_mfma_f32_16x16x32_bf16 v[80:83], v[146:149], v[210:213], v[80:83]
	v_mfma_f32_16x16x32_bf16 v[116:119], v[214:217], v[162:165], v[116:119]
	v_mfma_f32_16x16x32_bf16 v[112:115], v[222:225], v[162:165], v[112:115]
	v_mfma_f32_16x16x32_bf16 v[100:103], v[214:217], v[170:173], v[100:103]
	v_mfma_f32_16x16x32_bf16 v[92:95], v[222:225], v[170:173], v[92:95]
	v_mfma_f32_16x16x32_bf16 v[76:79], v[214:217], v[178:181], v[76:79]
	v_mfma_f32_16x16x32_bf16 v[72:75], v[222:225], v[178:181], v[72:75]
	v_mfma_f32_16x16x32_bf16 v[68:71], v[214:217], v[194:197], v[68:71]
	v_mfma_f32_16x16x32_bf16 v[64:67], v[222:225], v[194:197], v[64:67]
	v_mfma_f32_16x16x32_bf16 v[116:119], v[218:221], v[166:169], v[116:119]
	v_mfma_f32_16x16x32_bf16 v[112:115], v[226:229], v[166:169], v[112:115]
	v_mfma_f32_16x16x32_bf16 v[100:103], v[218:221], v[174:177], v[100:103]
	v_mfma_f32_16x16x32_bf16 v[92:95], v[226:229], v[174:177], v[92:95]
	v_mfma_f32_16x16x32_bf16 v[76:79], v[218:221], v[182:185], v[76:79]
	v_mfma_f32_16x16x32_bf16 v[72:75], v[226:229], v[182:185], v[72:75]
	v_mfma_f32_16x16x32_bf16 v[68:71], v[218:221], v[210:213], v[68:71]
	v_mfma_f32_16x16x32_bf16 v[64:67], v[226:229], v[210:213], v[64:67]
	s_barrier
	s_add_i32 s6, s6, s57
	v_lshl_add_u64 v[230:231], s[48:49], 0, v[140:141]
	s_mov_b32 m0, s6
	s_nop 0
	global_load_lds_dwordx4 v[230:231], off
	v_lshl_add_u64 v[232:233], s[48:49], 0, v[150:151]
	s_add_i32 m0, s6, 0x2000
	s_nop 0
	global_load_lds_dwordx4 v[232:233], off
	s_mov_b32 m0, s58
	v_lshl_add_u64 v[234:235], s[52:53], 0, v[154:155]
	ds_read_b128 v[162:165], v208 offset:16384
	ds_read_b128 v[166:169], v208 offset:17408
	ds_read_b128 v[170:173], v208 offset:18432
	ds_read_b128 v[174:177], v208 offset:19456
	ds_read_b128 v[178:181], v208 offset:20480
	ds_read_b128 v[182:185], v208 offset:21504
	ds_read_b128 v[194:197], v208 offset:22528
	ds_read_b128 v[210:213], v208 offset:23552
	global_load_lds_dwordx4 v[234:235], off
	v_lshl_add_u64 v[236:237], s[52:53], 0, v[152:153]
	s_mov_b32 m0, s59
	s_nop 0
	global_load_lds_dwordx4 v[236:237], off
	s_add_u32 s50, s48, 0xb0000
	s_addc_u32 s51, s49, 0
	s_add_i32 s6, s19, s57
	v_lshl_add_u64 v[250:251], s[50:51], 0, v[140:141]
	s_mov_b32 m0, s6
	s_nop 0
	global_load_lds_dwordx4 v[250:251], off
	v_lshl_add_u64 v[250:251], s[50:51], 0, v[150:151]
	s_add_i32 m0, s6, 0x2000
	s_nop 0
	global_load_lds_dwordx4 v[250:251], off
	s_waitcnt vmcnt(8)
	s_waitcnt lgkmcnt(0)
	s_barrier
	v_mfma_f32_16x16x32_bf16 v[60:63], v[128:131], v[162:165], v[60:63]
	v_mfma_f32_16x16x32_bf16 v[56:59], v[136:139], v[162:165], v[56:59]
	v_mfma_f32_16x16x32_bf16 v[48:51], v[128:131], v[170:173], v[48:51]
	v_mfma_f32_16x16x32_bf16 v[40:43], v[136:139], v[170:173], v[40:43]
	v_mfma_f32_16x16x32_bf16 v[32:35], v[128:131], v[178:181], v[32:35]
	v_mfma_f32_16x16x32_bf16 v[24:27], v[136:139], v[178:181], v[24:27]
	v_mfma_f32_16x16x32_bf16 v[16:19], v[128:131], v[194:197], v[16:19]
	v_mfma_f32_16x16x32_bf16 v[8:11], v[136:139], v[194:197], v[8:11]
	v_mfma_f32_16x16x32_bf16 v[60:63], v[132:135], v[166:169], v[60:63]
	v_mfma_f32_16x16x32_bf16 v[56:59], v[146:149], v[166:169], v[56:59]
	v_mfma_f32_16x16x32_bf16 v[48:51], v[132:135], v[174:177], v[48:51]
	v_mfma_f32_16x16x32_bf16 v[40:43], v[146:149], v[174:177], v[40:43]
	v_mfma_f32_16x16x32_bf16 v[32:35], v[132:135], v[182:185], v[32:35]
	v_mfma_f32_16x16x32_bf16 v[24:27], v[146:149], v[182:185], v[24:27]
	v_mfma_f32_16x16x32_bf16 v[16:19], v[132:135], v[210:213], v[16:19]
	v_mfma_f32_16x16x32_bf16 v[8:11], v[146:149], v[210:213], v[8:11]
	v_mfma_f32_16x16x32_bf16 v[52:55], v[214:217], v[162:165], v[52:55]
	v_mfma_f32_16x16x32_bf16 v[44:47], v[222:225], v[162:165], v[44:47]
	v_mfma_f32_16x16x32_bf16 v[36:39], v[214:217], v[170:173], v[36:39]
	v_mfma_f32_16x16x32_bf16 v[28:31], v[222:225], v[170:173], v[28:31]
	v_mfma_f32_16x16x32_bf16 v[20:23], v[214:217], v[178:181], v[20:23]
	v_mfma_f32_16x16x32_bf16 v[12:15], v[222:225], v[178:181], v[12:15]
	v_mfma_f32_16x16x32_bf16 v[4:7], v[214:217], v[194:197], v[4:7]
	v_mfma_f32_16x16x32_bf16 v[0:3], v[222:225], v[194:197], v[0:3]
	v_mfma_f32_16x16x32_bf16 v[52:55], v[218:221], v[166:169], v[52:55]
	v_mfma_f32_16x16x32_bf16 v[44:47], v[226:229], v[166:169], v[44:47]
	v_mfma_f32_16x16x32_bf16 v[36:39], v[218:221], v[174:177], v[36:39]
	v_mfma_f32_16x16x32_bf16 v[28:31], v[226:229], v[174:177], v[28:31]
	v_mfma_f32_16x16x32_bf16 v[20:23], v[218:221], v[182:185], v[20:23]
	v_mfma_f32_16x16x32_bf16 v[12:15], v[226:229], v[182:185], v[12:15]
	v_mfma_f32_16x16x32_bf16 v[4:7], v[218:221], v[210:213], v[4:7]
	v_mfma_f32_16x16x32_bf16 v[0:3], v[226:229], v[210:213], v[0:3]
	s_barrier
	s_add_i32 s6, 0, 0x18000
	v_add_u32_e32 v146, s6, v206
	ds_read_b128 v[128:131], v146
	ds_read_b128 v[132:135], v146 offset:1024
	ds_read_b128 v[136:139], v146 offset:2048
	ds_read_b128 v[146:149], v146 offset:3072
	s_add_u32 s50, s52, 0xb0000
	s_addc_u32 s51, s53, 0
	s_mov_b32 m0, s68
	v_lshl_add_u64 v[214:215], s[50:51], 0, v[154:155]
	ds_read_b128 v[162:165], v208 offset:32768
	ds_read_b128 v[166:169], v208 offset:33792
	ds_read_b128 v[170:173], v208 offset:34816
	ds_read_b128 v[174:177], v208 offset:35840
	ds_read_b128 v[178:181], v208 offset:36864
	ds_read_b128 v[182:185], v208 offset:37888
	ds_read_b128 v[194:197], v208 offset:38912
	ds_read_b128 v[210:213], v208 offset:39936
	global_load_lds_dwordx4 v[214:215], off
	v_lshl_add_u64 v[214:215], s[50:51], 0, v[152:153]
	s_mov_b32 m0, s69
	s_nop 0
	global_load_lds_dwordx4 v[214:215], off
	s_add_i32 s19, 0, 0x1c000
	v_add_u32_e32 v192, s19, v206
	ds_read_b128 v[214:217], v192
	ds_read_b128 v[218:221], v192 offset:1024
	ds_read_b128 v[222:225], v192 offset:2048
	ds_read_b128 v[226:229], v192 offset:3072
	s_waitcnt vmcnt(8)
	s_waitcnt lgkmcnt(0)
	s_barrier
	v_mfma_f32_16x16x32_bf16 v[124:127], v[128:131], v[162:165], v[124:127]
	v_mfma_f32_16x16x32_bf16 v[120:123], v[136:139], v[162:165], v[120:123]
	v_mfma_f32_16x16x32_bf16 v[108:111], v[128:131], v[170:173], v[108:111]
	v_mfma_f32_16x16x32_bf16 v[104:107], v[136:139], v[170:173], v[104:107]
	v_mfma_f32_16x16x32_bf16 v[96:99], v[128:131], v[178:181], v[96:99]
	v_mfma_f32_16x16x32_bf16 v[88:91], v[136:139], v[178:181], v[88:91]
	v_mfma_f32_16x16x32_bf16 v[84:87], v[128:131], v[194:197], v[84:87]
	v_mfma_f32_16x16x32_bf16 v[80:83], v[136:139], v[194:197], v[80:83]
	v_mfma_f32_16x16x32_bf16 v[124:127], v[132:135], v[166:169], v[124:127]
	v_mfma_f32_16x16x32_bf16 v[120:123], v[146:149], v[166:169], v[120:123]
	v_mfma_f32_16x16x32_bf16 v[108:111], v[132:135], v[174:177], v[108:111]
	v_mfma_f32_16x16x32_bf16 v[104:107], v[146:149], v[174:177], v[104:107]
	v_mfma_f32_16x16x32_bf16 v[96:99], v[132:135], v[182:185], v[96:99]
	v_mfma_f32_16x16x32_bf16 v[88:91], v[146:149], v[182:185], v[88:91]
	v_mfma_f32_16x16x32_bf16 v[84:87], v[132:135], v[210:213], v[84:87]
	v_mfma_f32_16x16x32_bf16 v[80:83], v[146:149], v[210:213], v[80:83]
	v_mfma_f32_16x16x32_bf16 v[116:119], v[214:217], v[162:165], v[116:119]
	v_mfma_f32_16x16x32_bf16 v[112:115], v[222:225], v[162:165], v[112:115]
	v_mfma_f32_16x16x32_bf16 v[100:103], v[214:217], v[170:173], v[100:103]
	v_mfma_f32_16x16x32_bf16 v[92:95], v[222:225], v[170:173], v[92:95]
	v_mfma_f32_16x16x32_bf16 v[76:79], v[214:217], v[178:181], v[76:79]
	v_mfma_f32_16x16x32_bf16 v[72:75], v[222:225], v[178:181], v[72:75]
	v_mfma_f32_16x16x32_bf16 v[68:71], v[214:217], v[194:197], v[68:71]
	v_mfma_f32_16x16x32_bf16 v[64:67], v[222:225], v[194:197], v[64:67]
	v_mfma_f32_16x16x32_bf16 v[116:119], v[218:221], v[166:169], v[116:119]
	v_mfma_f32_16x16x32_bf16 v[112:115], v[226:229], v[166:169], v[112:115]
	v_mfma_f32_16x16x32_bf16 v[100:103], v[218:221], v[174:177], v[100:103]
	v_mfma_f32_16x16x32_bf16 v[92:95], v[226:229], v[174:177], v[92:95]
	v_mfma_f32_16x16x32_bf16 v[76:79], v[218:221], v[182:185], v[76:79]
	v_mfma_f32_16x16x32_bf16 v[72:75], v[226:229], v[182:185], v[72:75]
	v_mfma_f32_16x16x32_bf16 v[68:71], v[218:221], v[210:213], v[68:71]
	v_mfma_f32_16x16x32_bf16 v[64:67], v[226:229], v[210:213], v[64:67]
	s_barrier
	s_add_i32 s6, s6, s57
	v_lshl_add_u64 v[230:231], v[230:231], 0, s[36:37]
	s_mov_b32 m0, s6
	s_nop 0
	global_load_lds_dwordx4 v[230:231], off
	v_lshl_add_u64 v[230:231], v[232:233], 0, s[36:37]
	s_add_i32 m0, s6, 0x2000
	s_nop 0
	global_load_lds_dwordx4 v[230:231], off
	s_mov_b32 m0, s70
	v_lshl_add_u64 v[230:231], v[234:235], 0, s[36:37]
	ds_read_b128 v[162:165], v208 offset:49152
	ds_read_b128 v[166:169], v208 offset:50176
	ds_read_b128 v[170:173], v208 offset:51200
	ds_read_b128 v[174:177], v208 offset:52224
	ds_read_b128 v[178:181], v208 offset:53248
	ds_read_b128 v[182:185], v208 offset:54272
	ds_read_b128 v[194:197], v208 offset:55296
	ds_read_b128 v[210:213], v208 offset:56320
	global_load_lds_dwordx4 v[230:231], off
	v_lshl_add_u64 v[230:231], v[236:237], 0, s[36:37]
	s_mov_b32 m0, s71
	s_nop 0
	global_load_lds_dwordx4 v[230:231], off
	s_add_u32 s48, s48, 0xb0080
	s_addc_u32 s49, s49, 0
	s_add_i32 s6, s19, s57
	v_lshl_add_u64 v[250:251], s[48:49], 0, v[140:141]
	s_mov_b32 m0, s6
	s_nop 0
	global_load_lds_dwordx4 v[250:251], off
	v_lshl_add_u64 v[250:251], s[48:49], 0, v[150:151]
	s_add_i32 m0, s6, 0x2000
	s_nop 0
	global_load_lds_dwordx4 v[250:251], off
	s_add_i32 s12, s12, 2
	s_add_u32 s10, s10, 0x100
	s_addc_u32 s11, s11, 0
	s_cmp_gt_u32 s12, 41
	s_mov_b64 s[50:51], s[46:47]
	s_waitcnt vmcnt(8)
	s_waitcnt lgkmcnt(0)
	s_barrier
	v_mfma_f32_16x16x32_bf16 v[60:63], v[128:131], v[162:165], v[60:63]
	v_mfma_f32_16x16x32_bf16 v[56:59], v[136:139], v[162:165], v[56:59]
	v_mfma_f32_16x16x32_bf16 v[48:51], v[128:131], v[170:173], v[48:51]
	v_mfma_f32_16x16x32_bf16 v[40:43], v[136:139], v[170:173], v[40:43]
	v_mfma_f32_16x16x32_bf16 v[32:35], v[128:131], v[178:181], v[32:35]
	v_mfma_f32_16x16x32_bf16 v[24:27], v[136:139], v[178:181], v[24:27]
	v_mfma_f32_16x16x32_bf16 v[16:19], v[128:131], v[194:197], v[16:19]
	v_mfma_f32_16x16x32_bf16 v[8:11], v[136:139], v[194:197], v[8:11]
	v_mfma_f32_16x16x32_bf16 v[60:63], v[132:135], v[166:169], v[60:63]
	v_mfma_f32_16x16x32_bf16 v[56:59], v[146:149], v[166:169], v[56:59]
	v_mfma_f32_16x16x32_bf16 v[48:51], v[132:135], v[174:177], v[48:51]
	v_mfma_f32_16x16x32_bf16 v[40:43], v[146:149], v[174:177], v[40:43]
	v_mfma_f32_16x16x32_bf16 v[32:35], v[132:135], v[182:185], v[32:35]
	v_mfma_f32_16x16x32_bf16 v[24:27], v[146:149], v[182:185], v[24:27]
	v_mfma_f32_16x16x32_bf16 v[16:19], v[132:135], v[210:213], v[16:19]
	v_mfma_f32_16x16x32_bf16 v[8:11], v[146:149], v[210:213], v[8:11]
	v_mfma_f32_16x16x32_bf16 v[52:55], v[214:217], v[162:165], v[52:55]
	v_mfma_f32_16x16x32_bf16 v[44:47], v[222:225], v[162:165], v[44:47]
	v_mfma_f32_16x16x32_bf16 v[36:39], v[214:217], v[170:173], v[36:39]
	v_mfma_f32_16x16x32_bf16 v[28:31], v[222:225], v[170:173], v[28:31]
	v_mfma_f32_16x16x32_bf16 v[20:23], v[214:217], v[178:181], v[20:23]
	v_mfma_f32_16x16x32_bf16 v[12:15], v[222:225], v[178:181], v[12:15]
	v_mfma_f32_16x16x32_bf16 v[4:7], v[214:217], v[194:197], v[4:7]
	v_mfma_f32_16x16x32_bf16 v[0:3], v[222:225], v[194:197], v[0:3]
	v_mfma_f32_16x16x32_bf16 v[52:55], v[218:221], v[166:169], v[52:55]
	v_mfma_f32_16x16x32_bf16 v[44:47], v[226:229], v[166:169], v[44:47]
	v_mfma_f32_16x16x32_bf16 v[36:39], v[218:221], v[174:177], v[36:39]
	v_mfma_f32_16x16x32_bf16 v[28:31], v[226:229], v[174:177], v[28:31]
	v_mfma_f32_16x16x32_bf16 v[20:23], v[218:221], v[182:185], v[20:23]
	v_mfma_f32_16x16x32_bf16 v[12:15], v[226:229], v[182:185], v[12:15]
	v_mfma_f32_16x16x32_bf16 v[4:7], v[218:221], v[210:213], v[4:7]
	v_mfma_f32_16x16x32_bf16 v[0:3], v[226:229], v[210:213], v[0:3]
	s_barrier
	s_cbranch_scc0 .LBB0_31
	s_mov_b32 s100, 1
	s_ashr_i32 s39, s38, 31
	v_lshl_or_b32 v128, s81, 8, v207
	s_lshl_b64 s[10:11], s[38:39], 8
	v_ashrrev_i32_e32 v129, 31, v128
	v_lshl_add_u64 v[168:169], s[10:11], 0, v[156:157]
	v_lshlrev_b64 v[170:171], 1, v[128:129]
	v_lshl_add_u64 v[174:175], s[4:5], 0, v[170:171]
	v_lshlrev_b64 v[172:173], 11, v[168:169]
	v_lshl_add_u64 v[128:129], v[174:175], 0, v[172:173]
	global_load_dwordx4 v[146:149], v[128:129], off
	global_load_dwordx4 v[182:185], v[128:129], off offset:256
	v_or_b32_e32 v166, 16, v168
	v_mov_b32_e32 v167, v169
	v_lshlrev_b64 v[176:177], 11, v[166:167]
	v_lshl_add_u64 v[128:129], v[174:175], 0, v[176:177]
	global_load_dwordx4 v[194:197], v[128:129], off
	global_load_dwordx4 v[210:213], v[128:129], off offset:256
	v_or_b32_e32 v164, 32, v168
	v_mov_b32_e32 v165, v169
	v_or_b32_e32 v162, 48, v168
	v_mov_b32_e32 v163, v169
	v_lshlrev_b64 v[180:181], 11, v[164:165]
	v_lshlrev_b64 v[178:179], 11, v[162:163]
	v_lshl_add_u64 v[128:129], v[174:175], 0, v[180:181]
	v_lshl_add_u64 v[130:131], v[174:175], 0, v[178:179]
	global_load_dwordx4 v[214:217], v[128:129], off
	global_load_dwordx4 v[136:139], v[128:129], off offset:256
	global_load_dwordx4 v[132:135], v[130:131], off
	s_nop 0
	global_load_dwordx4 v[128:131], v[130:131], off offset:256
	s_mov_b64 s[10:11], 0x90
	v_lshl_add_u64 v[172:173], s[28:29], 0, v[172:173]
	v_lshl_add_u64 v[172:173], v[172:173], 0, v[170:171]
	s_waitcnt vmcnt(0)
	v_lshlrev_b32_e32 v218, 16, v146
	v_and_b32_e32 v219, 0xffff0000, v146
	v_lshlrev_b32_e32 v220, 16, v148
	v_and_b32_e32 v221, 0xffff0000, v148
	v_lshlrev_b32_e32 v146, 16, v147
	v_and_b32_e32 v147, 0xffff0000, v147
	v_lshlrev_b32_e32 v222, 16, v182
	v_and_b32_e32 v223, 0xffff0000, v182
	v_lshlrev_b32_e32 v224, 16, v184
	v_and_b32_e32 v225, 0xffff0000, v184
	v_lshlrev_b32_e32 v182, 16, v183
	v_and_b32_e32 v183, 0xffff0000, v183
	v_pk_fma_f32 v[124:125], v[124:125], 0.5, v[218:219] op_sel_hi:[1,0,1]
	v_pk_fma_f32 v[120:121], v[120:121], 0.5, v[220:221] op_sel_hi:[1,0,1]
	v_pk_fma_f32 v[126:127], v[126:127], 0.5, v[146:147] op_sel_hi:[1,0,1]
	v_pk_fma_f32 v[116:117], v[116:117], 0.5, v[222:223] op_sel_hi:[1,0,1]
	v_pk_fma_f32 v[146:147], v[112:113], 0.5, v[224:225] op_sel_hi:[1,0,1]
	v_pk_fma_f32 v[118:119], v[118:119], 0.5, v[182:183] op_sel_hi:[1,0,1]
	v_pk_mul_f32 v[220:221], v[124:125], v[124:125]
	v_pk_mul_f32 v[222:223], v[126:127], v[126:127]
	v_cvt_pk_bf16_f32 v112, v124, v125
	v_cvt_pk_bf16_f32 v113, v126, v127
	v_pk_mul_f32 v[124:125], v[116:117], v[116:117]
	v_pk_mul_f32 v[126:127], v[118:119], v[118:119]
	v_pk_mul_f32 v[228:229], v[146:147], v[146:147]
	v_cvt_pk_bf16_f32 v116, v116, v117
	v_cvt_pk_bf16_f32 v117, v118, v119
	v_cvt_pk_bf16_f32 v118, v146, v147
	v_add_f32_e32 v146, v220, v221
	v_add_f32_e32 v146, v222, v146
	v_lshlrev_b32_e32 v148, 16, v149
	v_and_b32_e32 v149, 0xffff0000, v149
	v_pk_mul_f32 v[224:225], v[120:121], v[120:121]
	v_add_f32_e32 v146, v223, v146
	v_pk_fma_f32 v[122:123], v[122:123], 0.5, v[148:149] op_sel_hi:[1,0,1]
	v_add_f32_e32 v146, v224, v146
	v_pk_mul_f32 v[226:227], v[122:123], v[122:123]
	v_add_f32_e32 v146, v225, v146
	v_add_f32_e32 v146, v226, v146
	v_add_f32_e32 v146, v227, v146
	v_add_f32_e32 v124, v124, v146
	v_add_f32_e32 v124, v125, v124
	v_add_f32_e32 v124, v126, v124
	v_lshlrev_b32_e32 v184, 16, v185
	v_and_b32_e32 v185, 0xffff0000, v185
	v_add_f32_e32 v124, v127, v124
	v_pk_fma_f32 v[148:149], v[114:115], 0.5, v[184:185] op_sel_hi:[1,0,1]
	v_add_f32_e32 v124, v228, v124
	v_pk_mul_f32 v[230:231], v[148:149], v[148:149]
	v_add_f32_e32 v124, v229, v124
	v_add_f32_e32 v124, v230, v124
	v_add_f32_e32 v209, v231, v124
	v_lshlrev_b32_e32 v124, 16, v212
	v_and_b32_e32 v125, 0xffff0000, v212
	v_pk_fma_f32 v[124:125], v[92:93], 0.5, v[124:125] op_sel_hi:[1,0,1]
	v_lshlrev_b32_e32 v92, 16, v211
	v_and_b32_e32 v93, 0xffff0000, v211
	v_pk_fma_f32 v[102:103], v[102:103], 0.5, v[92:93] op_sel_hi:[1,0,1]
	v_lshlrev_b32_e32 v92, 16, v213
	v_and_b32_e32 v93, 0xffff0000, v213
	v_pk_fma_f32 v[126:127], v[94:95], 0.5, v[92:93] op_sel_hi:[1,0,1]
	v_lshlrev_b32_e32 v92, 16, v214
	v_and_b32_e32 v93, 0xffff0000, v214
	v_pk_fma_f32 v[92:93], v[96:97], 0.5, v[92:93] op_sel_hi:[1,0,1]
	v_lshlrev_b32_e32 v96, 16, v217
	v_and_b32_e32 v97, 0xffff0000, v217
	v_lshlrev_b32_e32 v94, 16, v216
	v_and_b32_e32 v95, 0xffff0000, v216
	v_pk_fma_f32 v[90:91], v[90:91], 0.5, v[96:97] op_sel_hi:[1,0,1]
	v_lshlrev_b32_e32 v96, 16, v136
	v_and_b32_e32 v97, 0xffff0000, v136
	v_lshlrev_b32_e32 v182, 16, v194
	v_and_b32_e32 v183, 0xffff0000, v194
	v_pk_fma_f32 v[88:89], v[88:89], 0.5, v[94:95] op_sel_hi:[1,0,1]
	v_lshlrev_b32_e32 v94, 16, v215
	v_and_b32_e32 v95, 0xffff0000, v215
	v_pk_fma_f32 v[96:97], v[76:77], 0.5, v[96:97] op_sel_hi:[1,0,1]
	v_lshl_add_u64 v[76:77], v[168:169], 0, s[36:37]
	v_lshlrev_b32_e32 v184, 16, v196
	v_and_b32_e32 v185, 0xffff0000, v196
	v_cvt_pk_bf16_f32 v114, v120, v121
	v_pk_fma_f32 v[120:121], v[108:109], 0.5, v[182:183] op_sel_hi:[1,0,1]
	v_pk_fma_f32 v[94:95], v[98:99], 0.5, v[94:95] op_sel_hi:[1,0,1]
	v_lshlrev_b64 v[182:183], 11, v[76:77]
	v_lshlrev_b32_e32 v98, 16, v138
	v_and_b32_e32 v99, 0xffff0000, v138
	v_pk_fma_f32 v[108:109], v[104:105], 0.5, v[184:185] op_sel_hi:[1,0,1]
	v_lshl_add_u64 v[184:185], v[174:175], 0, v[182:183]
	v_pk_fma_f32 v[98:99], v[72:73], 0.5, v[98:99] op_sel_hi:[1,0,1]
	v_lshlrev_b32_e32 v72, 16, v137
	v_and_b32_e32 v73, 0xffff0000, v137
	v_lshlrev_b32_e32 v218, 16, v210
	v_and_b32_e32 v219, 0xffff0000, v210
	global_load_dwordx4 v[210:213], v[184:185], off
	v_pk_fma_f32 v[136:137], v[78:79], 0.5, v[72:73] op_sel_hi:[1,0,1]
	v_lshlrev_b32_e32 v72, 16, v139
	v_and_b32_e32 v73, 0xffff0000, v139
	v_pk_fma_f32 v[138:139], v[74:75], 0.5, v[72:73] op_sel_hi:[1,0,1]
	v_lshlrev_b32_e32 v72, 16, v132
	v_and_b32_e32 v73, 0xffff0000, v132
	v_pk_fma_f32 v[74:75], v[84:85], 0.5, v[72:73] op_sel_hi:[1,0,1]
	v_lshlrev_b32_e32 v72, 16, v134
	v_and_b32_e32 v73, 0xffff0000, v134
	v_pk_fma_f32 v[78:79], v[80:81], 0.5, v[72:73] op_sel_hi:[1,0,1]
	v_lshlrev_b32_e32 v72, 16, v133
	v_and_b32_e32 v73, 0xffff0000, v133
	v_pk_fma_f32 v[100:101], v[100:101], 0.5, v[218:219] op_sel_hi:[1,0,1]
	global_load_dwordx4 v[218:221], v[184:185], off offset:256
	v_pk_fma_f32 v[80:81], v[86:87], 0.5, v[72:73] op_sel_hi:[1,0,1]
	v_lshlrev_b32_e32 v72, 16, v135
	v_and_b32_e32 v73, 0xffff0000, v135
	v_pk_fma_f32 v[82:83], v[82:83], 0.5, v[72:73] op_sel_hi:[1,0,1]
	v_lshl_add_u64 v[72:73], v[168:169], 0, s[10:11]
	v_lshlrev_b64 v[132:133], 11, v[72:73]
	v_lshl_add_u64 v[134:135], v[174:175], 0, v[132:133]
	v_lshlrev_b32_e32 v84, 16, v128
	v_and_b32_e32 v85, 0xffff0000, v128
	global_load_dwordx4 v[226:229], v[134:135], off
	global_load_dwordx4 v[234:237], v[134:135], off offset:256
	v_pk_fma_f32 v[84:85], v[68:69], 0.5, v[84:85] op_sel_hi:[1,0,1]
	v_lshlrev_b32_e32 v68, 16, v130
	v_and_b32_e32 v69, 0xffff0000, v130
	v_pk_fma_f32 v[86:87], v[64:65], 0.5, v[68:69] op_sel_hi:[1,0,1]
	v_lshlrev_b32_e32 v64, 16, v129
	v_and_b32_e32 v65, 0xffff0000, v129
	s_mov_b64 s[10:11], 0xa0
	v_pk_fma_f32 v[128:129], v[70:71], 0.5, v[64:65] op_sel_hi:[1,0,1]
	v_lshl_add_u64 v[70:71], v[168:169], 0, s[10:11]
	s_mov_b64 s[10:11], 0xb0
	v_lshlrev_b32_e32 v64, 16, v131
	v_and_b32_e32 v65, 0xffff0000, v131
	v_lshlrev_b64 v[134:135], 11, v[70:71]
	v_lshl_add_u64 v[68:69], v[168:169], 0, s[10:11]
	v_pk_fma_f32 v[130:131], v[66:67], 0.5, v[64:65] op_sel_hi:[1,0,1]
	v_lshl_add_u64 v[64:65], v[174:175], 0, v[134:135]
	v_lshlrev_b64 v[184:185], 11, v[68:69]
	global_load_dwordx4 v[238:241], v[64:65], off
	global_load_dwordx4 v[242:245], v[64:65], off offset:256
	v_lshl_add_u64 v[64:65], v[174:175], 0, v[184:185]
	global_load_dwordx4 v[246:249], v[64:65], off
	s_nop 0
	global_load_dwordx4 v[64:67], v[64:65], off offset:256
	v_lshlrev_b32_e32 v194, 16, v195
	v_and_b32_e32 v195, 0xffff0000, v195
	v_lshlrev_b32_e32 v196, 16, v197
	v_and_b32_e32 v197, 0xffff0000, v197
	v_cvt_pk_bf16_f32 v115, v122, v123
	v_cvt_pk_bf16_f32 v119, v148, v149
	v_pk_fma_f32 v[122:123], v[110:111], 0.5, v[194:195] op_sel_hi:[1,0,1]
	v_pk_fma_f32 v[110:111], v[106:107], 0.5, v[196:197] op_sel_hi:[1,0,1]
	global_store_dwordx4 v[172:173], v[112:115], off
	global_store_dwordx4 v[172:173], v[116:119], off offset:256
	v_cvt_pk_bf16_f32 v104, v120, v121
	v_lshl_add_u64 v[112:113], s[28:29], 0, v[176:177]
	v_cvt_pk_bf16_f32 v105, v122, v123
	v_cvt_pk_bf16_f32 v106, v108, v109
	v_cvt_pk_bf16_f32 v107, v110, v111
	v_lshl_add_u64 v[112:113], v[112:113], 0, v[170:171]
	v_cvt_pk_bf16_f32 v146, v100, v101
	v_cvt_pk_bf16_f32 v147, v102, v103
	v_cvt_pk_bf16_f32 v148, v124, v125
	v_cvt_pk_bf16_f32 v149, v126, v127
	global_store_dwordx4 v[112:113], v[104:107], off
	global_store_dwordx4 v[112:113], v[146:149], off offset:256
	v_cvt_pk_bf16_f32 v194, v92, v93
	v_lshl_add_u64 v[104:105], s[28:29], 0, v[180:181]
	v_cvt_pk_bf16_f32 v195, v94, v95
	v_cvt_pk_bf16_f32 v196, v88, v89
	v_cvt_pk_bf16_f32 v197, v90, v91
	v_lshl_add_u64 v[104:105], v[104:105], 0, v[170:171]
	v_cvt_pk_bf16_f32 v214, v96, v97
	v_cvt_pk_bf16_f32 v215, v136, v137
	v_cvt_pk_bf16_f32 v216, v98, v99
	v_cvt_pk_bf16_f32 v217, v138, v139
	global_store_dwordx4 v[104:105], v[194:197], off
	global_store_dwordx4 v[104:105], v[214:217], off offset:256
	v_lshl_add_u64 v[104:105], s[28:29], 0, v[178:179]
	v_cvt_pk_bf16_f32 v222, v74, v75
	v_cvt_pk_bf16_f32 v223, v80, v81
	v_cvt_pk_bf16_f32 v224, v78, v79
	v_cvt_pk_bf16_f32 v225, v82, v83
	v_lshl_add_u64 v[104:105], v[104:105], 0, v[170:171]
	v_cvt_pk_bf16_f32 v230, v84, v85
	v_cvt_pk_bf16_f32 v231, v128, v129
	v_cvt_pk_bf16_f32 v232, v86, v87
	v_cvt_pk_bf16_f32 v233, v130, v131
	global_store_dwordx4 v[104:105], v[222:225], off
	global_store_dwordx4 v[104:105], v[230:233], off offset:256
	s_waitcnt vmcnt(8)
	v_lshlrev_b32_e32 v104, 16, v210
	v_and_b32_e32 v105, 0xffff0000, v210
	v_pk_fma_f32 v[60:61], v[60:61], 0.5, v[104:105] op_sel_hi:[1,0,1]
	v_lshlrev_b32_e32 v104, 16, v212
	v_and_b32_e32 v105, 0xffff0000, v212
	v_pk_fma_f32 v[56:57], v[56:57], 0.5, v[104:105] op_sel_hi:[1,0,1]
	v_lshlrev_b32_e32 v104, 16, v211
	v_and_b32_e32 v105, 0xffff0000, v211
	v_pk_fma_f32 v[62:63], v[62:63], 0.5, v[104:105] op_sel_hi:[1,0,1]
	v_lshlrev_b32_e32 v104, 16, v213
	v_and_b32_e32 v105, 0xffff0000, v213
	v_pk_fma_f32 v[58:59], v[58:59], 0.5, v[104:105] op_sel_hi:[1,0,1]
	v_lshlrev_b32_e32 v104, 16, v218
	v_and_b32_e32 v105, 0xffff0000, v218
	v_pk_fma_f32 v[52:53], v[52:53], 0.5, v[104:105] op_sel_hi:[1,0,1]
	v_lshlrev_b32_e32 v104, 16, v220
	v_and_b32_e32 v105, 0xffff0000, v220
	v_pk_fma_f32 v[104:105], v[44:45], 0.5, v[104:105] op_sel_hi:[1,0,1]
	v_lshlrev_b32_e32 v44, 16, v219
	v_and_b32_e32 v45, 0xffff0000, v219
	v_pk_fma_f32 v[54:55], v[54:55], 0.5, v[44:45] op_sel_hi:[1,0,1]
	v_lshlrev_b32_e32 v44, 16, v221
	v_and_b32_e32 v45, 0xffff0000, v221
	v_pk_fma_f32 v[106:107], v[46:47], 0.5, v[44:45] op_sel_hi:[1,0,1]
	v_lshlrev_b32_e32 v44, 16, v226
	v_and_b32_e32 v45, 0xffff0000, v226
	v_pk_fma_f32 v[44:45], v[48:49], 0.5, v[44:45] op_sel_hi:[1,0,1]
	v_lshlrev_b32_e32 v48, 16, v229
	v_and_b32_e32 v49, 0xffff0000, v229
	v_pk_fma_f32 v[42:43], v[42:43], 0.5, v[48:49] op_sel_hi:[1,0,1]
	v_lshlrev_b32_e32 v48, 16, v234
	v_and_b32_e32 v49, 0xffff0000, v234
	v_pk_fma_f32 v[36:37], v[36:37], 0.5, v[48:49] op_sel_hi:[1,0,1]
	v_lshlrev_b32_e32 v48, 16, v236
	v_and_b32_e32 v49, 0xffff0000, v236
	v_lshlrev_b32_e32 v46, 16, v228
	v_and_b32_e32 v47, 0xffff0000, v228
	v_pk_fma_f32 v[48:49], v[28:29], 0.5, v[48:49] op_sel_hi:[1,0,1]
	v_lshlrev_b32_e32 v28, 16, v235
	v_and_b32_e32 v29, 0xffff0000, v235
	v_pk_fma_f32 v[40:41], v[40:41], 0.5, v[46:47] op_sel_hi:[1,0,1]
	v_lshlrev_b32_e32 v46, 16, v227
	v_and_b32_e32 v47, 0xffff0000, v227
	v_pk_fma_f32 v[38:39], v[38:39], 0.5, v[28:29] op_sel_hi:[1,0,1]
	v_lshlrev_b32_e32 v28, 16, v237
	v_and_b32_e32 v29, 0xffff0000, v237
	v_pk_fma_f32 v[46:47], v[50:51], 0.5, v[46:47] op_sel_hi:[1,0,1]
	v_pk_fma_f32 v[50:51], v[30:31], 0.5, v[28:29] op_sel_hi:[1,0,1]
	v_lshlrev_b32_e32 v28, 16, v238
	v_and_b32_e32 v29, 0xffff0000, v238
	v_lshlrev_b32_e32 v180, 16, v64
	v_and_b32_e32 v181, 0xffff0000, v64
	v_pk_fma_f32 v[28:29], v[32:33], 0.5, v[28:29] op_sel_hi:[1,0,1]
	v_lshlrev_b32_e32 v32, 16, v241
	v_and_b32_e32 v33, 0xffff0000, v241
	v_pk_fma_f32 v[4:5], v[4:5], 0.5, v[180:181] op_sel_hi:[1,0,1]
	v_lshlrev_b32_e32 v180, 16, v66
	v_and_b32_e32 v181, 0xffff0000, v66
	v_pk_fma_f32 v[26:27], v[26:27], 0.5, v[32:33] op_sel_hi:[1,0,1]
	v_lshlrev_b32_e32 v32, 16, v242
	v_and_b32_e32 v33, 0xffff0000, v242
	v_pk_fma_f32 v[0:1], v[0:1], 0.5, v[180:181] op_sel_hi:[1,0,1]
	v_lshl_add_u64 v[180:181], s[28:29], 0, v[182:183]
	v_cvt_pk_bf16_f32 v112, v60, v61
	v_cvt_pk_bf16_f32 v113, v62, v63
	v_cvt_pk_bf16_f32 v114, v56, v57
	v_cvt_pk_bf16_f32 v115, v58, v59
	v_pk_fma_f32 v[20:21], v[20:21], 0.5, v[32:33] op_sel_hi:[1,0,1]
	v_lshlrev_b32_e32 v32, 16, v244
	v_and_b32_e32 v33, 0xffff0000, v244
	v_lshl_add_u64 v[180:181], v[180:181], 0, v[170:171]
	v_cvt_pk_bf16_f32 v116, v52, v53
	v_cvt_pk_bf16_f32 v117, v54, v55
	v_cvt_pk_bf16_f32 v118, v104, v105
	v_cvt_pk_bf16_f32 v119, v106, v107
	v_lshlrev_b32_e32 v30, 16, v240
	v_and_b32_e32 v31, 0xffff0000, v240
	v_pk_fma_f32 v[32:33], v[12:13], 0.5, v[32:33] op_sel_hi:[1,0,1]
	v_lshlrev_b32_e32 v12, 16, v243
	v_and_b32_e32 v13, 0xffff0000, v243
	global_store_dwordx4 v[180:181], v[112:115], off
	global_store_dwordx4 v[180:181], v[116:119], off offset:256
	v_cvt_pk_bf16_f32 v146, v44, v45
	v_lshl_add_u64 v[112:113], s[28:29], 0, v[132:133]
	v_cvt_pk_bf16_f32 v147, v46, v47
	v_cvt_pk_bf16_f32 v148, v40, v41
	v_cvt_pk_bf16_f32 v149, v42, v43
	v_pk_fma_f32 v[24:25], v[24:25], 0.5, v[30:31] op_sel_hi:[1,0,1]
	v_lshlrev_b32_e32 v30, 16, v239
	v_and_b32_e32 v31, 0xffff0000, v239
	v_pk_fma_f32 v[22:23], v[22:23], 0.5, v[12:13] op_sel_hi:[1,0,1]
	v_lshlrev_b32_e32 v12, 16, v245
	v_and_b32_e32 v13, 0xffff0000, v245
	v_lshl_add_u64 v[112:113], v[112:113], 0, v[170:171]
	v_cvt_pk_bf16_f32 v172, v36, v37
	v_cvt_pk_bf16_f32 v173, v38, v39
	v_cvt_pk_bf16_f32 v174, v48, v49
	v_cvt_pk_bf16_f32 v175, v50, v51
	v_pk_fma_f32 v[30:31], v[34:35], 0.5, v[30:31] op_sel_hi:[1,0,1]
	v_pk_fma_f32 v[34:35], v[14:15], 0.5, v[12:13] op_sel_hi:[1,0,1]
	v_lshlrev_b32_e32 v12, 16, v246
	v_and_b32_e32 v13, 0xffff0000, v246
	v_lshlrev_b32_e32 v14, 16, v248
	v_and_b32_e32 v15, 0xffff0000, v248
	global_store_dwordx4 v[112:113], v[146:149], off
	global_store_dwordx4 v[112:113], v[172:175], off offset:256
	v_lshl_add_u64 v[112:113], s[28:29], 0, v[134:135]
	v_cvt_pk_bf16_f32 v176, v28, v29
	v_cvt_pk_bf16_f32 v177, v30, v31
	v_cvt_pk_bf16_f32 v178, v24, v25
	v_cvt_pk_bf16_f32 v179, v26, v27
	v_pk_fma_f32 v[12:13], v[16:17], 0.5, v[12:13] op_sel_hi:[1,0,1]
	v_pk_fma_f32 v[8:9], v[8:9], 0.5, v[14:15] op_sel_hi:[1,0,1]
	v_lshlrev_b32_e32 v14, 16, v247
	v_and_b32_e32 v15, 0xffff0000, v247
	v_lshlrev_b32_e32 v16, 16, v249
	v_and_b32_e32 v17, 0xffff0000, v249
	v_lshlrev_b32_e32 v64, 16, v65
	v_and_b32_e32 v65, 0xffff0000, v65
	v_lshl_add_u64 v[112:113], v[112:113], 0, v[170:171]
	v_cvt_pk_bf16_f32 v194, v20, v21
	v_cvt_pk_bf16_f32 v195, v22, v23
	v_cvt_pk_bf16_f32 v196, v32, v33
	v_cvt_pk_bf16_f32 v197, v34, v35
	v_pk_fma_f32 v[14:15], v[18:19], 0.5, v[14:15] op_sel_hi:[1,0,1]
	v_pk_fma_f32 v[10:11], v[10:11], 0.5, v[16:17] op_sel_hi:[1,0,1]
	v_pk_fma_f32 v[6:7], v[6:7], 0.5, v[64:65] op_sel_hi:[1,0,1]
	v_lshlrev_b32_e32 v64, 16, v67
	v_and_b32_e32 v65, 0xffff0000, v67
	global_store_dwordx4 v[112:113], v[176:179], off
	global_store_dwordx4 v[112:113], v[194:197], off offset:256
	v_lshl_add_u64 v[112:113], s[28:29], 0, v[184:185]
	v_cvt_pk_bf16_f32 v16, v12, v13
	v_cvt_pk_bf16_f32 v17, v14, v15
	v_cvt_pk_bf16_f32 v18, v8, v9
	v_cvt_pk_bf16_f32 v19, v10, v11
	v_pk_fma_f32 v[2:3], v[2:3], 0.5, v[64:65] op_sel_hi:[1,0,1]
	v_lshl_add_u64 v[112:113], v[112:113], 0, v[170:171]
	v_cvt_pk_bf16_f32 v64, v4, v5
	v_cvt_pk_bf16_f32 v65, v6, v7
	v_cvt_pk_bf16_f32 v66, v0, v1
	v_cvt_pk_bf16_f32 v67, v2, v3
	global_store_dwordx4 v[112:113], v[16:19], off
	global_store_dwordx4 v[112:113], v[64:67], off offset:256
	s_lshl_b32 s10, s81, 2
	v_and_b32_e32 v17, 64, v188
	v_xor_b32_e32 v16, 16, v188
	v_add_u32_e32 v17, 64, v17
	v_cmp_lt_i32_e32 vcc, v16, v17
	v_xor_b32_e32 v18, 32, v188
	s_ashr_i32 s11, s10, 31
	v_cndmask_b32_e32 v16, v188, v16, vcc
	v_lshlrev_b32_e32 v16, 2, v16
	v_mov_b32_e32 v132, v209
	v_cmp_lt_i32_e32 vcc, v18, v17
	s_lshl_b64 s[10:11], s[10:11], 2
	s_add_u32 s38, s73, s10
	v_cndmask_b32_e32 v17, v188, v18, vcc
	v_lshlrev_b32_e32 v17, 2, v17
	s_addc_u32 s39, s74, s11
	v_pk_mul_f32 v[18:19], v[120:121], v[120:121]
	v_pk_fma_f32 v[18:19], v[122:123], v[122:123], v[18:19]
	v_pk_fma_f32 v[18:19], v[108:109], v[108:109], v[18:19]
	v_pk_fma_f32 v[18:19], v[110:111], v[110:111], v[18:19]
	v_pk_fma_f32 v[18:19], v[100:101], v[100:101], v[18:19]
	v_pk_fma_f32 v[18:19], v[102:103], v[102:103], v[18:19]
	v_pk_fma_f32 v[18:19], v[124:125], v[124:125], v[18:19]
	v_pk_fma_f32 v[18:19], v[126:127], v[126:127], v[18:19]
	v_add_f32_e32 v18, v18, v19
	v_mov_b32_e32 v133, v18
	v_pk_mul_f32 v[18:19], v[92:93], v[92:93]
	v_pk_fma_f32 v[18:19], v[94:95], v[94:95], v[18:19]
	v_pk_fma_f32 v[18:19], v[88:89], v[88:89], v[18:19]
	v_pk_fma_f32 v[18:19], v[90:91], v[90:91], v[18:19]
	v_pk_fma_f32 v[18:19], v[96:97], v[96:97], v[18:19]
	v_pk_fma_f32 v[18:19], v[136:137], v[136:137], v[18:19]
	v_pk_fma_f32 v[18:19], v[98:99], v[98:99], v[18:19]
	v_pk_fma_f32 v[18:19], v[138:139], v[138:139], v[18:19]
	v_add_f32_e32 v18, v18, v19
	v_mov_b32_e32 v134, v18
	v_pk_mul_f32 v[18:19], v[74:75], v[74:75]
	v_pk_mul_f32 v[210:211], v[60:61], v[60:61]
	v_pk_fma_f32 v[18:19], v[80:81], v[80:81], v[18:19]
	v_pk_fma_f32 v[210:211], v[62:63], v[62:63], v[210:211]
	v_pk_fma_f32 v[18:19], v[78:79], v[78:79], v[18:19]
	v_pk_fma_f32 v[210:211], v[56:57], v[56:57], v[210:211]
	v_pk_fma_f32 v[18:19], v[82:83], v[82:83], v[18:19]
	v_pk_fma_f32 v[210:211], v[58:59], v[58:59], v[210:211]
	v_pk_fma_f32 v[18:19], v[84:85], v[84:85], v[18:19]
	v_pk_fma_f32 v[210:211], v[52:53], v[52:53], v[210:211]
	v_pk_fma_f32 v[18:19], v[128:129], v[128:129], v[18:19]
	v_pk_fma_f32 v[210:211], v[54:55], v[54:55], v[210:211]
	v_pk_fma_f32 v[18:19], v[86:87], v[86:87], v[18:19]
	v_pk_fma_f32 v[210:211], v[104:105], v[104:105], v[210:211]
	v_pk_fma_f32 v[18:19], v[130:131], v[130:131], v[18:19]
	v_pk_fma_f32 v[210:211], v[106:107], v[106:107], v[210:211]
	v_add_f32_e32 v18, v18, v19
	v_add_f32_e32 v210, v210, v211
	v_mov_b32_e32 v135, v18
	v_mov_b32_e32 v146, v210
	v_pk_mul_f32 v[18:19], v[44:45], v[44:45]
	v_pk_mul_f32 v[210:211], v[28:29], v[28:29]
	v_pk_fma_f32 v[18:19], v[46:47], v[46:47], v[18:19]
	v_pk_fma_f32 v[210:211], v[30:31], v[30:31], v[210:211]
	v_pk_fma_f32 v[18:19], v[40:41], v[40:41], v[18:19]
	v_pk_fma_f32 v[210:211], v[24:25], v[24:25], v[210:211]
	v_pk_fma_f32 v[18:19], v[42:43], v[42:43], v[18:19]
	v_pk_fma_f32 v[210:211], v[26:27], v[26:27], v[210:211]
	v_pk_fma_f32 v[18:19], v[36:37], v[36:37], v[18:19]
	v_pk_fma_f32 v[210:211], v[20:21], v[20:21], v[210:211]
	v_pk_fma_f32 v[18:19], v[38:39], v[38:39], v[18:19]
	v_pk_fma_f32 v[210:211], v[22:23], v[22:23], v[210:211]
	v_pk_fma_f32 v[18:19], v[48:49], v[48:49], v[18:19]
	v_pk_fma_f32 v[210:211], v[32:33], v[32:33], v[210:211]
	v_pk_fma_f32 v[18:19], v[50:51], v[50:51], v[18:19]
	v_pk_fma_f32 v[210:211], v[34:35], v[34:35], v[210:211]
	v_add_f32_e32 v18, v18, v19
	v_add_f32_e32 v210, v210, v211
	v_mov_b32_e32 v147, v18
	v_mov_b32_e32 v148, v210
	v_pk_mul_f32 v[18:19], v[12:13], v[12:13]
	v_pk_fma_f32 v[18:19], v[14:15], v[14:15], v[18:19]
	v_pk_fma_f32 v[18:19], v[8:9], v[8:9], v[18:19]
	v_pk_fma_f32 v[18:19], v[10:11], v[10:11], v[18:19]
	v_pk_fma_f32 v[18:19], v[4:5], v[4:5], v[18:19]
	v_pk_fma_f32 v[18:19], v[6:7], v[6:7], v[18:19]
	v_pk_fma_f32 v[18:19], v[0:1], v[0:1], v[18:19]
	v_pk_fma_f32 v[18:19], v[2:3], v[2:3], v[18:19]
	v_add_f32_e32 v0, v18, v19
	v_mov_b32_e32 v149, v0
	ds_bpermute_b32 v172, v16, v132
	ds_bpermute_b32 v173, v16, v133
	ds_bpermute_b32 v174, v16, v134
	ds_bpermute_b32 v175, v16, v135
	ds_bpermute_b32 v180, v16, v146
	ds_bpermute_b32 v181, v16, v147
	ds_bpermute_b32 v182, v16, v148
	ds_bpermute_b32 v183, v16, v149
	s_waitcnt lgkmcnt(0)
	v_add_f32_e32 v132, v132, v172
	v_add_f32_e32 v133, v133, v173
	v_add_f32_e32 v134, v134, v174
	v_add_f32_e32 v135, v135, v175
	v_add_f32_e32 v146, v146, v180
	v_add_f32_e32 v147, v147, v181
	v_add_f32_e32 v148, v148, v182
	v_add_f32_e32 v149, v149, v183
	ds_bpermute_b32 v172, v17, v132
	ds_bpermute_b32 v173, v17, v133
	ds_bpermute_b32 v174, v17, v134
	ds_bpermute_b32 v175, v17, v135
	ds_bpermute_b32 v180, v17, v146
	ds_bpermute_b32 v181, v17, v147
	ds_bpermute_b32 v182, v17, v148
	ds_bpermute_b32 v183, v17, v149
	s_and_saveexec_b64 s[46:47], s[42:43]
	s_cbranch_execz .LBB0_19
	s_waitcnt lgkmcnt(0)
	v_add_f32_e32 v132, v132, v172
	v_lshlrev_b64 v[18:19], 6, v[168:169]
	v_lshl_add_u64 v[18:19], s[38:39], 0, v[18:19]
	global_store_dword v[18:19], v132, off
	v_add_f32_e32 v133, v133, v173
	v_lshlrev_b64 v[18:19], 6, v[166:167]
	v_lshl_add_u64 v[18:19], s[38:39], 0, v[18:19]
	global_store_dword v[18:19], v133, off
	v_add_f32_e32 v134, v134, v174
	v_lshlrev_b64 v[18:19], 6, v[164:165]
	v_lshl_add_u64 v[18:19], s[38:39], 0, v[18:19]
	global_store_dword v[18:19], v134, off
	v_add_f32_e32 v135, v135, v175
	v_lshlrev_b64 v[18:19], 6, v[162:163]
	v_lshl_add_u64 v[18:19], s[38:39], 0, v[18:19]
	global_store_dword v[18:19], v135, off
	v_add_f32_e32 v146, v146, v180
	v_lshlrev_b64 v[18:19], 6, v[76:77]
	v_lshl_add_u64 v[18:19], s[38:39], 0, v[18:19]
	global_store_dword v[18:19], v146, off
	v_add_f32_e32 v147, v147, v181
	v_lshlrev_b64 v[18:19], 6, v[72:73]
	v_lshl_add_u64 v[18:19], s[38:39], 0, v[18:19]
	global_store_dword v[18:19], v147, off
	v_add_f32_e32 v148, v148, v182
	v_lshlrev_b64 v[18:19], 6, v[70:71]
	v_lshl_add_u64 v[18:19], s[38:39], 0, v[18:19]
	global_store_dword v[18:19], v148, off
	v_add_f32_e32 v149, v149, v183
	v_lshlrev_b64 v[18:19], 6, v[68:69]
	v_lshl_add_u64 v[18:19], s[38:39], 0, v[18:19]
	global_store_dword v[18:19], v149, off
	s_branch .LBB0_19

.LBB0_103:
	s_add_u32 s6, s54, 0xfffc0080
	s_addc_u32 s19, s55, -1
	s_add_i32 s23, 0, 0x10000
	v_add_u32_e32 v146, s23, v206
	ds_read_b128 v[128:131], v146
	ds_read_b128 v[132:135], v146 offset:1024
	ds_read_b128 v[136:139], v146 offset:2048
	ds_read_b128 v[146:149], v146 offset:3072
	s_cmp_eq_u32 s12, 12
	s_cselect_b32 s69, s47, s19
	s_cselect_b32 s68, s46, s6
	s_cselect_b32 s59, s49, s11
	s_cselect_b32 s58, s48, s10
	v_lshl_add_u64 v[192:193], s[54:55], 0, v[158:159]
	s_add_i32 m0, s72, 0xc000
	ds_read_b128 v[162:165], v208
	ds_read_b128 v[166:169], v208 offset:1024
	ds_read_b128 v[170:173], v208 offset:2048
	ds_read_b128 v[174:177], v208 offset:3072
	ds_read_b128 v[178:181], v208 offset:4096
	ds_read_b128 v[182:185], v208 offset:5120
	ds_read_b128 v[194:197], v208 offset:6144
	ds_read_b128 v[210:213], v208 offset:7168
	global_load_lds_dwordx4 v[192:193], off
	v_lshl_add_u64 v[192:193], s[54:55], 0, v[160:161]
	s_add_i32 m0, s72, 0xe000
	s_nop 0
	global_load_lds_dwordx4 v[192:193], off
	s_add_i32 s6, 0, 0x14000
	v_add_u32_e32 v192, s6, v206
	ds_read_b128 v[214:217], v192
	ds_read_b128 v[218:221], v192 offset:1024
	ds_read_b128 v[222:225], v192 offset:2048
	ds_read_b128 v[226:229], v192 offset:3072
	s_nop 0
	s_waitcnt vmcnt(8)
	s_waitcnt lgkmcnt(0)
	s_barrier
	v_mfma_f32_16x16x32_bf16 v[124:127], v[128:131], v[162:165], v[124:127]
	v_mfma_f32_16x16x32_bf16 v[120:123], v[136:139], v[162:165], v[120:123]
	v_mfma_f32_16x16x32_bf16 v[108:111], v[128:131], v[170:173], v[108:111]
	v_mfma_f32_16x16x32_bf16 v[104:107], v[136:139], v[170:173], v[104:107]
	v_mfma_f32_16x16x32_bf16 v[96:99], v[128:131], v[178:181], v[96:99]
	v_mfma_f32_16x16x32_bf16 v[88:91], v[136:139], v[178:181], v[88:91]
	v_mfma_f32_16x16x32_bf16 v[84:87], v[128:131], v[194:197], v[84:87]
	v_mfma_f32_16x16x32_bf16 v[80:83], v[136:139], v[194:197], v[80:83]
	v_mfma_f32_16x16x32_bf16 v[124:127], v[132:135], v[166:169], v[124:127]
	v_mfma_f32_16x16x32_bf16 v[120:123], v[146:149], v[166:169], v[120:123]
	v_mfma_f32_16x16x32_bf16 v[108:111], v[132:135], v[174:177], v[108:111]
	v_mfma_f32_16x16x32_bf16 v[104:107], v[146:149], v[174:177], v[104:107]
	v_mfma_f32_16x16x32_bf16 v[96:99], v[132:135], v[182:185], v[96:99]
	v_mfma_f32_16x16x32_bf16 v[88:91], v[146:149], v[182:185], v[88:91]
	v_mfma_f32_16x16x32_bf16 v[84:87], v[132:135], v[210:213], v[84:87]
	v_mfma_f32_16x16x32_bf16 v[80:83], v[146:149], v[210:213], v[80:83]
	v_mfma_f32_16x16x32_bf16 v[116:119], v[214:217], v[162:165], v[116:119]
	v_mfma_f32_16x16x32_bf16 v[112:115], v[222:225], v[162:165], v[112:115]
	v_mfma_f32_16x16x32_bf16 v[100:103], v[214:217], v[170:173], v[100:103]
	v_mfma_f32_16x16x32_bf16 v[92:95], v[222:225], v[170:173], v[92:95]
	v_mfma_f32_16x16x32_bf16 v[76:79], v[214:217], v[178:181], v[76:79]
	v_mfma_f32_16x16x32_bf16 v[72:75], v[222:225], v[178:181], v[72:75]
	v_mfma_f32_16x16x32_bf16 v[68:71], v[214:217], v[194:197], v[68:71]
	v_mfma_f32_16x16x32_bf16 v[64:67], v[222:225], v[194:197], v[64:67]
	v_mfma_f32_16x16x32_bf16 v[116:119], v[218:221], v[166:169], v[116:119]
	v_mfma_f32_16x16x32_bf16 v[112:115], v[226:229], v[166:169], v[112:115]
	v_mfma_f32_16x16x32_bf16 v[100:103], v[218:221], v[174:177], v[100:103]
	v_mfma_f32_16x16x32_bf16 v[92:95], v[226:229], v[174:177], v[92:95]
	v_mfma_f32_16x16x32_bf16 v[76:79], v[218:221], v[182:185], v[76:79]
	v_mfma_f32_16x16x32_bf16 v[72:75], v[226:229], v[182:185], v[72:75]
	v_mfma_f32_16x16x32_bf16 v[68:71], v[218:221], v[210:213], v[68:71]
	v_mfma_f32_16x16x32_bf16 v[64:67], v[226:229], v[210:213], v[64:67]
	s_barrier
	s_add_i32 s19, s23, s71
	v_lshl_add_u64 v[192:193], s[58:59], 0, v[140:141]
	s_mov_b32 m0, s19
	v_lshl_add_u64 v[230:231], s[58:59], 0, v[150:151]
	global_load_lds_dwordx4 v[192:193], off
	s_add_i32 m0, s19, 0x2000
	s_nop 0
	global_load_lds_dwordx4 v[230:231], off
	s_mov_b32 m0, s72
	v_lshl_add_u64 v[232:233], s[68:69], 0, v[154:155]
	ds_read_b128 v[162:165], v208 offset:16384
	ds_read_b128 v[166:169], v208 offset:17408
	ds_read_b128 v[170:173], v208 offset:18432
	ds_read_b128 v[174:177], v208 offset:19456
	ds_read_b128 v[178:181], v208 offset:20480
	ds_read_b128 v[182:185], v208 offset:21504
	ds_read_b128 v[194:197], v208 offset:22528
	ds_read_b128 v[210:213], v208 offset:23552
	global_load_lds_dwordx4 v[232:233], off
	v_lshl_add_u64 v[234:235], s[68:69], 0, v[152:153]
	s_mov_b32 m0, s73
	s_nop 0
	global_load_lds_dwordx4 v[234:235], off
	s_add_u32 s86, s58, 0x40000
	s_addc_u32 s87, s59, 0
	s_add_i32 s6, s6, s71
	v_lshl_add_u64 v[250:251], s[86:87], 0, v[140:141]
	s_mov_b32 m0, s6
	s_nop 0
	global_load_lds_dwordx4 v[250:251], off
	v_lshl_add_u64 v[250:251], s[86:87], 0, v[150:151]
	s_add_i32 m0, s6, 0x2000
	s_nop 0
	global_load_lds_dwordx4 v[250:251], off
	s_nop 0
	s_waitcnt vmcnt(8)
	s_waitcnt lgkmcnt(0)
	s_barrier
	v_mfma_f32_16x16x32_bf16 v[60:63], v[128:131], v[162:165], v[60:63]
	v_mfma_f32_16x16x32_bf16 v[56:59], v[136:139], v[162:165], v[56:59]
	v_mfma_f32_16x16x32_bf16 v[48:51], v[128:131], v[170:173], v[48:51]
	v_mfma_f32_16x16x32_bf16 v[40:43], v[136:139], v[170:173], v[40:43]
	v_mfma_f32_16x16x32_bf16 v[32:35], v[128:131], v[178:181], v[32:35]
	v_mfma_f32_16x16x32_bf16 v[24:27], v[136:139], v[178:181], v[24:27]
	v_mfma_f32_16x16x32_bf16 v[16:19], v[128:131], v[194:197], v[16:19]
	v_mfma_f32_16x16x32_bf16 v[8:11], v[136:139], v[194:197], v[8:11]
	v_mfma_f32_16x16x32_bf16 v[60:63], v[132:135], v[166:169], v[60:63]
	v_mfma_f32_16x16x32_bf16 v[56:59], v[146:149], v[166:169], v[56:59]
	v_mfma_f32_16x16x32_bf16 v[48:51], v[132:135], v[174:177], v[48:51]
	v_mfma_f32_16x16x32_bf16 v[40:43], v[146:149], v[174:177], v[40:43]
	v_mfma_f32_16x16x32_bf16 v[32:35], v[132:135], v[182:185], v[32:35]
	v_mfma_f32_16x16x32_bf16 v[24:27], v[146:149], v[182:185], v[24:27]
	v_mfma_f32_16x16x32_bf16 v[16:19], v[132:135], v[210:213], v[16:19]
	v_mfma_f32_16x16x32_bf16 v[8:11], v[146:149], v[210:213], v[8:11]
	v_mfma_f32_16x16x32_bf16 v[52:55], v[214:217], v[162:165], v[52:55]
	v_mfma_f32_16x16x32_bf16 v[44:47], v[222:225], v[162:165], v[44:47]
	v_mfma_f32_16x16x32_bf16 v[36:39], v[214:217], v[170:173], v[36:39]
	v_mfma_f32_16x16x32_bf16 v[28:31], v[222:225], v[170:173], v[28:31]
	v_mfma_f32_16x16x32_bf16 v[20:23], v[214:217], v[178:181], v[20:23]
	v_mfma_f32_16x16x32_bf16 v[12:15], v[222:225], v[178:181], v[12:15]
	v_mfma_f32_16x16x32_bf16 v[4:7], v[214:217], v[194:197], v[4:7]
	v_mfma_f32_16x16x32_bf16 v[0:3], v[222:225], v[194:197], v[0:3]
	v_mfma_f32_16x16x32_bf16 v[52:55], v[218:221], v[166:169], v[52:55]
	v_mfma_f32_16x16x32_bf16 v[44:47], v[226:229], v[166:169], v[44:47]
	v_mfma_f32_16x16x32_bf16 v[36:39], v[218:221], v[174:177], v[36:39]
	v_mfma_f32_16x16x32_bf16 v[28:31], v[226:229], v[174:177], v[28:31]
	v_mfma_f32_16x16x32_bf16 v[20:23], v[218:221], v[182:185], v[20:23]
	v_mfma_f32_16x16x32_bf16 v[12:15], v[226:229], v[182:185], v[12:15]
	v_mfma_f32_16x16x32_bf16 v[4:7], v[218:221], v[210:213], v[4:7]
	v_mfma_f32_16x16x32_bf16 v[0:3], v[226:229], v[210:213], v[0:3]
	s_barrier
	s_add_i32 s6, 0, 0x18000
	v_add_u32_e32 v146, s6, v206
	ds_read_b128 v[128:131], v146
	ds_read_b128 v[132:135], v146 offset:1024
	ds_read_b128 v[136:139], v146 offset:2048
	ds_read_b128 v[146:149], v146 offset:3072
	s_add_u32 s68, s68, 0x40000
	s_addc_u32 s69, s69, 0
	s_mov_b32 m0, s74
	v_lshl_add_u64 v[214:215], s[68:69], 0, v[154:155]
	ds_read_b128 v[162:165], v208 offset:32768
	ds_read_b128 v[166:169], v208 offset:33792
	ds_read_b128 v[170:173], v208 offset:34816
	ds_read_b128 v[174:177], v208 offset:35840
	ds_read_b128 v[178:181], v208 offset:36864
	ds_read_b128 v[182:185], v208 offset:37888
	ds_read_b128 v[194:197], v208 offset:38912
	ds_read_b128 v[210:213], v208 offset:39936
	global_load_lds_dwordx4 v[214:215], off
	v_lshl_add_u64 v[214:215], s[68:69], 0, v[152:153]
	s_mov_b32 m0, s75
	s_nop 0
	global_load_lds_dwordx4 v[214:215], off
	s_add_i32 s19, 0, 0x1c000
	v_add_u32_e32 v209, s19, v206
	ds_read_b128 v[214:217], v209
	ds_read_b128 v[218:221], v209 offset:1024
	ds_read_b128 v[222:225], v209 offset:2048
	ds_read_b128 v[226:229], v209 offset:3072
	s_waitcnt vmcnt(8)
	s_waitcnt lgkmcnt(0)
	s_barrier
	v_mfma_f32_16x16x32_bf16 v[124:127], v[128:131], v[162:165], v[124:127]
	v_mfma_f32_16x16x32_bf16 v[120:123], v[136:139], v[162:165], v[120:123]
	v_mfma_f32_16x16x32_bf16 v[108:111], v[128:131], v[170:173], v[108:111]
	v_mfma_f32_16x16x32_bf16 v[104:107], v[136:139], v[170:173], v[104:107]
	v_mfma_f32_16x16x32_bf16 v[96:99], v[128:131], v[178:181], v[96:99]
	v_mfma_f32_16x16x32_bf16 v[88:91], v[136:139], v[178:181], v[88:91]
	v_mfma_f32_16x16x32_bf16 v[84:87], v[128:131], v[194:197], v[84:87]
	v_mfma_f32_16x16x32_bf16 v[80:83], v[136:139], v[194:197], v[80:83]
	v_mfma_f32_16x16x32_bf16 v[124:127], v[132:135], v[166:169], v[124:127]
	v_mfma_f32_16x16x32_bf16 v[120:123], v[146:149], v[166:169], v[120:123]
	v_mfma_f32_16x16x32_bf16 v[108:111], v[132:135], v[174:177], v[108:111]
	v_mfma_f32_16x16x32_bf16 v[104:107], v[146:149], v[174:177], v[104:107]
	v_mfma_f32_16x16x32_bf16 v[96:99], v[132:135], v[182:185], v[96:99]
	v_mfma_f32_16x16x32_bf16 v[88:91], v[146:149], v[182:185], v[88:91]
	v_mfma_f32_16x16x32_bf16 v[84:87], v[132:135], v[210:213], v[84:87]
	v_mfma_f32_16x16x32_bf16 v[80:83], v[146:149], v[210:213], v[80:83]
	v_mfma_f32_16x16x32_bf16 v[116:119], v[214:217], v[162:165], v[116:119]
	v_mfma_f32_16x16x32_bf16 v[112:115], v[222:225], v[162:165], v[112:115]
	v_mfma_f32_16x16x32_bf16 v[100:103], v[214:217], v[170:173], v[100:103]
	v_mfma_f32_16x16x32_bf16 v[92:95], v[222:225], v[170:173], v[92:95]
	v_mfma_f32_16x16x32_bf16 v[76:79], v[214:217], v[178:181], v[76:79]
	v_mfma_f32_16x16x32_bf16 v[72:75], v[222:225], v[178:181], v[72:75]
	v_mfma_f32_16x16x32_bf16 v[68:71], v[214:217], v[194:197], v[68:71]
	v_mfma_f32_16x16x32_bf16 v[64:67], v[222:225], v[194:197], v[64:67]
	v_mfma_f32_16x16x32_bf16 v[116:119], v[218:221], v[166:169], v[116:119]
	v_mfma_f32_16x16x32_bf16 v[112:115], v[226:229], v[166:169], v[112:115]
	v_mfma_f32_16x16x32_bf16 v[100:103], v[218:221], v[174:177], v[100:103]
	v_mfma_f32_16x16x32_bf16 v[92:95], v[226:229], v[174:177], v[92:95]
	v_mfma_f32_16x16x32_bf16 v[76:79], v[218:221], v[182:185], v[76:79]
	v_mfma_f32_16x16x32_bf16 v[72:75], v[226:229], v[182:185], v[72:75]
	v_mfma_f32_16x16x32_bf16 v[68:71], v[218:221], v[210:213], v[68:71]
	v_mfma_f32_16x16x32_bf16 v[64:67], v[226:229], v[210:213], v[64:67]
	s_barrier
	s_add_i32 s6, s6, s71
	v_lshl_add_u64 v[192:193], v[192:193], 0, s[36:37]
	s_mov_b32 m0, s6
	s_nop 0
	global_load_lds_dwordx4 v[192:193], off
	v_lshl_add_u64 v[192:193], v[230:231], 0, s[36:37]
	s_add_i32 m0, s6, 0x2000
	s_nop 0
	global_load_lds_dwordx4 v[192:193], off
	s_mov_b32 m0, s80
	v_lshl_add_u64 v[192:193], v[232:233], 0, s[36:37]
	ds_read_b128 v[162:165], v208 offset:49152
	ds_read_b128 v[166:169], v208 offset:50176
	ds_read_b128 v[170:173], v208 offset:51200
	ds_read_b128 v[174:177], v208 offset:52224
	ds_read_b128 v[178:181], v208 offset:53248
	ds_read_b128 v[182:185], v208 offset:54272
	ds_read_b128 v[194:197], v208 offset:55296
	ds_read_b128 v[210:213], v208 offset:56320
	global_load_lds_dwordx4 v[192:193], off
	v_lshl_add_u64 v[192:193], v[234:235], 0, s[36:37]
	s_mov_b32 m0, s81
	s_nop 0
	global_load_lds_dwordx4 v[192:193], off
	s_add_u32 s58, s58, 0x40080
	s_addc_u32 s59, s59, 0
	s_add_i32 s6, s19, s71
	v_lshl_add_u64 v[250:251], s[58:59], 0, v[140:141]
	s_mov_b32 m0, s6
	s_nop 0
	global_load_lds_dwordx4 v[250:251], off
	v_lshl_add_u64 v[250:251], s[58:59], 0, v[150:151]
	s_add_i32 m0, s6, 0x2000
	s_nop 0
	global_load_lds_dwordx4 v[250:251], off
	s_add_i32 s12, s12, 2
	s_add_u32 s54, s54, 0x100
	s_addc_u32 s55, s55, 0
	s_add_u32 s10, s10, 0x100
	s_addc_u32 s11, s11, 0
	s_cmp_gt_u32 s12, 13
	s_waitcnt vmcnt(8)
	s_waitcnt lgkmcnt(0)
	s_barrier
	v_mfma_f32_16x16x32_bf16 v[60:63], v[128:131], v[162:165], v[60:63]
	v_mfma_f32_16x16x32_bf16 v[56:59], v[136:139], v[162:165], v[56:59]
	v_mfma_f32_16x16x32_bf16 v[48:51], v[128:131], v[170:173], v[48:51]
	v_mfma_f32_16x16x32_bf16 v[40:43], v[136:139], v[170:173], v[40:43]
	v_mfma_f32_16x16x32_bf16 v[32:35], v[128:131], v[178:181], v[32:35]
	v_mfma_f32_16x16x32_bf16 v[24:27], v[136:139], v[178:181], v[24:27]
	v_mfma_f32_16x16x32_bf16 v[16:19], v[128:131], v[194:197], v[16:19]
	v_mfma_f32_16x16x32_bf16 v[8:11], v[136:139], v[194:197], v[8:11]
	v_mfma_f32_16x16x32_bf16 v[60:63], v[132:135], v[166:169], v[60:63]
	v_mfma_f32_16x16x32_bf16 v[56:59], v[146:149], v[166:169], v[56:59]
	v_mfma_f32_16x16x32_bf16 v[48:51], v[132:135], v[174:177], v[48:51]
	v_mfma_f32_16x16x32_bf16 v[40:43], v[146:149], v[174:177], v[40:43]
	v_mfma_f32_16x16x32_bf16 v[32:35], v[132:135], v[182:185], v[32:35]
	v_mfma_f32_16x16x32_bf16 v[24:27], v[146:149], v[182:185], v[24:27]
	v_mfma_f32_16x16x32_bf16 v[16:19], v[132:135], v[210:213], v[16:19]
	v_mfma_f32_16x16x32_bf16 v[8:11], v[146:149], v[210:213], v[8:11]
	v_mfma_f32_16x16x32_bf16 v[52:55], v[214:217], v[162:165], v[52:55]
	v_mfma_f32_16x16x32_bf16 v[44:47], v[222:225], v[162:165], v[44:47]
	v_mfma_f32_16x16x32_bf16 v[36:39], v[214:217], v[170:173], v[36:39]
	v_mfma_f32_16x16x32_bf16 v[28:31], v[222:225], v[170:173], v[28:31]
	v_mfma_f32_16x16x32_bf16 v[20:23], v[214:217], v[178:181], v[20:23]
	v_mfma_f32_16x16x32_bf16 v[12:15], v[222:225], v[178:181], v[12:15]
	v_mfma_f32_16x16x32_bf16 v[4:7], v[214:217], v[194:197], v[4:7]
	v_mfma_f32_16x16x32_bf16 v[0:3], v[222:225], v[194:197], v[0:3]
	v_mfma_f32_16x16x32_bf16 v[52:55], v[218:221], v[166:169], v[52:55]
	v_mfma_f32_16x16x32_bf16 v[44:47], v[226:229], v[166:169], v[44:47]
	v_mfma_f32_16x16x32_bf16 v[36:39], v[218:221], v[174:177], v[36:39]
	v_mfma_f32_16x16x32_bf16 v[28:31], v[226:229], v[174:177], v[28:31]
	v_mfma_f32_16x16x32_bf16 v[20:23], v[218:221], v[182:185], v[20:23]
	v_mfma_f32_16x16x32_bf16 v[12:15], v[226:229], v[182:185], v[12:15]
	v_mfma_f32_16x16x32_bf16 v[4:7], v[218:221], v[210:213], v[4:7]
	v_mfma_f32_16x16x32_bf16 v[0:3], v[226:229], v[210:213], v[0:3]
	s_barrier
	s_cbranch_scc0 .LBB0_103
	s_mov_b32 s100, 1
	s_ashr_i32 s51, s50, 31
	s_ashr_i32 s53, s52, 31
	s_lshl_b64 s[10:11], s[50:51], 13
	s_lshl_b64 s[50:51], s[52:53], 8
	s_add_u32 s10, s50, s10
	v_lshl_or_b32 v128, s85, 8, v207
	s_addc_u32 s11, s51, s11
	v_ashrrev_i32_e32 v129, 31, v128
	v_lshl_add_u64 v[168:169], s[10:11], 0, v[156:157]
	v_lshlrev_b64 v[170:171], 1, v[128:129]
	v_lshl_add_u64 v[174:175], s[26:27], 0, v[170:171]
	v_lshlrev_b64 v[172:173], 11, v[168:169]
	v_or_b32_e32 v166, 16, v168
	v_mov_b32_e32 v167, v169
	v_lshl_add_u64 v[128:129], v[174:175], 0, v[172:173]
	v_lshlrev_b64 v[176:177], 11, v[166:167]
	global_load_dwordx4 v[146:149], v[128:129], off
	global_load_dwordx4 v[182:185], v[128:129], off offset:256
	v_lshl_add_u64 v[128:129], v[174:175], 0, v[176:177]
	global_load_dwordx4 v[194:197], v[128:129], off
	global_load_dwordx4 v[210:213], v[128:129], off offset:256
	v_or_b32_e32 v164, 32, v168
	v_mov_b32_e32 v165, v169
	v_or_b32_e32 v162, 48, v168
	v_mov_b32_e32 v163, v169
	v_lshlrev_b64 v[180:181], 11, v[164:165]
	v_lshlrev_b64 v[178:179], 11, v[162:163]
	v_lshl_add_u64 v[128:129], v[174:175], 0, v[180:181]
	v_lshl_add_u64 v[130:131], v[174:175], 0, v[178:179]
	global_load_dwordx4 v[214:217], v[128:129], off
	global_load_dwordx4 v[136:139], v[128:129], off offset:256
	global_load_dwordx4 v[132:135], v[130:131], off
	s_nop 0
	global_load_dwordx4 v[128:131], v[130:131], off offset:256
	s_mov_b64 s[10:11], 0x90
	v_lshl_add_u64 v[172:173], s[28:29], 0, v[172:173]
	v_lshl_add_u64 v[172:173], v[172:173], 0, v[170:171]
	s_waitcnt vmcnt(0)
	v_lshlrev_b32_e32 v192, 16, v146
	v_and_b32_e32 v193, 0xffff0000, v146
	v_lshlrev_b32_e32 v218, 16, v148
	v_and_b32_e32 v219, 0xffff0000, v148
	v_lshlrev_b32_e32 v146, 16, v147
	v_and_b32_e32 v147, 0xffff0000, v147
	v_lshlrev_b32_e32 v148, 16, v149
	v_and_b32_e32 v149, 0xffff0000, v149
	v_lshlrev_b32_e32 v220, 16, v182
	v_and_b32_e32 v221, 0xffff0000, v182
	v_lshlrev_b32_e32 v222, 16, v184
	v_and_b32_e32 v223, 0xffff0000, v184
	v_lshlrev_b32_e32 v182, 16, v183
	v_and_b32_e32 v183, 0xffff0000, v183
	v_lshlrev_b32_e32 v184, 16, v185
	v_and_b32_e32 v185, 0xffff0000, v185
	v_pk_add_f32 v[124:125], v[124:125], v[192:193]
	v_pk_add_f32 v[126:127], v[126:127], v[146:147]
	v_pk_add_f32 v[122:123], v[122:123], v[148:149]
	v_pk_add_f32 v[116:117], v[116:117], v[220:221]
	v_pk_add_f32 v[146:147], v[112:113], v[222:223]
	v_pk_add_f32 v[118:119], v[118:119], v[182:183]
	v_pk_add_f32 v[148:149], v[114:115], v[184:185]
	v_lshlrev_b32_e32 v182, 16, v194
	v_and_b32_e32 v183, 0xffff0000, v194
	v_lshlrev_b32_e32 v184, 16, v196
	v_and_b32_e32 v185, 0xffff0000, v196
	v_lshlrev_b32_e32 v192, 16, v195
	v_and_b32_e32 v193, 0xffff0000, v195
	v_lshlrev_b32_e32 v194, 16, v197
	v_and_b32_e32 v195, 0xffff0000, v197
	v_pk_mul_f32 v[196:197], v[124:125], v[124:125]
	v_pk_add_f32 v[120:121], v[120:121], v[218:219]
	v_pk_mul_f32 v[218:219], v[126:127], v[126:127]
	v_cvt_pk_bf16_f32 v112, v124, v125
	v_cvt_pk_bf16_f32 v113, v126, v127
	v_pk_mul_f32 v[124:125], v[116:117], v[116:117]
	v_pk_mul_f32 v[126:127], v[118:119], v[118:119]
	v_pk_mul_f32 v[224:225], v[146:147], v[146:147]
	v_cvt_pk_bf16_f32 v116, v116, v117
	v_cvt_pk_bf16_f32 v117, v118, v119
	v_cvt_pk_bf16_f32 v118, v146, v147
	v_add_f32_e32 v146, v196, v197
	v_add_f32_e32 v146, v218, v146
	v_pk_mul_f32 v[220:221], v[120:121], v[120:121]
	v_add_f32_e32 v146, v219, v146
	v_add_f32_e32 v146, v220, v146
	v_pk_mul_f32 v[222:223], v[122:123], v[122:123]
	v_add_f32_e32 v146, v221, v146
	v_add_f32_e32 v146, v222, v146
	v_add_f32_e32 v146, v223, v146
	v_add_f32_e32 v124, v124, v146
	v_add_f32_e32 v124, v125, v124
	v_add_f32_e32 v124, v126, v124
	v_add_f32_e32 v124, v127, v124
	v_add_f32_e32 v124, v224, v124
	v_pk_mul_f32 v[226:227], v[148:149], v[148:149]
	v_add_f32_e32 v124, v225, v124
	v_add_f32_e32 v124, v226, v124
	v_add_f32_e32 v209, v227, v124
	v_lshlrev_b32_e32 v124, 16, v210
	v_and_b32_e32 v125, 0xffff0000, v210
	v_pk_add_f32 v[100:101], v[100:101], v[124:125]
	v_lshlrev_b32_e32 v124, 16, v212
	v_and_b32_e32 v125, 0xffff0000, v212
	v_pk_add_f32 v[124:125], v[92:93], v[124:125]
	v_lshlrev_b32_e32 v92, 16, v211
	v_and_b32_e32 v93, 0xffff0000, v211
	v_pk_add_f32 v[102:103], v[102:103], v[92:93]
	v_lshlrev_b32_e32 v92, 16, v213
	v_and_b32_e32 v93, 0xffff0000, v213
	v_pk_add_f32 v[126:127], v[94:95], v[92:93]
	v_lshlrev_b32_e32 v92, 16, v214
	v_and_b32_e32 v93, 0xffff0000, v214
	v_pk_add_f32 v[92:93], v[96:97], v[92:93]
	v_lshlrev_b32_e32 v96, 16, v217
	v_and_b32_e32 v97, 0xffff0000, v217
	v_lshlrev_b32_e32 v94, 16, v216
	v_and_b32_e32 v95, 0xffff0000, v216
	v_pk_add_f32 v[90:91], v[90:91], v[96:97]
	v_lshlrev_b32_e32 v96, 16, v136
	v_and_b32_e32 v97, 0xffff0000, v136
	v_pk_add_f32 v[88:89], v[88:89], v[94:95]
	v_lshlrev_b32_e32 v94, 16, v215
	v_and_b32_e32 v95, 0xffff0000, v215
	v_pk_add_f32 v[96:97], v[76:77], v[96:97]
	v_lshl_add_u64 v[76:77], v[168:169], 0, s[36:37]
	v_cvt_pk_bf16_f32 v114, v120, v121
	v_pk_add_f32 v[120:121], v[108:109], v[182:183]
	v_pk_add_f32 v[94:95], v[98:99], v[94:95]
	v_lshlrev_b64 v[182:183], 11, v[76:77]
	v_lshlrev_b32_e32 v98, 16, v138
	v_and_b32_e32 v99, 0xffff0000, v138
	v_pk_add_f32 v[108:109], v[104:105], v[184:185]
	v_lshl_add_u64 v[184:185], v[174:175], 0, v[182:183]
	v_pk_add_f32 v[98:99], v[72:73], v[98:99]
	v_lshlrev_b32_e32 v72, 16, v137
	v_and_b32_e32 v73, 0xffff0000, v137
	global_load_dwordx4 v[210:213], v[184:185], off
	global_load_dwordx4 v[218:221], v[184:185], off offset:256
	v_pk_add_f32 v[136:137], v[78:79], v[72:73]
	v_lshlrev_b32_e32 v72, 16, v139
	v_and_b32_e32 v73, 0xffff0000, v139
	v_pk_add_f32 v[138:139], v[74:75], v[72:73]
	v_lshlrev_b32_e32 v72, 16, v132
	v_and_b32_e32 v73, 0xffff0000, v132
	v_pk_add_f32 v[74:75], v[84:85], v[72:73]
	v_lshlrev_b32_e32 v72, 16, v134
	v_and_b32_e32 v73, 0xffff0000, v134
	v_pk_add_f32 v[78:79], v[80:81], v[72:73]
	v_lshlrev_b32_e32 v72, 16, v133
	v_and_b32_e32 v73, 0xffff0000, v133
	v_pk_add_f32 v[80:81], v[86:87], v[72:73]
	v_lshlrev_b32_e32 v72, 16, v135
	v_and_b32_e32 v73, 0xffff0000, v135
	v_pk_add_f32 v[82:83], v[82:83], v[72:73]
	v_lshl_add_u64 v[72:73], v[168:169], 0, s[10:11]
	v_lshlrev_b64 v[132:133], 11, v[72:73]
	v_lshl_add_u64 v[134:135], v[174:175], 0, v[132:133]
	v_lshlrev_b32_e32 v84, 16, v128
	v_and_b32_e32 v85, 0xffff0000, v128
	global_load_dwordx4 v[226:229], v[134:135], off
	global_load_dwordx4 v[234:237], v[134:135], off offset:256
	v_pk_add_f32 v[84:85], v[68:69], v[84:85]
	v_lshlrev_b32_e32 v68, 16, v130
	v_and_b32_e32 v69, 0xffff0000, v130
	v_pk_add_f32 v[86:87], v[64:65], v[68:69]
	v_lshlrev_b32_e32 v64, 16, v129
	v_and_b32_e32 v65, 0xffff0000, v129
	s_mov_b64 s[10:11], 0xa0
	v_pk_add_f32 v[128:129], v[70:71], v[64:65]
	v_lshl_add_u64 v[70:71], v[168:169], 0, s[10:11]
	s_mov_b64 s[10:11], 0xb0
	v_lshlrev_b32_e32 v64, 16, v131
	v_and_b32_e32 v65, 0xffff0000, v131
	v_lshlrev_b64 v[134:135], 11, v[70:71]
	v_lshl_add_u64 v[68:69], v[168:169], 0, s[10:11]
	v_pk_add_f32 v[130:131], v[66:67], v[64:65]
	v_lshl_add_u64 v[64:65], v[174:175], 0, v[134:135]
	v_lshlrev_b64 v[184:185], 11, v[68:69]
	global_load_dwordx4 v[238:241], v[64:65], off
	global_load_dwordx4 v[242:245], v[64:65], off offset:256
	v_lshl_add_u64 v[64:65], v[174:175], 0, v[184:185]
	global_load_dwordx4 v[246:249], v[64:65], off
	s_nop 0
	global_load_dwordx4 v[64:67], v[64:65], off offset:256
	v_cvt_pk_bf16_f32 v115, v122, v123
	v_cvt_pk_bf16_f32 v119, v148, v149
	v_pk_add_f32 v[110:111], v[110:111], v[192:193]
	v_pk_add_f32 v[122:123], v[106:107], v[194:195]
	global_store_dwordx4 v[172:173], v[112:115], off
	global_store_dwordx4 v[172:173], v[116:119], off offset:256
	v_cvt_pk_bf16_f32 v104, v120, v121
	v_lshl_add_u64 v[112:113], s[28:29], 0, v[176:177]
	v_cvt_pk_bf16_f32 v105, v110, v111
	v_cvt_pk_bf16_f32 v106, v108, v109
	v_cvt_pk_bf16_f32 v107, v122, v123
	v_lshl_add_u64 v[112:113], v[112:113], 0, v[170:171]
	v_cvt_pk_bf16_f32 v146, v100, v101
	v_cvt_pk_bf16_f32 v147, v102, v103
	v_cvt_pk_bf16_f32 v148, v124, v125
	v_cvt_pk_bf16_f32 v149, v126, v127
	global_store_dwordx4 v[112:113], v[104:107], off
	global_store_dwordx4 v[112:113], v[146:149], off offset:256
	v_cvt_pk_bf16_f32 v194, v92, v93
	v_lshl_add_u64 v[104:105], s[28:29], 0, v[180:181]
	v_cvt_pk_bf16_f32 v195, v94, v95
	v_cvt_pk_bf16_f32 v196, v88, v89
	v_cvt_pk_bf16_f32 v197, v90, v91
	v_lshl_add_u64 v[104:105], v[104:105], 0, v[170:171]
	v_cvt_pk_bf16_f32 v214, v96, v97
	v_cvt_pk_bf16_f32 v215, v136, v137
	v_cvt_pk_bf16_f32 v216, v98, v99
	v_cvt_pk_bf16_f32 v217, v138, v139
	global_store_dwordx4 v[104:105], v[194:197], off
	global_store_dwordx4 v[104:105], v[214:217], off offset:256
	v_lshl_add_u64 v[104:105], s[28:29], 0, v[178:179]
	v_cvt_pk_bf16_f32 v222, v74, v75
	v_cvt_pk_bf16_f32 v223, v80, v81
	v_cvt_pk_bf16_f32 v224, v78, v79
	v_cvt_pk_bf16_f32 v225, v82, v83
	v_lshl_add_u64 v[104:105], v[104:105], 0, v[170:171]
	v_cvt_pk_bf16_f32 v230, v84, v85
	v_cvt_pk_bf16_f32 v231, v128, v129
	v_cvt_pk_bf16_f32 v232, v86, v87
	v_cvt_pk_bf16_f32 v233, v130, v131
	global_store_dwordx4 v[104:105], v[222:225], off
	global_store_dwordx4 v[104:105], v[230:233], off offset:256
	s_waitcnt vmcnt(8)
	v_lshlrev_b32_e32 v104, 16, v210
	v_and_b32_e32 v105, 0xffff0000, v210
	v_pk_add_f32 v[60:61], v[60:61], v[104:105]
	v_lshlrev_b32_e32 v104, 16, v212
	v_and_b32_e32 v105, 0xffff0000, v212
	v_pk_add_f32 v[56:57], v[56:57], v[104:105]
	v_lshlrev_b32_e32 v104, 16, v211
	v_and_b32_e32 v105, 0xffff0000, v211
	v_pk_add_f32 v[62:63], v[62:63], v[104:105]
	v_lshlrev_b32_e32 v104, 16, v213
	v_and_b32_e32 v105, 0xffff0000, v213
	v_pk_add_f32 v[58:59], v[58:59], v[104:105]
	v_lshlrev_b32_e32 v104, 16, v218
	v_and_b32_e32 v105, 0xffff0000, v218
	v_pk_add_f32 v[52:53], v[52:53], v[104:105]
	v_lshlrev_b32_e32 v104, 16, v220
	v_and_b32_e32 v105, 0xffff0000, v220
	v_pk_add_f32 v[104:105], v[44:45], v[104:105]
	v_lshlrev_b32_e32 v44, 16, v219
	v_and_b32_e32 v45, 0xffff0000, v219
	v_pk_add_f32 v[54:55], v[54:55], v[44:45]
	v_lshlrev_b32_e32 v44, 16, v221
	v_and_b32_e32 v45, 0xffff0000, v221
	v_pk_add_f32 v[106:107], v[46:47], v[44:45]
	v_lshlrev_b32_e32 v44, 16, v226
	v_and_b32_e32 v45, 0xffff0000, v226
	v_pk_add_f32 v[44:45], v[48:49], v[44:45]
	v_lshlrev_b32_e32 v48, 16, v229
	v_and_b32_e32 v49, 0xffff0000, v229
	v_pk_add_f32 v[42:43], v[42:43], v[48:49]
	v_lshlrev_b32_e32 v48, 16, v234
	v_and_b32_e32 v49, 0xffff0000, v234
	v_pk_add_f32 v[36:37], v[36:37], v[48:49]
	v_lshlrev_b32_e32 v48, 16, v236
	v_and_b32_e32 v49, 0xffff0000, v236
	v_lshlrev_b32_e32 v46, 16, v228
	v_and_b32_e32 v47, 0xffff0000, v228
	v_pk_add_f32 v[48:49], v[28:29], v[48:49]
	v_lshlrev_b32_e32 v28, 16, v235
	v_and_b32_e32 v29, 0xffff0000, v235
	v_pk_add_f32 v[40:41], v[40:41], v[46:47]
	v_lshlrev_b32_e32 v46, 16, v227
	v_and_b32_e32 v47, 0xffff0000, v227
	v_pk_add_f32 v[38:39], v[38:39], v[28:29]
	v_lshlrev_b32_e32 v28, 16, v237
	v_and_b32_e32 v29, 0xffff0000, v237
	v_pk_add_f32 v[46:47], v[50:51], v[46:47]
	v_pk_add_f32 v[50:51], v[30:31], v[28:29]
	v_lshlrev_b32_e32 v28, 16, v238
	v_and_b32_e32 v29, 0xffff0000, v238
	v_lshlrev_b32_e32 v180, 16, v64
	v_and_b32_e32 v181, 0xffff0000, v64
	v_pk_add_f32 v[28:29], v[32:33], v[28:29]
	v_lshlrev_b32_e32 v32, 16, v241
	v_and_b32_e32 v33, 0xffff0000, v241
	v_pk_add_f32 v[4:5], v[4:5], v[180:181]
	v_lshlrev_b32_e32 v180, 16, v66
	v_and_b32_e32 v181, 0xffff0000, v66
	v_pk_add_f32 v[26:27], v[26:27], v[32:33]
	v_lshlrev_b32_e32 v32, 16, v242
	v_and_b32_e32 v33, 0xffff0000, v242
	v_pk_add_f32 v[0:1], v[0:1], v[180:181]
	v_lshl_add_u64 v[180:181], s[28:29], 0, v[182:183]
	v_cvt_pk_bf16_f32 v112, v60, v61
	v_cvt_pk_bf16_f32 v113, v62, v63
	v_cvt_pk_bf16_f32 v114, v56, v57
	v_cvt_pk_bf16_f32 v115, v58, v59
	v_pk_add_f32 v[20:21], v[20:21], v[32:33]
	v_lshlrev_b32_e32 v32, 16, v244
	v_and_b32_e32 v33, 0xffff0000, v244
	v_lshl_add_u64 v[180:181], v[180:181], 0, v[170:171]
	v_cvt_pk_bf16_f32 v116, v52, v53
	v_cvt_pk_bf16_f32 v117, v54, v55
	v_cvt_pk_bf16_f32 v118, v104, v105
	v_cvt_pk_bf16_f32 v119, v106, v107
	v_lshlrev_b32_e32 v30, 16, v240
	v_and_b32_e32 v31, 0xffff0000, v240
	v_pk_add_f32 v[32:33], v[12:13], v[32:33]
	v_lshlrev_b32_e32 v12, 16, v243
	v_and_b32_e32 v13, 0xffff0000, v243
	global_store_dwordx4 v[180:181], v[112:115], off
	global_store_dwordx4 v[180:181], v[116:119], off offset:256
	v_cvt_pk_bf16_f32 v146, v44, v45
	v_lshl_add_u64 v[112:113], s[28:29], 0, v[132:133]
	v_cvt_pk_bf16_f32 v147, v46, v47
	v_cvt_pk_bf16_f32 v148, v40, v41
	v_cvt_pk_bf16_f32 v149, v42, v43
	v_pk_add_f32 v[24:25], v[24:25], v[30:31]
	v_lshlrev_b32_e32 v30, 16, v239
	v_and_b32_e32 v31, 0xffff0000, v239
	v_pk_add_f32 v[22:23], v[22:23], v[12:13]
	v_lshlrev_b32_e32 v12, 16, v245
	v_and_b32_e32 v13, 0xffff0000, v245
	v_lshl_add_u64 v[112:113], v[112:113], 0, v[170:171]
	v_cvt_pk_bf16_f32 v172, v36, v37
	v_cvt_pk_bf16_f32 v173, v38, v39
	v_cvt_pk_bf16_f32 v174, v48, v49
	v_cvt_pk_bf16_f32 v175, v50, v51
	v_pk_add_f32 v[30:31], v[34:35], v[30:31]
	v_pk_add_f32 v[34:35], v[14:15], v[12:13]
	v_lshlrev_b32_e32 v12, 16, v246
	v_and_b32_e32 v13, 0xffff0000, v246
	v_lshlrev_b32_e32 v14, 16, v248
	v_and_b32_e32 v15, 0xffff0000, v248
	global_store_dwordx4 v[112:113], v[146:149], off
	global_store_dwordx4 v[112:113], v[172:175], off offset:256
	v_lshl_add_u64 v[112:113], s[28:29], 0, v[134:135]
	v_cvt_pk_bf16_f32 v176, v28, v29
	v_cvt_pk_bf16_f32 v177, v30, v31
	v_cvt_pk_bf16_f32 v178, v24, v25
	v_cvt_pk_bf16_f32 v179, v26, v27
	v_pk_add_f32 v[12:13], v[16:17], v[12:13]
	v_pk_add_f32 v[8:9], v[8:9], v[14:15]
	v_lshlrev_b32_e32 v14, 16, v247
	v_and_b32_e32 v15, 0xffff0000, v247
	v_lshlrev_b32_e32 v16, 16, v249
	v_and_b32_e32 v17, 0xffff0000, v249
	v_lshlrev_b32_e32 v64, 16, v65
	v_and_b32_e32 v65, 0xffff0000, v65
	v_lshl_add_u64 v[112:113], v[112:113], 0, v[170:171]
	v_cvt_pk_bf16_f32 v194, v20, v21
	v_cvt_pk_bf16_f32 v195, v22, v23
	v_cvt_pk_bf16_f32 v196, v32, v33
	v_cvt_pk_bf16_f32 v197, v34, v35
	v_pk_add_f32 v[14:15], v[18:19], v[14:15]
	v_pk_add_f32 v[10:11], v[10:11], v[16:17]
	v_pk_add_f32 v[6:7], v[6:7], v[64:65]
	v_lshlrev_b32_e32 v64, 16, v67
	v_and_b32_e32 v65, 0xffff0000, v67
	global_store_dwordx4 v[112:113], v[176:179], off
	global_store_dwordx4 v[112:113], v[194:197], off offset:256
	v_lshl_add_u64 v[112:113], s[28:29], 0, v[184:185]
	v_cvt_pk_bf16_f32 v16, v12, v13
	v_cvt_pk_bf16_f32 v17, v14, v15
	v_cvt_pk_bf16_f32 v18, v8, v9
	v_cvt_pk_bf16_f32 v19, v10, v11
	v_pk_add_f32 v[2:3], v[2:3], v[64:65]
	v_lshl_add_u64 v[112:113], v[112:113], 0, v[170:171]
	v_cvt_pk_bf16_f32 v64, v4, v5
	v_cvt_pk_bf16_f32 v65, v6, v7
	v_cvt_pk_bf16_f32 v66, v0, v1
	v_cvt_pk_bf16_f32 v67, v2, v3
	global_store_dwordx4 v[112:113], v[16:19], off
	global_store_dwordx4 v[112:113], v[64:67], off offset:256
	s_lshl_b32 s10, s85, 2
	v_and_b32_e32 v17, 64, v188
	v_xor_b32_e32 v16, 16, v188
	v_add_u32_e32 v17, 64, v17
	v_cmp_lt_i32_e32 vcc, v16, v17
	v_xor_b32_e32 v18, 32, v188
	s_ashr_i32 s11, s10, 31
	v_cndmask_b32_e32 v16, v188, v16, vcc
	v_lshlrev_b32_e32 v16, 2, v16
	v_mov_b32_e32 v132, v209
	v_cmp_lt_i32_e32 vcc, v18, v17
	s_lshl_b64 s[10:11], s[10:11], 2
	s_add_u32 s50, s83, s10
	v_cndmask_b32_e32 v17, v188, v18, vcc
	v_lshlrev_b32_e32 v17, 2, v17
	s_addc_u32 s51, s84, s11
	v_pk_mul_f32 v[18:19], v[120:121], v[120:121]
	v_pk_fma_f32 v[18:19], v[110:111], v[110:111], v[18:19]
	v_pk_fma_f32 v[18:19], v[108:109], v[108:109], v[18:19]
	v_pk_fma_f32 v[18:19], v[122:123], v[122:123], v[18:19]
	v_pk_fma_f32 v[18:19], v[100:101], v[100:101], v[18:19]
	v_pk_fma_f32 v[18:19], v[102:103], v[102:103], v[18:19]
	v_pk_fma_f32 v[18:19], v[124:125], v[124:125], v[18:19]
	v_pk_fma_f32 v[18:19], v[126:127], v[126:127], v[18:19]
	v_add_f32_e32 v18, v18, v19
	v_mov_b32_e32 v133, v18
	v_pk_mul_f32 v[18:19], v[92:93], v[92:93]
	v_pk_fma_f32 v[18:19], v[94:95], v[94:95], v[18:19]
	v_pk_fma_f32 v[18:19], v[88:89], v[88:89], v[18:19]
	v_pk_fma_f32 v[18:19], v[90:91], v[90:91], v[18:19]
	v_pk_fma_f32 v[18:19], v[96:97], v[96:97], v[18:19]
	v_pk_fma_f32 v[18:19], v[136:137], v[136:137], v[18:19]
	v_pk_fma_f32 v[18:19], v[98:99], v[98:99], v[18:19]
	v_pk_fma_f32 v[18:19], v[138:139], v[138:139], v[18:19]
	v_add_f32_e32 v18, v18, v19
	v_mov_b32_e32 v134, v18
	v_pk_mul_f32 v[18:19], v[74:75], v[74:75]
	v_pk_mul_f32 v[192:193], v[60:61], v[60:61]
	v_pk_fma_f32 v[18:19], v[80:81], v[80:81], v[18:19]
	v_pk_fma_f32 v[192:193], v[62:63], v[62:63], v[192:193]
	v_pk_fma_f32 v[18:19], v[78:79], v[78:79], v[18:19]
	v_pk_fma_f32 v[192:193], v[56:57], v[56:57], v[192:193]
	v_pk_fma_f32 v[18:19], v[82:83], v[82:83], v[18:19]
	v_pk_fma_f32 v[192:193], v[58:59], v[58:59], v[192:193]
	v_pk_fma_f32 v[18:19], v[84:85], v[84:85], v[18:19]
	v_pk_fma_f32 v[192:193], v[52:53], v[52:53], v[192:193]
	v_pk_fma_f32 v[18:19], v[128:129], v[128:129], v[18:19]
	v_pk_fma_f32 v[192:193], v[54:55], v[54:55], v[192:193]
	v_pk_fma_f32 v[18:19], v[86:87], v[86:87], v[18:19]
	v_pk_fma_f32 v[192:193], v[104:105], v[104:105], v[192:193]
	v_pk_fma_f32 v[18:19], v[130:131], v[130:131], v[18:19]
	v_pk_fma_f32 v[192:193], v[106:107], v[106:107], v[192:193]
	v_add_f32_e32 v18, v18, v19
	v_add_f32_e32 v192, v192, v193
	v_mov_b32_e32 v135, v18
	v_mov_b32_e32 v146, v192
	v_pk_mul_f32 v[18:19], v[44:45], v[44:45]
	v_pk_mul_f32 v[192:193], v[28:29], v[28:29]
	v_pk_fma_f32 v[18:19], v[46:47], v[46:47], v[18:19]
	v_pk_fma_f32 v[192:193], v[30:31], v[30:31], v[192:193]
	v_pk_fma_f32 v[18:19], v[40:41], v[40:41], v[18:19]
	v_pk_fma_f32 v[192:193], v[24:25], v[24:25], v[192:193]
	v_pk_fma_f32 v[18:19], v[42:43], v[42:43], v[18:19]
	v_pk_fma_f32 v[192:193], v[26:27], v[26:27], v[192:193]
	v_pk_fma_f32 v[18:19], v[36:37], v[36:37], v[18:19]
	v_pk_fma_f32 v[192:193], v[20:21], v[20:21], v[192:193]
	v_pk_fma_f32 v[18:19], v[38:39], v[38:39], v[18:19]
	v_pk_fma_f32 v[192:193], v[22:23], v[22:23], v[192:193]
	v_pk_fma_f32 v[18:19], v[48:49], v[48:49], v[18:19]
	v_pk_fma_f32 v[192:193], v[32:33], v[32:33], v[192:193]
	v_pk_fma_f32 v[18:19], v[50:51], v[50:51], v[18:19]
	v_pk_fma_f32 v[192:193], v[34:35], v[34:35], v[192:193]
	v_add_f32_e32 v18, v18, v19
	v_add_f32_e32 v192, v192, v193
	v_mov_b32_e32 v147, v18
	v_mov_b32_e32 v148, v192
	v_pk_mul_f32 v[18:19], v[12:13], v[12:13]
	v_pk_fma_f32 v[18:19], v[14:15], v[14:15], v[18:19]
	v_pk_fma_f32 v[18:19], v[8:9], v[8:9], v[18:19]
	v_pk_fma_f32 v[18:19], v[10:11], v[10:11], v[18:19]
	v_pk_fma_f32 v[18:19], v[4:5], v[4:5], v[18:19]
	v_pk_fma_f32 v[18:19], v[6:7], v[6:7], v[18:19]
	v_pk_fma_f32 v[18:19], v[0:1], v[0:1], v[18:19]
	v_pk_fma_f32 v[18:19], v[2:3], v[2:3], v[18:19]
	v_add_f32_e32 v0, v18, v19
	v_mov_b32_e32 v149, v0
	ds_bpermute_b32 v172, v16, v132
	ds_bpermute_b32 v173, v16, v133
	ds_bpermute_b32 v174, v16, v134
	ds_bpermute_b32 v175, v16, v135
	ds_bpermute_b32 v180, v16, v146
	ds_bpermute_b32 v181, v16, v147
	ds_bpermute_b32 v182, v16, v148
	ds_bpermute_b32 v183, v16, v149
	s_waitcnt lgkmcnt(0)
	v_add_f32_e32 v132, v132, v172
	v_add_f32_e32 v133, v133, v173
	v_add_f32_e32 v134, v134, v174
	v_add_f32_e32 v135, v135, v175
	v_add_f32_e32 v146, v146, v180
	v_add_f32_e32 v147, v147, v181
	v_add_f32_e32 v148, v148, v182
	v_add_f32_e32 v149, v149, v183
	ds_bpermute_b32 v172, v17, v132
	ds_bpermute_b32 v173, v17, v133
	ds_bpermute_b32 v174, v17, v134
	ds_bpermute_b32 v175, v17, v135
	ds_bpermute_b32 v180, v17, v146
	ds_bpermute_b32 v181, v17, v147
	ds_bpermute_b32 v182, v17, v148
	ds_bpermute_b32 v183, v17, v149
	s_and_saveexec_b64 s[52:53], s[42:43]
	s_cbranch_execz .LBB0_91
	s_waitcnt lgkmcnt(0)
	v_add_f32_e32 v132, v132, v172
	v_lshlrev_b64 v[18:19], 6, v[168:169]
	v_lshl_add_u64 v[18:19], s[50:51], 0, v[18:19]
	global_store_dword v[18:19], v132, off
	v_add_f32_e32 v133, v133, v173
	v_lshlrev_b64 v[18:19], 6, v[166:167]
	v_lshl_add_u64 v[18:19], s[50:51], 0, v[18:19]
	global_store_dword v[18:19], v133, off
	v_add_f32_e32 v134, v134, v174
	v_lshlrev_b64 v[18:19], 6, v[164:165]
	v_lshl_add_u64 v[18:19], s[50:51], 0, v[18:19]
	global_store_dword v[18:19], v134, off
	v_add_f32_e32 v135, v135, v175
	v_lshlrev_b64 v[18:19], 6, v[162:163]
	v_lshl_add_u64 v[18:19], s[50:51], 0, v[18:19]
	global_store_dword v[18:19], v135, off
	v_add_f32_e32 v146, v146, v180
	v_lshlrev_b64 v[18:19], 6, v[76:77]
	v_lshl_add_u64 v[18:19], s[50:51], 0, v[18:19]
	global_store_dword v[18:19], v146, off
	v_add_f32_e32 v147, v147, v181
	v_lshlrev_b64 v[18:19], 6, v[72:73]
	v_lshl_add_u64 v[18:19], s[50:51], 0, v[18:19]
	global_store_dword v[18:19], v147, off
	v_add_f32_e32 v148, v148, v182
	v_lshlrev_b64 v[18:19], 6, v[70:71]
	v_lshl_add_u64 v[18:19], s[50:51], 0, v[18:19]
	global_store_dword v[18:19], v148, off
	v_add_f32_e32 v149, v149, v183
	v_lshlrev_b64 v[18:19], 6, v[68:69]
	v_lshl_add_u64 v[18:19], s[50:51], 0, v[18:19]
	global_store_dword v[18:19], v149, off
	s_branch .LBB0_91

.LBB0_248:
	s_add_u32 s6, s52, 0xfffc0080
	s_addc_u32 s19, s53, -1
	s_add_i32 s23, 0, 0x10000
	v_add_u32_e32 v146, s23, v206
	ds_read_b128 v[128:131], v146
	ds_read_b128 v[132:135], v146 offset:1024
	ds_read_b128 v[136:139], v146 offset:2048
	ds_read_b128 v[146:149], v146 offset:3072
	s_cmp_eq_u32 s82, 12
	s_cselect_b32 s59, s10, s19
	s_cselect_b32 s58, s11, s6
	s_cselect_b32 s55, s12, s51
	s_cselect_b32 s54, s35, s39
	v_lshl_add_u64 v[214:215], s[52:53], 0, v[158:159]
	s_add_i32 m0, s68, 0xc000
	ds_read_b128 v[162:165], v208
	ds_read_b128 v[166:169], v208 offset:1024
	ds_read_b128 v[170:173], v208 offset:2048
	ds_read_b128 v[174:177], v208 offset:3072
	ds_read_b128 v[178:181], v208 offset:4096
	ds_read_b128 v[182:185], v208 offset:5120
	ds_read_b128 v[194:197], v208 offset:6144
	ds_read_b128 v[210:213], v208 offset:7168
	global_load_lds_dwordx4 v[214:215], off
	v_lshl_add_u64 v[214:215], s[52:53], 0, v[160:161]
	s_add_i32 m0, s68, 0xe000
	s_nop 0
	global_load_lds_dwordx4 v[214:215], off
	s_add_i32 s6, 0, 0x14000
	v_add_u32_e32 v192, s6, v206
	ds_read_b128 v[214:217], v192
	ds_read_b128 v[218:221], v192 offset:1024
	ds_read_b128 v[222:225], v192 offset:2048
	ds_read_b128 v[226:229], v192 offset:3072
	s_nop 0
	s_waitcnt vmcnt(8)
	s_waitcnt lgkmcnt(0)
	s_barrier
	v_mfma_f32_16x16x32_bf16 v[124:127], v[128:131], v[162:165], v[124:127]
	v_mfma_f32_16x16x32_bf16 v[120:123], v[136:139], v[162:165], v[120:123]
	v_mfma_f32_16x16x32_bf16 v[108:111], v[128:131], v[170:173], v[108:111]
	v_mfma_f32_16x16x32_bf16 v[104:107], v[136:139], v[170:173], v[104:107]
	v_mfma_f32_16x16x32_bf16 v[96:99], v[128:131], v[178:181], v[96:99]
	v_mfma_f32_16x16x32_bf16 v[88:91], v[136:139], v[178:181], v[88:91]
	v_mfma_f32_16x16x32_bf16 v[84:87], v[128:131], v[194:197], v[84:87]
	v_mfma_f32_16x16x32_bf16 v[80:83], v[136:139], v[194:197], v[80:83]
	v_mfma_f32_16x16x32_bf16 v[124:127], v[132:135], v[166:169], v[124:127]
	v_mfma_f32_16x16x32_bf16 v[120:123], v[146:149], v[166:169], v[120:123]
	v_mfma_f32_16x16x32_bf16 v[108:111], v[132:135], v[174:177], v[108:111]
	v_mfma_f32_16x16x32_bf16 v[104:107], v[146:149], v[174:177], v[104:107]
	v_mfma_f32_16x16x32_bf16 v[96:99], v[132:135], v[182:185], v[96:99]
	v_mfma_f32_16x16x32_bf16 v[88:91], v[146:149], v[182:185], v[88:91]
	v_mfma_f32_16x16x32_bf16 v[84:87], v[132:135], v[210:213], v[84:87]
	v_mfma_f32_16x16x32_bf16 v[80:83], v[146:149], v[210:213], v[80:83]
	v_mfma_f32_16x16x32_bf16 v[116:119], v[214:217], v[162:165], v[116:119]
	v_mfma_f32_16x16x32_bf16 v[112:115], v[222:225], v[162:165], v[112:115]
	v_mfma_f32_16x16x32_bf16 v[100:103], v[214:217], v[170:173], v[100:103]
	v_mfma_f32_16x16x32_bf16 v[92:95], v[222:225], v[170:173], v[92:95]
	v_mfma_f32_16x16x32_bf16 v[76:79], v[214:217], v[178:181], v[76:79]
	v_mfma_f32_16x16x32_bf16 v[72:75], v[222:225], v[178:181], v[72:75]
	v_mfma_f32_16x16x32_bf16 v[68:71], v[214:217], v[194:197], v[68:71]
	v_mfma_f32_16x16x32_bf16 v[64:67], v[222:225], v[194:197], v[64:67]
	v_mfma_f32_16x16x32_bf16 v[116:119], v[218:221], v[166:169], v[116:119]
	v_mfma_f32_16x16x32_bf16 v[112:115], v[226:229], v[166:169], v[112:115]
	v_mfma_f32_16x16x32_bf16 v[100:103], v[218:221], v[174:177], v[100:103]
	v_mfma_f32_16x16x32_bf16 v[92:95], v[226:229], v[174:177], v[92:95]
	v_mfma_f32_16x16x32_bf16 v[76:79], v[218:221], v[182:185], v[76:79]
	v_mfma_f32_16x16x32_bf16 v[72:75], v[226:229], v[182:185], v[72:75]
	v_mfma_f32_16x16x32_bf16 v[68:71], v[218:221], v[210:213], v[68:71]
	v_mfma_f32_16x16x32_bf16 v[64:67], v[226:229], v[210:213], v[64:67]
	s_barrier
	s_add_i32 s19, s23, s57
	v_lshl_add_u64 v[230:231], s[54:55], 0, v[140:141]
	s_mov_b32 m0, s19
	s_nop 0
	global_load_lds_dwordx4 v[230:231], off
	v_lshl_add_u64 v[232:233], s[54:55], 0, v[150:151]
	s_add_i32 m0, s19, 0x2000
	s_nop 0
	global_load_lds_dwordx4 v[232:233], off
	s_mov_b32 m0, s68
	v_lshl_add_u64 v[234:235], s[58:59], 0, v[154:155]
	ds_read_b128 v[162:165], v208 offset:16384
	ds_read_b128 v[166:169], v208 offset:17408
	ds_read_b128 v[170:173], v208 offset:18432
	ds_read_b128 v[174:177], v208 offset:19456
	ds_read_b128 v[178:181], v208 offset:20480
	ds_read_b128 v[182:185], v208 offset:21504
	ds_read_b128 v[194:197], v208 offset:22528
	ds_read_b128 v[210:213], v208 offset:23552
	global_load_lds_dwordx4 v[234:235], off
	v_lshl_add_u64 v[236:237], s[58:59], 0, v[152:153]
	s_mov_b32 m0, s69
	s_nop 0
	global_load_lds_dwordx4 v[236:237], off
	s_add_u32 s84, s54, 0x40000
	s_addc_u32 s85, s55, 0
	s_add_i32 s6, s6, s57
	v_lshl_add_u64 v[250:251], s[84:85], 0, v[140:141]
	s_mov_b32 m0, s6
	s_nop 0
	global_load_lds_dwordx4 v[250:251], off
	v_lshl_add_u64 v[250:251], s[84:85], 0, v[150:151]
	s_add_i32 m0, s6, 0x2000
	s_nop 0
	global_load_lds_dwordx4 v[250:251], off
	s_waitcnt vmcnt(8)
	s_waitcnt lgkmcnt(0)
	s_barrier
	v_mfma_f32_16x16x32_bf16 v[60:63], v[128:131], v[162:165], v[60:63]
	v_mfma_f32_16x16x32_bf16 v[56:59], v[136:139], v[162:165], v[56:59]
	v_mfma_f32_16x16x32_bf16 v[48:51], v[128:131], v[170:173], v[48:51]
	v_mfma_f32_16x16x32_bf16 v[40:43], v[136:139], v[170:173], v[40:43]
	v_mfma_f32_16x16x32_bf16 v[32:35], v[128:131], v[178:181], v[32:35]
	v_mfma_f32_16x16x32_bf16 v[24:27], v[136:139], v[178:181], v[24:27]
	v_mfma_f32_16x16x32_bf16 v[16:19], v[128:131], v[194:197], v[16:19]
	v_mfma_f32_16x16x32_bf16 v[8:11], v[136:139], v[194:197], v[8:11]
	v_mfma_f32_16x16x32_bf16 v[60:63], v[132:135], v[166:169], v[60:63]
	v_mfma_f32_16x16x32_bf16 v[56:59], v[146:149], v[166:169], v[56:59]
	v_mfma_f32_16x16x32_bf16 v[48:51], v[132:135], v[174:177], v[48:51]
	v_mfma_f32_16x16x32_bf16 v[40:43], v[146:149], v[174:177], v[40:43]
	v_mfma_f32_16x16x32_bf16 v[32:35], v[132:135], v[182:185], v[32:35]
	v_mfma_f32_16x16x32_bf16 v[24:27], v[146:149], v[182:185], v[24:27]
	v_mfma_f32_16x16x32_bf16 v[16:19], v[132:135], v[210:213], v[16:19]
	v_mfma_f32_16x16x32_bf16 v[8:11], v[146:149], v[210:213], v[8:11]
	v_mfma_f32_16x16x32_bf16 v[52:55], v[214:217], v[162:165], v[52:55]
	v_mfma_f32_16x16x32_bf16 v[44:47], v[222:225], v[162:165], v[44:47]
	v_mfma_f32_16x16x32_bf16 v[36:39], v[214:217], v[170:173], v[36:39]
	v_mfma_f32_16x16x32_bf16 v[28:31], v[222:225], v[170:173], v[28:31]
	v_mfma_f32_16x16x32_bf16 v[20:23], v[214:217], v[178:181], v[20:23]
	v_mfma_f32_16x16x32_bf16 v[12:15], v[222:225], v[178:181], v[12:15]
	v_mfma_f32_16x16x32_bf16 v[4:7], v[214:217], v[194:197], v[4:7]
	v_mfma_f32_16x16x32_bf16 v[0:3], v[222:225], v[194:197], v[0:3]
	v_mfma_f32_16x16x32_bf16 v[52:55], v[218:221], v[166:169], v[52:55]
	v_mfma_f32_16x16x32_bf16 v[44:47], v[226:229], v[166:169], v[44:47]
	v_mfma_f32_16x16x32_bf16 v[36:39], v[218:221], v[174:177], v[36:39]
	v_mfma_f32_16x16x32_bf16 v[28:31], v[226:229], v[174:177], v[28:31]
	v_mfma_f32_16x16x32_bf16 v[20:23], v[218:221], v[182:185], v[20:23]
	v_mfma_f32_16x16x32_bf16 v[12:15], v[226:229], v[182:185], v[12:15]
	v_mfma_f32_16x16x32_bf16 v[4:7], v[218:221], v[210:213], v[4:7]
	v_mfma_f32_16x16x32_bf16 v[0:3], v[226:229], v[210:213], v[0:3]
	s_barrier
	s_add_i32 s6, 0, 0x18000
	v_add_u32_e32 v146, s6, v206
	ds_read_b128 v[128:131], v146
	ds_read_b128 v[132:135], v146 offset:1024
	ds_read_b128 v[136:139], v146 offset:2048
	ds_read_b128 v[146:149], v146 offset:3072
	s_add_u32 s58, s58, 0x40000
	s_addc_u32 s59, s59, 0
	s_mov_b32 m0, s70
	v_lshl_add_u64 v[214:215], s[58:59], 0, v[154:155]
	ds_read_b128 v[162:165], v208 offset:32768
	ds_read_b128 v[166:169], v208 offset:33792
	ds_read_b128 v[170:173], v208 offset:34816
	ds_read_b128 v[174:177], v208 offset:35840
	ds_read_b128 v[178:181], v208 offset:36864
	ds_read_b128 v[182:185], v208 offset:37888
	ds_read_b128 v[194:197], v208 offset:38912
	ds_read_b128 v[210:213], v208 offset:39936
	global_load_lds_dwordx4 v[214:215], off
	v_lshl_add_u64 v[214:215], s[58:59], 0, v[152:153]
	s_mov_b32 m0, s71
	s_nop 0
	global_load_lds_dwordx4 v[214:215], off
	s_add_i32 s19, 0, 0x1c000
	v_add_u32_e32 v192, s19, v206
	ds_read_b128 v[214:217], v192
	ds_read_b128 v[218:221], v192 offset:1024
	ds_read_b128 v[222:225], v192 offset:2048
	ds_read_b128 v[226:229], v192 offset:3072
	s_waitcnt vmcnt(8)
	s_waitcnt lgkmcnt(0)
	s_barrier
	v_mfma_f32_16x16x32_bf16 v[124:127], v[128:131], v[162:165], v[124:127]
	v_mfma_f32_16x16x32_bf16 v[120:123], v[136:139], v[162:165], v[120:123]
	v_mfma_f32_16x16x32_bf16 v[108:111], v[128:131], v[170:173], v[108:111]
	v_mfma_f32_16x16x32_bf16 v[104:107], v[136:139], v[170:173], v[104:107]
	v_mfma_f32_16x16x32_bf16 v[96:99], v[128:131], v[178:181], v[96:99]
	v_mfma_f32_16x16x32_bf16 v[88:91], v[136:139], v[178:181], v[88:91]
	v_mfma_f32_16x16x32_bf16 v[84:87], v[128:131], v[194:197], v[84:87]
	v_mfma_f32_16x16x32_bf16 v[80:83], v[136:139], v[194:197], v[80:83]
	v_mfma_f32_16x16x32_bf16 v[124:127], v[132:135], v[166:169], v[124:127]
	v_mfma_f32_16x16x32_bf16 v[120:123], v[146:149], v[166:169], v[120:123]
	v_mfma_f32_16x16x32_bf16 v[108:111], v[132:135], v[174:177], v[108:111]
	v_mfma_f32_16x16x32_bf16 v[104:107], v[146:149], v[174:177], v[104:107]
	v_mfma_f32_16x16x32_bf16 v[96:99], v[132:135], v[182:185], v[96:99]
	v_mfma_f32_16x16x32_bf16 v[88:91], v[146:149], v[182:185], v[88:91]
	v_mfma_f32_16x16x32_bf16 v[84:87], v[132:135], v[210:213], v[84:87]
	v_mfma_f32_16x16x32_bf16 v[80:83], v[146:149], v[210:213], v[80:83]
	v_mfma_f32_16x16x32_bf16 v[116:119], v[214:217], v[162:165], v[116:119]
	v_mfma_f32_16x16x32_bf16 v[112:115], v[222:225], v[162:165], v[112:115]
	v_mfma_f32_16x16x32_bf16 v[100:103], v[214:217], v[170:173], v[100:103]
	v_mfma_f32_16x16x32_bf16 v[92:95], v[222:225], v[170:173], v[92:95]
	v_mfma_f32_16x16x32_bf16 v[76:79], v[214:217], v[178:181], v[76:79]
	v_mfma_f32_16x16x32_bf16 v[72:75], v[222:225], v[178:181], v[72:75]
	v_mfma_f32_16x16x32_bf16 v[68:71], v[214:217], v[194:197], v[68:71]
	v_mfma_f32_16x16x32_bf16 v[64:67], v[222:225], v[194:197], v[64:67]
	v_mfma_f32_16x16x32_bf16 v[116:119], v[218:221], v[166:169], v[116:119]
	v_mfma_f32_16x16x32_bf16 v[112:115], v[226:229], v[166:169], v[112:115]
	v_mfma_f32_16x16x32_bf16 v[100:103], v[218:221], v[174:177], v[100:103]
	v_mfma_f32_16x16x32_bf16 v[92:95], v[226:229], v[174:177], v[92:95]
	v_mfma_f32_16x16x32_bf16 v[76:79], v[218:221], v[182:185], v[76:79]
	v_mfma_f32_16x16x32_bf16 v[72:75], v[226:229], v[182:185], v[72:75]
	v_mfma_f32_16x16x32_bf16 v[68:71], v[218:221], v[210:213], v[68:71]
	v_mfma_f32_16x16x32_bf16 v[64:67], v[226:229], v[210:213], v[64:67]
	s_barrier
	s_add_i32 s6, s6, s57
	v_lshl_add_u64 v[230:231], v[230:231], 0, s[36:37]
	s_mov_b32 m0, s6
	s_nop 0
	global_load_lds_dwordx4 v[230:231], off
	v_lshl_add_u64 v[230:231], v[232:233], 0, s[36:37]
	s_add_i32 m0, s6, 0x2000
	s_nop 0
	global_load_lds_dwordx4 v[230:231], off
	s_mov_b32 m0, s72
	v_lshl_add_u64 v[230:231], v[234:235], 0, s[36:37]
	ds_read_b128 v[162:165], v208 offset:49152
	ds_read_b128 v[166:169], v208 offset:50176
	ds_read_b128 v[170:173], v208 offset:51200
	ds_read_b128 v[174:177], v208 offset:52224
	ds_read_b128 v[178:181], v208 offset:53248
	ds_read_b128 v[182:185], v208 offset:54272
	ds_read_b128 v[194:197], v208 offset:55296
	ds_read_b128 v[210:213], v208 offset:56320
	global_load_lds_dwordx4 v[230:231], off
	v_lshl_add_u64 v[230:231], v[236:237], 0, s[36:37]
	s_mov_b32 m0, s73
	s_nop 0
	global_load_lds_dwordx4 v[230:231], off
	s_add_u32 s54, s54, 0x40080
	s_addc_u32 s55, s55, 0
	s_add_i32 s6, s19, s57
	v_lshl_add_u64 v[250:251], s[54:55], 0, v[140:141]
	s_mov_b32 m0, s6
	s_nop 0
	global_load_lds_dwordx4 v[250:251], off
	v_lshl_add_u64 v[250:251], s[54:55], 0, v[150:151]
	s_add_i32 m0, s6, 0x2000
	s_nop 0
	global_load_lds_dwordx4 v[250:251], off
	s_add_i32 s82, s82, 2
	s_add_u32 s52, s52, 0x100
	s_addc_u32 s53, s53, 0
	s_add_u32 s39, s39, 0x100
	s_addc_u32 s51, s51, 0
	s_cmp_gt_u32 s82, 13
	s_waitcnt vmcnt(8)
	s_waitcnt lgkmcnt(0)
	s_barrier
	v_mfma_f32_16x16x32_bf16 v[60:63], v[128:131], v[162:165], v[60:63]
	v_mfma_f32_16x16x32_bf16 v[56:59], v[136:139], v[162:165], v[56:59]
	v_mfma_f32_16x16x32_bf16 v[48:51], v[128:131], v[170:173], v[48:51]
	v_mfma_f32_16x16x32_bf16 v[40:43], v[136:139], v[170:173], v[40:43]
	v_mfma_f32_16x16x32_bf16 v[32:35], v[128:131], v[178:181], v[32:35]
	v_mfma_f32_16x16x32_bf16 v[24:27], v[136:139], v[178:181], v[24:27]
	v_mfma_f32_16x16x32_bf16 v[16:19], v[128:131], v[194:197], v[16:19]
	v_mfma_f32_16x16x32_bf16 v[8:11], v[136:139], v[194:197], v[8:11]
	v_mfma_f32_16x16x32_bf16 v[60:63], v[132:135], v[166:169], v[60:63]
	v_mfma_f32_16x16x32_bf16 v[56:59], v[146:149], v[166:169], v[56:59]
	v_mfma_f32_16x16x32_bf16 v[48:51], v[132:135], v[174:177], v[48:51]
	v_mfma_f32_16x16x32_bf16 v[40:43], v[146:149], v[174:177], v[40:43]
	v_mfma_f32_16x16x32_bf16 v[32:35], v[132:135], v[182:185], v[32:35]
	v_mfma_f32_16x16x32_bf16 v[24:27], v[146:149], v[182:185], v[24:27]
	v_mfma_f32_16x16x32_bf16 v[16:19], v[132:135], v[210:213], v[16:19]
	v_mfma_f32_16x16x32_bf16 v[8:11], v[146:149], v[210:213], v[8:11]
	v_mfma_f32_16x16x32_bf16 v[52:55], v[214:217], v[162:165], v[52:55]
	v_mfma_f32_16x16x32_bf16 v[44:47], v[222:225], v[162:165], v[44:47]
	v_mfma_f32_16x16x32_bf16 v[36:39], v[214:217], v[170:173], v[36:39]
	v_mfma_f32_16x16x32_bf16 v[28:31], v[222:225], v[170:173], v[28:31]
	v_mfma_f32_16x16x32_bf16 v[20:23], v[214:217], v[178:181], v[20:23]
	v_mfma_f32_16x16x32_bf16 v[12:15], v[222:225], v[178:181], v[12:15]
	v_mfma_f32_16x16x32_bf16 v[4:7], v[214:217], v[194:197], v[4:7]
	v_mfma_f32_16x16x32_bf16 v[0:3], v[222:225], v[194:197], v[0:3]
	v_mfma_f32_16x16x32_bf16 v[52:55], v[218:221], v[166:169], v[52:55]
	v_mfma_f32_16x16x32_bf16 v[44:47], v[226:229], v[166:169], v[44:47]
	v_mfma_f32_16x16x32_bf16 v[36:39], v[218:221], v[174:177], v[36:39]
	v_mfma_f32_16x16x32_bf16 v[28:31], v[226:229], v[174:177], v[28:31]
	v_mfma_f32_16x16x32_bf16 v[20:23], v[218:221], v[182:185], v[20:23]
	v_mfma_f32_16x16x32_bf16 v[12:15], v[226:229], v[182:185], v[12:15]
	v_mfma_f32_16x16x32_bf16 v[4:7], v[218:221], v[210:213], v[4:7]
	v_mfma_f32_16x16x32_bf16 v[0:3], v[226:229], v[210:213], v[0:3]
	s_barrier
	s_cbranch_scc0 .LBB0_248
	s_mov_b32 s100, 1
	s_ashr_i32 s51, s50, 31
	v_lshl_or_b32 v128, s81, 8, v207
	s_lshl_b64 s[10:11], s[50:51], 8
	v_ashrrev_i32_e32 v129, 31, v128
	v_lshl_add_u64 v[168:169], s[10:11], 0, v[156:157]
	v_lshlrev_b64 v[170:171], 1, v[128:129]
	v_lshl_add_u64 v[174:175], s[28:29], 0, v[170:171]
	v_lshlrev_b64 v[172:173], 11, v[168:169]
	v_lshl_add_u64 v[128:129], v[174:175], 0, v[172:173]
	global_load_dwordx4 v[146:149], v[128:129], off
	global_load_dwordx4 v[182:185], v[128:129], off offset:256
	v_or_b32_e32 v166, 16, v168
	v_mov_b32_e32 v167, v169
	v_lshlrev_b64 v[176:177], 11, v[166:167]
	v_lshl_add_u64 v[128:129], v[174:175], 0, v[176:177]
	global_load_dwordx4 v[194:197], v[128:129], off
	global_load_dwordx4 v[210:213], v[128:129], off offset:256
	v_or_b32_e32 v164, 32, v168
	v_mov_b32_e32 v165, v169
	v_or_b32_e32 v162, 48, v168
	v_mov_b32_e32 v163, v169
	v_lshlrev_b64 v[180:181], 11, v[164:165]
	v_lshlrev_b64 v[178:179], 11, v[162:163]
	v_lshl_add_u64 v[128:129], v[174:175], 0, v[180:181]
	v_lshl_add_u64 v[130:131], v[174:175], 0, v[178:179]
	global_load_dwordx4 v[214:217], v[128:129], off
	global_load_dwordx4 v[136:139], v[128:129], off offset:256
	global_load_dwordx4 v[132:135], v[130:131], off
	s_nop 0
	global_load_dwordx4 v[128:131], v[130:131], off offset:256
	s_mov_b64 s[10:11], 0x90
	v_lshl_add_u64 v[172:173], s[30:31], 0, v[172:173]
	v_lshl_add_u64 v[172:173], v[172:173], 0, v[170:171]
	s_waitcnt vmcnt(0)
	v_lshlrev_b32_e32 v218, 16, v146
	v_and_b32_e32 v219, 0xffff0000, v146
	v_lshlrev_b32_e32 v220, 16, v148
	v_and_b32_e32 v221, 0xffff0000, v148
	v_lshlrev_b32_e32 v146, 16, v147
	v_and_b32_e32 v147, 0xffff0000, v147
	v_lshlrev_b32_e32 v222, 16, v182
	v_and_b32_e32 v223, 0xffff0000, v182
	v_lshlrev_b32_e32 v224, 16, v184
	v_and_b32_e32 v225, 0xffff0000, v184
	v_lshlrev_b32_e32 v182, 16, v183
	v_and_b32_e32 v183, 0xffff0000, v183
	v_pk_add_f32 v[124:125], v[124:125], v[218:219]
	v_pk_add_f32 v[120:121], v[120:121], v[220:221]
	v_pk_add_f32 v[126:127], v[126:127], v[146:147]
	v_pk_add_f32 v[116:117], v[116:117], v[222:223]
	v_pk_add_f32 v[146:147], v[112:113], v[224:225]
	v_pk_add_f32 v[118:119], v[118:119], v[182:183]
	v_pk_mul_f32 v[220:221], v[124:125], v[124:125]
	v_pk_mul_f32 v[222:223], v[126:127], v[126:127]
	v_cvt_pk_bf16_f32 v112, v124, v125
	v_cvt_pk_bf16_f32 v113, v126, v127
	v_pk_mul_f32 v[124:125], v[116:117], v[116:117]
	v_pk_mul_f32 v[126:127], v[118:119], v[118:119]
	v_pk_mul_f32 v[228:229], v[146:147], v[146:147]
	v_cvt_pk_bf16_f32 v116, v116, v117
	v_cvt_pk_bf16_f32 v117, v118, v119
	v_cvt_pk_bf16_f32 v118, v146, v147
	v_add_f32_e32 v146, v220, v221
	v_add_f32_e32 v146, v222, v146
	v_lshlrev_b32_e32 v148, 16, v149
	v_and_b32_e32 v149, 0xffff0000, v149
	v_pk_mul_f32 v[224:225], v[120:121], v[120:121]
	v_add_f32_e32 v146, v223, v146
	v_pk_add_f32 v[122:123], v[122:123], v[148:149]
	v_add_f32_e32 v146, v224, v146
	v_pk_mul_f32 v[226:227], v[122:123], v[122:123]
	v_add_f32_e32 v146, v225, v146
	v_add_f32_e32 v146, v226, v146
	v_add_f32_e32 v146, v227, v146
	v_add_f32_e32 v124, v124, v146
	v_add_f32_e32 v124, v125, v124
	v_add_f32_e32 v124, v126, v124
	v_lshlrev_b32_e32 v184, 16, v185
	v_and_b32_e32 v185, 0xffff0000, v185
	v_add_f32_e32 v124, v127, v124
	v_pk_add_f32 v[148:149], v[114:115], v[184:185]
	v_add_f32_e32 v124, v228, v124
	v_pk_mul_f32 v[230:231], v[148:149], v[148:149]
	v_add_f32_e32 v124, v229, v124
	v_add_f32_e32 v124, v230, v124
	v_add_f32_e32 v209, v231, v124
	v_lshlrev_b32_e32 v124, 16, v212
	v_and_b32_e32 v125, 0xffff0000, v212
	v_pk_add_f32 v[124:125], v[92:93], v[124:125]
	v_lshlrev_b32_e32 v92, 16, v211
	v_and_b32_e32 v93, 0xffff0000, v211
	v_pk_add_f32 v[102:103], v[102:103], v[92:93]
	v_lshlrev_b32_e32 v92, 16, v213
	v_and_b32_e32 v93, 0xffff0000, v213
	v_pk_add_f32 v[126:127], v[94:95], v[92:93]
	v_lshlrev_b32_e32 v92, 16, v214
	v_and_b32_e32 v93, 0xffff0000, v214
	v_pk_add_f32 v[92:93], v[96:97], v[92:93]
	v_lshlrev_b32_e32 v96, 16, v217
	v_and_b32_e32 v97, 0xffff0000, v217
	v_lshlrev_b32_e32 v94, 16, v216
	v_and_b32_e32 v95, 0xffff0000, v216
	v_pk_add_f32 v[90:91], v[90:91], v[96:97]
	v_lshlrev_b32_e32 v96, 16, v136
	v_and_b32_e32 v97, 0xffff0000, v136
	v_lshlrev_b32_e32 v182, 16, v194
	v_and_b32_e32 v183, 0xffff0000, v194
	v_pk_add_f32 v[88:89], v[88:89], v[94:95]
	v_lshlrev_b32_e32 v94, 16, v215
	v_and_b32_e32 v95, 0xffff0000, v215
	v_pk_add_f32 v[96:97], v[76:77], v[96:97]
	v_lshl_add_u64 v[76:77], v[168:169], 0, s[36:37]
	v_lshlrev_b32_e32 v184, 16, v196
	v_and_b32_e32 v185, 0xffff0000, v196
	v_cvt_pk_bf16_f32 v114, v120, v121
	v_pk_add_f32 v[120:121], v[108:109], v[182:183]
	v_pk_add_f32 v[94:95], v[98:99], v[94:95]
	v_lshlrev_b64 v[182:183], 11, v[76:77]
	v_lshlrev_b32_e32 v98, 16, v138
	v_and_b32_e32 v99, 0xffff0000, v138
	v_pk_add_f32 v[108:109], v[104:105], v[184:185]
	v_lshl_add_u64 v[184:185], v[174:175], 0, v[182:183]
	v_pk_add_f32 v[98:99], v[72:73], v[98:99]
	v_lshlrev_b32_e32 v72, 16, v137
	v_and_b32_e32 v73, 0xffff0000, v137
	v_lshlrev_b32_e32 v218, 16, v210
	v_and_b32_e32 v219, 0xffff0000, v210
	global_load_dwordx4 v[210:213], v[184:185], off
	v_pk_add_f32 v[136:137], v[78:79], v[72:73]
	v_lshlrev_b32_e32 v72, 16, v139
	v_and_b32_e32 v73, 0xffff0000, v139
	v_pk_add_f32 v[138:139], v[74:75], v[72:73]
	v_lshlrev_b32_e32 v72, 16, v132
	v_and_b32_e32 v73, 0xffff0000, v132
	v_pk_add_f32 v[74:75], v[84:85], v[72:73]
	v_lshlrev_b32_e32 v72, 16, v134
	v_and_b32_e32 v73, 0xffff0000, v134
	v_pk_add_f32 v[78:79], v[80:81], v[72:73]
	v_lshlrev_b32_e32 v72, 16, v133
	v_and_b32_e32 v73, 0xffff0000, v133
	v_pk_add_f32 v[100:101], v[100:101], v[218:219]
	global_load_dwordx4 v[218:221], v[184:185], off offset:256
	v_pk_add_f32 v[80:81], v[86:87], v[72:73]
	v_lshlrev_b32_e32 v72, 16, v135
	v_and_b32_e32 v73, 0xffff0000, v135
	v_pk_add_f32 v[82:83], v[82:83], v[72:73]
	v_lshl_add_u64 v[72:73], v[168:169], 0, s[10:11]
	v_lshlrev_b64 v[132:133], 11, v[72:73]
	v_lshl_add_u64 v[134:135], v[174:175], 0, v[132:133]
	v_lshlrev_b32_e32 v84, 16, v128
	v_and_b32_e32 v85, 0xffff0000, v128
	global_load_dwordx4 v[226:229], v[134:135], off
	global_load_dwordx4 v[234:237], v[134:135], off offset:256
	v_pk_add_f32 v[84:85], v[68:69], v[84:85]
	v_lshlrev_b32_e32 v68, 16, v130
	v_and_b32_e32 v69, 0xffff0000, v130
	v_pk_add_f32 v[86:87], v[64:65], v[68:69]
	v_lshlrev_b32_e32 v64, 16, v129
	v_and_b32_e32 v65, 0xffff0000, v129
	s_mov_b64 s[10:11], 0xa0
	v_pk_add_f32 v[128:129], v[70:71], v[64:65]
	v_lshl_add_u64 v[70:71], v[168:169], 0, s[10:11]
	s_mov_b64 s[10:11], 0xb0
	v_lshlrev_b32_e32 v64, 16, v131
	v_and_b32_e32 v65, 0xffff0000, v131
	v_lshlrev_b64 v[134:135], 11, v[70:71]
	v_lshl_add_u64 v[68:69], v[168:169], 0, s[10:11]
	v_pk_add_f32 v[130:131], v[66:67], v[64:65]
	v_lshl_add_u64 v[64:65], v[174:175], 0, v[134:135]
	v_lshlrev_b64 v[184:185], 11, v[68:69]
	global_load_dwordx4 v[238:241], v[64:65], off
	global_load_dwordx4 v[242:245], v[64:65], off offset:256
	v_lshl_add_u64 v[64:65], v[174:175], 0, v[184:185]
	global_load_dwordx4 v[246:249], v[64:65], off
	s_nop 0
	global_load_dwordx4 v[64:67], v[64:65], off offset:256
	v_lshlrev_b32_e32 v194, 16, v195
	v_and_b32_e32 v195, 0xffff0000, v195
	v_lshlrev_b32_e32 v196, 16, v197
	v_and_b32_e32 v197, 0xffff0000, v197
	v_cvt_pk_bf16_f32 v115, v122, v123
	v_cvt_pk_bf16_f32 v119, v148, v149
	v_pk_add_f32 v[122:123], v[110:111], v[194:195]
	v_pk_add_f32 v[110:111], v[106:107], v[196:197]
	global_store_dwordx4 v[172:173], v[112:115], off
	global_store_dwordx4 v[172:173], v[116:119], off offset:256
	v_cvt_pk_bf16_f32 v104, v120, v121
	v_lshl_add_u64 v[112:113], s[30:31], 0, v[176:177]
	v_cvt_pk_bf16_f32 v105, v122, v123
	v_cvt_pk_bf16_f32 v106, v108, v109
	v_cvt_pk_bf16_f32 v107, v110, v111
	v_lshl_add_u64 v[112:113], v[112:113], 0, v[170:171]
	v_cvt_pk_bf16_f32 v146, v100, v101
	v_cvt_pk_bf16_f32 v147, v102, v103
	v_cvt_pk_bf16_f32 v148, v124, v125
	v_cvt_pk_bf16_f32 v149, v126, v127
	global_store_dwordx4 v[112:113], v[104:107], off
	global_store_dwordx4 v[112:113], v[146:149], off offset:256
	v_cvt_pk_bf16_f32 v194, v92, v93
	v_lshl_add_u64 v[104:105], s[30:31], 0, v[180:181]
	v_cvt_pk_bf16_f32 v195, v94, v95
	v_cvt_pk_bf16_f32 v196, v88, v89
	v_cvt_pk_bf16_f32 v197, v90, v91
	v_lshl_add_u64 v[104:105], v[104:105], 0, v[170:171]
	v_cvt_pk_bf16_f32 v214, v96, v97
	v_cvt_pk_bf16_f32 v215, v136, v137
	v_cvt_pk_bf16_f32 v216, v98, v99
	v_cvt_pk_bf16_f32 v217, v138, v139
	global_store_dwordx4 v[104:105], v[194:197], off
	global_store_dwordx4 v[104:105], v[214:217], off offset:256
	v_lshl_add_u64 v[104:105], s[30:31], 0, v[178:179]
	v_cvt_pk_bf16_f32 v222, v74, v75
	v_cvt_pk_bf16_f32 v223, v80, v81
	v_cvt_pk_bf16_f32 v224, v78, v79
	v_cvt_pk_bf16_f32 v225, v82, v83
	v_lshl_add_u64 v[104:105], v[104:105], 0, v[170:171]
	v_cvt_pk_bf16_f32 v230, v84, v85
	v_cvt_pk_bf16_f32 v231, v128, v129
	v_cvt_pk_bf16_f32 v232, v86, v87
	v_cvt_pk_bf16_f32 v233, v130, v131
	global_store_dwordx4 v[104:105], v[222:225], off
	global_store_dwordx4 v[104:105], v[230:233], off offset:256
	s_waitcnt vmcnt(8)
	v_lshlrev_b32_e32 v104, 16, v210
	v_and_b32_e32 v105, 0xffff0000, v210
	v_pk_add_f32 v[60:61], v[60:61], v[104:105]
	v_lshlrev_b32_e32 v104, 16, v212
	v_and_b32_e32 v105, 0xffff0000, v212
	v_pk_add_f32 v[56:57], v[56:57], v[104:105]
	v_lshlrev_b32_e32 v104, 16, v211
	v_and_b32_e32 v105, 0xffff0000, v211
	v_pk_add_f32 v[62:63], v[62:63], v[104:105]
	v_lshlrev_b32_e32 v104, 16, v213
	v_and_b32_e32 v105, 0xffff0000, v213
	v_pk_add_f32 v[58:59], v[58:59], v[104:105]
	v_lshlrev_b32_e32 v104, 16, v218
	v_and_b32_e32 v105, 0xffff0000, v218
	v_pk_add_f32 v[52:53], v[52:53], v[104:105]
	v_lshlrev_b32_e32 v104, 16, v220
	v_and_b32_e32 v105, 0xffff0000, v220
	v_pk_add_f32 v[104:105], v[44:45], v[104:105]
	v_lshlrev_b32_e32 v44, 16, v219
	v_and_b32_e32 v45, 0xffff0000, v219
	v_pk_add_f32 v[54:55], v[54:55], v[44:45]
	v_lshlrev_b32_e32 v44, 16, v221
	v_and_b32_e32 v45, 0xffff0000, v221
	v_pk_add_f32 v[106:107], v[46:47], v[44:45]
	v_lshlrev_b32_e32 v44, 16, v226
	v_and_b32_e32 v45, 0xffff0000, v226
	v_pk_add_f32 v[44:45], v[48:49], v[44:45]
	v_lshlrev_b32_e32 v48, 16, v229
	v_and_b32_e32 v49, 0xffff0000, v229
	v_pk_add_f32 v[42:43], v[42:43], v[48:49]
	v_lshlrev_b32_e32 v48, 16, v234
	v_and_b32_e32 v49, 0xffff0000, v234
	v_pk_add_f32 v[36:37], v[36:37], v[48:49]
	v_lshlrev_b32_e32 v48, 16, v236
	v_and_b32_e32 v49, 0xffff0000, v236
	v_lshlrev_b32_e32 v46, 16, v228
	v_and_b32_e32 v47, 0xffff0000, v228
	v_pk_add_f32 v[48:49], v[28:29], v[48:49]
	v_lshlrev_b32_e32 v28, 16, v235
	v_and_b32_e32 v29, 0xffff0000, v235
	v_pk_add_f32 v[40:41], v[40:41], v[46:47]
	v_lshlrev_b32_e32 v46, 16, v227
	v_and_b32_e32 v47, 0xffff0000, v227
	v_pk_add_f32 v[38:39], v[38:39], v[28:29]
	v_lshlrev_b32_e32 v28, 16, v237
	v_and_b32_e32 v29, 0xffff0000, v237
	v_pk_add_f32 v[46:47], v[50:51], v[46:47]
	v_pk_add_f32 v[50:51], v[30:31], v[28:29]
	v_lshlrev_b32_e32 v28, 16, v238
	v_and_b32_e32 v29, 0xffff0000, v238
	v_lshlrev_b32_e32 v180, 16, v64
	v_and_b32_e32 v181, 0xffff0000, v64
	v_pk_add_f32 v[28:29], v[32:33], v[28:29]
	v_lshlrev_b32_e32 v32, 16, v241
	v_and_b32_e32 v33, 0xffff0000, v241
	v_pk_add_f32 v[4:5], v[4:5], v[180:181]
	v_lshlrev_b32_e32 v180, 16, v66
	v_and_b32_e32 v181, 0xffff0000, v66
	v_pk_add_f32 v[26:27], v[26:27], v[32:33]
	v_lshlrev_b32_e32 v32, 16, v242
	v_and_b32_e32 v33, 0xffff0000, v242
	v_pk_add_f32 v[0:1], v[0:1], v[180:181]
	v_lshl_add_u64 v[180:181], s[30:31], 0, v[182:183]
	v_cvt_pk_bf16_f32 v112, v60, v61
	v_cvt_pk_bf16_f32 v113, v62, v63
	v_cvt_pk_bf16_f32 v114, v56, v57
	v_cvt_pk_bf16_f32 v115, v58, v59
	v_pk_add_f32 v[20:21], v[20:21], v[32:33]
	v_lshlrev_b32_e32 v32, 16, v244
	v_and_b32_e32 v33, 0xffff0000, v244
	v_lshl_add_u64 v[180:181], v[180:181], 0, v[170:171]
	v_cvt_pk_bf16_f32 v116, v52, v53
	v_cvt_pk_bf16_f32 v117, v54, v55
	v_cvt_pk_bf16_f32 v118, v104, v105
	v_cvt_pk_bf16_f32 v119, v106, v107
	v_lshlrev_b32_e32 v30, 16, v240
	v_and_b32_e32 v31, 0xffff0000, v240
	v_pk_add_f32 v[32:33], v[12:13], v[32:33]
	v_lshlrev_b32_e32 v12, 16, v243
	v_and_b32_e32 v13, 0xffff0000, v243
	global_store_dwordx4 v[180:181], v[112:115], off
	global_store_dwordx4 v[180:181], v[116:119], off offset:256
	v_cvt_pk_bf16_f32 v146, v44, v45
	v_lshl_add_u64 v[112:113], s[30:31], 0, v[132:133]
	v_cvt_pk_bf16_f32 v147, v46, v47
	v_cvt_pk_bf16_f32 v148, v40, v41
	v_cvt_pk_bf16_f32 v149, v42, v43
	v_pk_add_f32 v[24:25], v[24:25], v[30:31]
	v_lshlrev_b32_e32 v30, 16, v239
	v_and_b32_e32 v31, 0xffff0000, v239
	v_pk_add_f32 v[22:23], v[22:23], v[12:13]
	v_lshlrev_b32_e32 v12, 16, v245
	v_and_b32_e32 v13, 0xffff0000, v245
	v_lshl_add_u64 v[112:113], v[112:113], 0, v[170:171]
	v_cvt_pk_bf16_f32 v172, v36, v37
	v_cvt_pk_bf16_f32 v173, v38, v39
	v_cvt_pk_bf16_f32 v174, v48, v49
	v_cvt_pk_bf16_f32 v175, v50, v51
	v_pk_add_f32 v[30:31], v[34:35], v[30:31]
	v_pk_add_f32 v[34:35], v[14:15], v[12:13]
	v_lshlrev_b32_e32 v12, 16, v246
	v_and_b32_e32 v13, 0xffff0000, v246
	v_lshlrev_b32_e32 v14, 16, v248
	v_and_b32_e32 v15, 0xffff0000, v248
	global_store_dwordx4 v[112:113], v[146:149], off
	global_store_dwordx4 v[112:113], v[172:175], off offset:256
	v_lshl_add_u64 v[112:113], s[30:31], 0, v[134:135]
	v_cvt_pk_bf16_f32 v176, v28, v29
	v_cvt_pk_bf16_f32 v177, v30, v31
	v_cvt_pk_bf16_f32 v178, v24, v25
	v_cvt_pk_bf16_f32 v179, v26, v27
	v_pk_add_f32 v[12:13], v[16:17], v[12:13]
	v_pk_add_f32 v[8:9], v[8:9], v[14:15]
	v_lshlrev_b32_e32 v14, 16, v247
	v_and_b32_e32 v15, 0xffff0000, v247
	v_lshlrev_b32_e32 v16, 16, v249
	v_and_b32_e32 v17, 0xffff0000, v249
	v_lshlrev_b32_e32 v64, 16, v65
	v_and_b32_e32 v65, 0xffff0000, v65
	v_lshl_add_u64 v[112:113], v[112:113], 0, v[170:171]
	v_cvt_pk_bf16_f32 v194, v20, v21
	v_cvt_pk_bf16_f32 v195, v22, v23
	v_cvt_pk_bf16_f32 v196, v32, v33
	v_cvt_pk_bf16_f32 v197, v34, v35
	v_pk_add_f32 v[14:15], v[18:19], v[14:15]
	v_pk_add_f32 v[10:11], v[10:11], v[16:17]
	v_pk_add_f32 v[6:7], v[6:7], v[64:65]
	v_lshlrev_b32_e32 v64, 16, v67
	v_and_b32_e32 v65, 0xffff0000, v67
	global_store_dwordx4 v[112:113], v[176:179], off
	global_store_dwordx4 v[112:113], v[194:197], off offset:256
	v_lshl_add_u64 v[112:113], s[30:31], 0, v[184:185]
	v_cvt_pk_bf16_f32 v16, v12, v13
	v_cvt_pk_bf16_f32 v17, v14, v15
	v_cvt_pk_bf16_f32 v18, v8, v9
	v_cvt_pk_bf16_f32 v19, v10, v11
	v_pk_add_f32 v[2:3], v[2:3], v[64:65]
	v_lshl_add_u64 v[112:113], v[112:113], 0, v[170:171]
	v_cvt_pk_bf16_f32 v64, v4, v5
	v_cvt_pk_bf16_f32 v65, v6, v7
	v_cvt_pk_bf16_f32 v66, v0, v1
	v_cvt_pk_bf16_f32 v67, v2, v3
	global_store_dwordx4 v[112:113], v[16:19], off
	global_store_dwordx4 v[112:113], v[64:67], off offset:256
	s_lshl_b32 s10, s81, 2
	v_and_b32_e32 v17, 64, v188
	v_xor_b32_e32 v16, 16, v188
	v_add_u32_e32 v17, 64, v17
	v_cmp_lt_i32_e32 vcc, v16, v17
	v_xor_b32_e32 v18, 32, v188
	s_ashr_i32 s11, s10, 31
	v_cndmask_b32_e32 v16, v188, v16, vcc
	v_lshlrev_b32_e32 v16, 2, v16
	v_mov_b32_e32 v132, v209
	v_cmp_lt_i32_e32 vcc, v18, v17
	s_lshl_b64 s[10:11], s[10:11], 2
	s_add_u32 s50, s75, s10
	v_cndmask_b32_e32 v17, v188, v18, vcc
	v_lshlrev_b32_e32 v17, 2, v17
	s_addc_u32 s51, s80, s11
	v_pk_mul_f32 v[18:19], v[120:121], v[120:121]
	v_pk_fma_f32 v[18:19], v[122:123], v[122:123], v[18:19]
	v_pk_fma_f32 v[18:19], v[108:109], v[108:109], v[18:19]
	v_pk_fma_f32 v[18:19], v[110:111], v[110:111], v[18:19]
	v_pk_fma_f32 v[18:19], v[100:101], v[100:101], v[18:19]
	v_pk_fma_f32 v[18:19], v[102:103], v[102:103], v[18:19]
	v_pk_fma_f32 v[18:19], v[124:125], v[124:125], v[18:19]
	v_pk_fma_f32 v[18:19], v[126:127], v[126:127], v[18:19]
	v_add_f32_e32 v18, v18, v19
	v_mov_b32_e32 v133, v18
	v_pk_mul_f32 v[18:19], v[92:93], v[92:93]
	v_pk_fma_f32 v[18:19], v[94:95], v[94:95], v[18:19]
	v_pk_fma_f32 v[18:19], v[88:89], v[88:89], v[18:19]
	v_pk_fma_f32 v[18:19], v[90:91], v[90:91], v[18:19]
	v_pk_fma_f32 v[18:19], v[96:97], v[96:97], v[18:19]
	v_pk_fma_f32 v[18:19], v[136:137], v[136:137], v[18:19]
	v_pk_fma_f32 v[18:19], v[98:99], v[98:99], v[18:19]
	v_pk_fma_f32 v[18:19], v[138:139], v[138:139], v[18:19]
	v_add_f32_e32 v18, v18, v19
	v_mov_b32_e32 v134, v18
	v_pk_mul_f32 v[18:19], v[74:75], v[74:75]
	v_pk_mul_f32 v[210:211], v[60:61], v[60:61]
	v_pk_fma_f32 v[18:19], v[80:81], v[80:81], v[18:19]
	v_pk_fma_f32 v[210:211], v[62:63], v[62:63], v[210:211]
	v_pk_fma_f32 v[18:19], v[78:79], v[78:79], v[18:19]
	v_pk_fma_f32 v[210:211], v[56:57], v[56:57], v[210:211]
	v_pk_fma_f32 v[18:19], v[82:83], v[82:83], v[18:19]
	v_pk_fma_f32 v[210:211], v[58:59], v[58:59], v[210:211]
	v_pk_fma_f32 v[18:19], v[84:85], v[84:85], v[18:19]
	v_pk_fma_f32 v[210:211], v[52:53], v[52:53], v[210:211]
	v_pk_fma_f32 v[18:19], v[128:129], v[128:129], v[18:19]
	v_pk_fma_f32 v[210:211], v[54:55], v[54:55], v[210:211]
	v_pk_fma_f32 v[18:19], v[86:87], v[86:87], v[18:19]
	v_pk_fma_f32 v[210:211], v[104:105], v[104:105], v[210:211]
	v_pk_fma_f32 v[18:19], v[130:131], v[130:131], v[18:19]
	v_pk_fma_f32 v[210:211], v[106:107], v[106:107], v[210:211]
	v_add_f32_e32 v18, v18, v19
	v_add_f32_e32 v210, v210, v211
	v_mov_b32_e32 v135, v18
	v_mov_b32_e32 v146, v210
	v_pk_mul_f32 v[18:19], v[44:45], v[44:45]
	v_pk_mul_f32 v[210:211], v[28:29], v[28:29]
	v_pk_fma_f32 v[18:19], v[46:47], v[46:47], v[18:19]
	v_pk_fma_f32 v[210:211], v[30:31], v[30:31], v[210:211]
	v_pk_fma_f32 v[18:19], v[40:41], v[40:41], v[18:19]
	v_pk_fma_f32 v[210:211], v[24:25], v[24:25], v[210:211]
	v_pk_fma_f32 v[18:19], v[42:43], v[42:43], v[18:19]
	v_pk_fma_f32 v[210:211], v[26:27], v[26:27], v[210:211]
	v_pk_fma_f32 v[18:19], v[36:37], v[36:37], v[18:19]
	v_pk_fma_f32 v[210:211], v[20:21], v[20:21], v[210:211]
	v_pk_fma_f32 v[18:19], v[38:39], v[38:39], v[18:19]
	v_pk_fma_f32 v[210:211], v[22:23], v[22:23], v[210:211]
	v_pk_fma_f32 v[18:19], v[48:49], v[48:49], v[18:19]
	v_pk_fma_f32 v[210:211], v[32:33], v[32:33], v[210:211]
	v_pk_fma_f32 v[18:19], v[50:51], v[50:51], v[18:19]
	v_pk_fma_f32 v[210:211], v[34:35], v[34:35], v[210:211]
	v_add_f32_e32 v18, v18, v19
	v_add_f32_e32 v210, v210, v211
	v_mov_b32_e32 v147, v18
	v_mov_b32_e32 v148, v210
	v_pk_mul_f32 v[18:19], v[12:13], v[12:13]
	v_pk_fma_f32 v[18:19], v[14:15], v[14:15], v[18:19]
	v_pk_fma_f32 v[18:19], v[8:9], v[8:9], v[18:19]
	v_pk_fma_f32 v[18:19], v[10:11], v[10:11], v[18:19]
	v_pk_fma_f32 v[18:19], v[4:5], v[4:5], v[18:19]
	v_pk_fma_f32 v[18:19], v[6:7], v[6:7], v[18:19]
	v_pk_fma_f32 v[18:19], v[0:1], v[0:1], v[18:19]
	v_pk_fma_f32 v[18:19], v[2:3], v[2:3], v[18:19]
	v_add_f32_e32 v0, v18, v19
	v_mov_b32_e32 v149, v0
	ds_bpermute_b32 v172, v16, v132
	ds_bpermute_b32 v173, v16, v133
	ds_bpermute_b32 v174, v16, v134
	ds_bpermute_b32 v175, v16, v135
	ds_bpermute_b32 v180, v16, v146
	ds_bpermute_b32 v181, v16, v147
	ds_bpermute_b32 v182, v16, v148
	ds_bpermute_b32 v183, v16, v149
	s_waitcnt lgkmcnt(0)
	v_add_f32_e32 v132, v132, v172
	v_add_f32_e32 v133, v133, v173
	v_add_f32_e32 v134, v134, v174
	v_add_f32_e32 v135, v135, v175
	v_add_f32_e32 v146, v146, v180
	v_add_f32_e32 v147, v147, v181
	v_add_f32_e32 v148, v148, v182
	v_add_f32_e32 v149, v149, v183
	ds_bpermute_b32 v172, v17, v132
	ds_bpermute_b32 v173, v17, v133
	ds_bpermute_b32 v174, v17, v134
	ds_bpermute_b32 v175, v17, v135
	ds_bpermute_b32 v180, v17, v146
	ds_bpermute_b32 v181, v17, v147
	ds_bpermute_b32 v182, v17, v148
	ds_bpermute_b32 v183, v17, v149
	s_and_saveexec_b64 s[52:53], s[42:43]
	s_cbranch_execz .LBB0_240
	s_waitcnt lgkmcnt(0)
	v_add_f32_e32 v132, v132, v172
	v_lshlrev_b64 v[18:19], 6, v[168:169]
	v_lshl_add_u64 v[18:19], s[50:51], 0, v[18:19]
	global_store_dword v[18:19], v132, off
	v_add_f32_e32 v133, v133, v173
	v_lshlrev_b64 v[18:19], 6, v[166:167]
	v_lshl_add_u64 v[18:19], s[50:51], 0, v[18:19]
	global_store_dword v[18:19], v133, off
	v_add_f32_e32 v134, v134, v174
	v_lshlrev_b64 v[18:19], 6, v[164:165]
	v_lshl_add_u64 v[18:19], s[50:51], 0, v[18:19]
	global_store_dword v[18:19], v134, off
	v_add_f32_e32 v135, v135, v175
	v_lshlrev_b64 v[18:19], 6, v[162:163]
	v_lshl_add_u64 v[18:19], s[50:51], 0, v[18:19]
	global_store_dword v[18:19], v135, off
	v_add_f32_e32 v146, v146, v180
	v_lshlrev_b64 v[18:19], 6, v[76:77]
	v_lshl_add_u64 v[18:19], s[50:51], 0, v[18:19]
	global_store_dword v[18:19], v146, off
	v_add_f32_e32 v147, v147, v181
	v_lshlrev_b64 v[18:19], 6, v[72:73]
	v_lshl_add_u64 v[18:19], s[50:51], 0, v[18:19]
	global_store_dword v[18:19], v147, off
	v_add_f32_e32 v148, v148, v182
	v_lshlrev_b64 v[18:19], 6, v[70:71]
	v_lshl_add_u64 v[18:19], s[50:51], 0, v[18:19]
	global_store_dword v[18:19], v148, off
	v_add_f32_e32 v149, v149, v183
	v_lshlrev_b64 v[18:19], 6, v[68:69]
	v_lshl_add_u64 v[18:19], s[50:51], 0, v[18:19]
	global_store_dword v[18:19], v149, off
	s_branch .LBB0_240

.LBB0_341:
	s_add_u32 s46, s50, 0x100
	s_addc_u32 s47, s51, 0
	s_add_i32 s6, 0, 0x10000
	v_add_u32_e32 v146, s6, v206
	ds_read_b128 v[128:131], v146
	ds_read_b128 v[132:135], v146 offset:1024
	ds_read_b128 v[136:139], v146 offset:2048
	ds_read_b128 v[146:149], v146 offset:3072
	s_cmp_eq_u32 s12, 40
	s_cselect_b32 s53, s31, s47
	s_cselect_b32 s52, s30, s46
	s_cselect_b32 s49, s35, s11
	s_cselect_b32 s48, s34, s10
	v_lshl_add_u64 v[214:215], s[50:51], 0, v[158:159]
	s_add_i32 m0, s58, 0xc000
	ds_read_b128 v[162:165], v208
	ds_read_b128 v[166:169], v208 offset:1024
	ds_read_b128 v[170:173], v208 offset:2048
	ds_read_b128 v[174:177], v208 offset:3072
	ds_read_b128 v[178:181], v208 offset:4096
	ds_read_b128 v[182:185], v208 offset:5120
	ds_read_b128 v[194:197], v208 offset:6144
	ds_read_b128 v[210:213], v208 offset:7168
	global_load_lds_dwordx4 v[214:215], off
	v_lshl_add_u64 v[214:215], s[50:51], 0, v[160:161]
	s_add_i32 m0, s58, 0xe000
	s_nop 0
	global_load_lds_dwordx4 v[214:215], off
	s_add_i32 s19, 0, 0x14000
	v_add_u32_e32 v192, s19, v206
	ds_read_b128 v[214:217], v192
	ds_read_b128 v[218:221], v192 offset:1024
	ds_read_b128 v[222:225], v192 offset:2048
	ds_read_b128 v[226:229], v192 offset:3072
	s_nop 0
	s_waitcnt vmcnt(8)
	s_waitcnt lgkmcnt(0)
	s_barrier
	v_mfma_f32_16x16x32_bf16 v[124:127], v[128:131], v[162:165], v[124:127]
	v_mfma_f32_16x16x32_bf16 v[120:123], v[136:139], v[162:165], v[120:123]
	v_mfma_f32_16x16x32_bf16 v[108:111], v[128:131], v[170:173], v[108:111]
	v_mfma_f32_16x16x32_bf16 v[104:107], v[136:139], v[170:173], v[104:107]
	v_mfma_f32_16x16x32_bf16 v[96:99], v[128:131], v[178:181], v[96:99]
	v_mfma_f32_16x16x32_bf16 v[88:91], v[136:139], v[178:181], v[88:91]
	v_mfma_f32_16x16x32_bf16 v[84:87], v[128:131], v[194:197], v[84:87]
	v_mfma_f32_16x16x32_bf16 v[80:83], v[136:139], v[194:197], v[80:83]
	v_mfma_f32_16x16x32_bf16 v[124:127], v[132:135], v[166:169], v[124:127]
	v_mfma_f32_16x16x32_bf16 v[120:123], v[146:149], v[166:169], v[120:123]
	v_mfma_f32_16x16x32_bf16 v[108:111], v[132:135], v[174:177], v[108:111]
	v_mfma_f32_16x16x32_bf16 v[104:107], v[146:149], v[174:177], v[104:107]
	v_mfma_f32_16x16x32_bf16 v[96:99], v[132:135], v[182:185], v[96:99]
	v_mfma_f32_16x16x32_bf16 v[88:91], v[146:149], v[182:185], v[88:91]
	v_mfma_f32_16x16x32_bf16 v[84:87], v[132:135], v[210:213], v[84:87]
	v_mfma_f32_16x16x32_bf16 v[80:83], v[146:149], v[210:213], v[80:83]
	v_mfma_f32_16x16x32_bf16 v[116:119], v[214:217], v[162:165], v[116:119]
	v_mfma_f32_16x16x32_bf16 v[112:115], v[222:225], v[162:165], v[112:115]
	v_mfma_f32_16x16x32_bf16 v[100:103], v[214:217], v[170:173], v[100:103]
	v_mfma_f32_16x16x32_bf16 v[92:95], v[222:225], v[170:173], v[92:95]
	v_mfma_f32_16x16x32_bf16 v[76:79], v[214:217], v[178:181], v[76:79]
	v_mfma_f32_16x16x32_bf16 v[72:75], v[222:225], v[178:181], v[72:75]
	v_mfma_f32_16x16x32_bf16 v[68:71], v[214:217], v[194:197], v[68:71]
	v_mfma_f32_16x16x32_bf16 v[64:67], v[222:225], v[194:197], v[64:67]
	v_mfma_f32_16x16x32_bf16 v[116:119], v[218:221], v[166:169], v[116:119]
	v_mfma_f32_16x16x32_bf16 v[112:115], v[226:229], v[166:169], v[112:115]
	v_mfma_f32_16x16x32_bf16 v[100:103], v[218:221], v[174:177], v[100:103]
	v_mfma_f32_16x16x32_bf16 v[92:95], v[226:229], v[174:177], v[92:95]
	v_mfma_f32_16x16x32_bf16 v[76:79], v[218:221], v[182:185], v[76:79]
	v_mfma_f32_16x16x32_bf16 v[72:75], v[226:229], v[182:185], v[72:75]
	v_mfma_f32_16x16x32_bf16 v[68:71], v[218:221], v[210:213], v[68:71]
	v_mfma_f32_16x16x32_bf16 v[64:67], v[226:229], v[210:213], v[64:67]
	s_barrier
	s_add_i32 s6, s6, s57
	v_lshl_add_u64 v[230:231], s[48:49], 0, v[140:141]
	s_mov_b32 m0, s6
	s_nop 0
	global_load_lds_dwordx4 v[230:231], off
	v_lshl_add_u64 v[232:233], s[48:49], 0, v[150:151]
	s_add_i32 m0, s6, 0x2000
	s_nop 0
	global_load_lds_dwordx4 v[232:233], off
	s_mov_b32 m0, s58
	v_lshl_add_u64 v[234:235], s[52:53], 0, v[154:155]
	ds_read_b128 v[162:165], v208 offset:16384
	ds_read_b128 v[166:169], v208 offset:17408
	ds_read_b128 v[170:173], v208 offset:18432
	ds_read_b128 v[174:177], v208 offset:19456
	ds_read_b128 v[178:181], v208 offset:20480
	ds_read_b128 v[182:185], v208 offset:21504
	ds_read_b128 v[194:197], v208 offset:22528
	ds_read_b128 v[210:213], v208 offset:23552
	global_load_lds_dwordx4 v[234:235], off
	v_lshl_add_u64 v[236:237], s[52:53], 0, v[152:153]
	s_mov_b32 m0, s59
	s_nop 0
	global_load_lds_dwordx4 v[236:237], off
	s_add_u32 s50, s48, 0xb0000
	s_addc_u32 s51, s49, 0
	s_add_i32 s6, s19, s57
	v_lshl_add_u64 v[250:251], s[50:51], 0, v[140:141]
	s_mov_b32 m0, s6
	s_nop 0
	global_load_lds_dwordx4 v[250:251], off
	v_lshl_add_u64 v[250:251], s[50:51], 0, v[150:151]
	s_add_i32 m0, s6, 0x2000
	s_nop 0
	global_load_lds_dwordx4 v[250:251], off
	s_waitcnt vmcnt(8)
	s_waitcnt lgkmcnt(0)
	s_barrier
	v_mfma_f32_16x16x32_bf16 v[60:63], v[128:131], v[162:165], v[60:63]
	v_mfma_f32_16x16x32_bf16 v[56:59], v[136:139], v[162:165], v[56:59]
	v_mfma_f32_16x16x32_bf16 v[48:51], v[128:131], v[170:173], v[48:51]
	v_mfma_f32_16x16x32_bf16 v[40:43], v[136:139], v[170:173], v[40:43]
	v_mfma_f32_16x16x32_bf16 v[32:35], v[128:131], v[178:181], v[32:35]
	v_mfma_f32_16x16x32_bf16 v[24:27], v[136:139], v[178:181], v[24:27]
	v_mfma_f32_16x16x32_bf16 v[16:19], v[128:131], v[194:197], v[16:19]
	v_mfma_f32_16x16x32_bf16 v[8:11], v[136:139], v[194:197], v[8:11]
	v_mfma_f32_16x16x32_bf16 v[60:63], v[132:135], v[166:169], v[60:63]
	v_mfma_f32_16x16x32_bf16 v[56:59], v[146:149], v[166:169], v[56:59]
	v_mfma_f32_16x16x32_bf16 v[48:51], v[132:135], v[174:177], v[48:51]
	v_mfma_f32_16x16x32_bf16 v[40:43], v[146:149], v[174:177], v[40:43]
	v_mfma_f32_16x16x32_bf16 v[32:35], v[132:135], v[182:185], v[32:35]
	v_mfma_f32_16x16x32_bf16 v[24:27], v[146:149], v[182:185], v[24:27]
	v_mfma_f32_16x16x32_bf16 v[16:19], v[132:135], v[210:213], v[16:19]
	v_mfma_f32_16x16x32_bf16 v[8:11], v[146:149], v[210:213], v[8:11]
	v_mfma_f32_16x16x32_bf16 v[52:55], v[214:217], v[162:165], v[52:55]
	v_mfma_f32_16x16x32_bf16 v[44:47], v[222:225], v[162:165], v[44:47]
	v_mfma_f32_16x16x32_bf16 v[36:39], v[214:217], v[170:173], v[36:39]
	v_mfma_f32_16x16x32_bf16 v[28:31], v[222:225], v[170:173], v[28:31]
	v_mfma_f32_16x16x32_bf16 v[20:23], v[214:217], v[178:181], v[20:23]
	v_mfma_f32_16x16x32_bf16 v[12:15], v[222:225], v[178:181], v[12:15]
	v_mfma_f32_16x16x32_bf16 v[4:7], v[214:217], v[194:197], v[4:7]
	v_mfma_f32_16x16x32_bf16 v[0:3], v[222:225], v[194:197], v[0:3]
	v_mfma_f32_16x16x32_bf16 v[52:55], v[218:221], v[166:169], v[52:55]
	v_mfma_f32_16x16x32_bf16 v[44:47], v[226:229], v[166:169], v[44:47]
	v_mfma_f32_16x16x32_bf16 v[36:39], v[218:221], v[174:177], v[36:39]
	v_mfma_f32_16x16x32_bf16 v[28:31], v[226:229], v[174:177], v[28:31]
	v_mfma_f32_16x16x32_bf16 v[20:23], v[218:221], v[182:185], v[20:23]
	v_mfma_f32_16x16x32_bf16 v[12:15], v[226:229], v[182:185], v[12:15]
	v_mfma_f32_16x16x32_bf16 v[4:7], v[218:221], v[210:213], v[4:7]
	v_mfma_f32_16x16x32_bf16 v[0:3], v[226:229], v[210:213], v[0:3]
	s_barrier
	s_add_i32 s6, 0, 0x18000
	v_add_u32_e32 v146, s6, v206
	ds_read_b128 v[128:131], v146
	ds_read_b128 v[132:135], v146 offset:1024
	ds_read_b128 v[136:139], v146 offset:2048
	ds_read_b128 v[146:149], v146 offset:3072
	s_add_u32 s50, s52, 0xb0000
	s_addc_u32 s51, s53, 0
	s_mov_b32 m0, s68
	v_lshl_add_u64 v[214:215], s[50:51], 0, v[154:155]
	ds_read_b128 v[162:165], v208 offset:32768
	ds_read_b128 v[166:169], v208 offset:33792
	ds_read_b128 v[170:173], v208 offset:34816
	ds_read_b128 v[174:177], v208 offset:35840
	ds_read_b128 v[178:181], v208 offset:36864
	ds_read_b128 v[182:185], v208 offset:37888
	ds_read_b128 v[194:197], v208 offset:38912
	ds_read_b128 v[210:213], v208 offset:39936
	global_load_lds_dwordx4 v[214:215], off
	v_lshl_add_u64 v[214:215], s[50:51], 0, v[152:153]
	s_mov_b32 m0, s69
	s_nop 0
	global_load_lds_dwordx4 v[214:215], off
	s_add_i32 s19, 0, 0x1c000
	v_add_u32_e32 v192, s19, v206
	ds_read_b128 v[214:217], v192
	ds_read_b128 v[218:221], v192 offset:1024
	ds_read_b128 v[222:225], v192 offset:2048
	ds_read_b128 v[226:229], v192 offset:3072
	s_waitcnt vmcnt(8)
	s_waitcnt lgkmcnt(0)
	s_barrier
	v_mfma_f32_16x16x32_bf16 v[124:127], v[128:131], v[162:165], v[124:127]
	v_mfma_f32_16x16x32_bf16 v[120:123], v[136:139], v[162:165], v[120:123]
	v_mfma_f32_16x16x32_bf16 v[108:111], v[128:131], v[170:173], v[108:111]
	v_mfma_f32_16x16x32_bf16 v[104:107], v[136:139], v[170:173], v[104:107]
	v_mfma_f32_16x16x32_bf16 v[96:99], v[128:131], v[178:181], v[96:99]
	v_mfma_f32_16x16x32_bf16 v[88:91], v[136:139], v[178:181], v[88:91]
	v_mfma_f32_16x16x32_bf16 v[84:87], v[128:131], v[194:197], v[84:87]
	v_mfma_f32_16x16x32_bf16 v[80:83], v[136:139], v[194:197], v[80:83]
	v_mfma_f32_16x16x32_bf16 v[124:127], v[132:135], v[166:169], v[124:127]
	v_mfma_f32_16x16x32_bf16 v[120:123], v[146:149], v[166:169], v[120:123]
	v_mfma_f32_16x16x32_bf16 v[108:111], v[132:135], v[174:177], v[108:111]
	v_mfma_f32_16x16x32_bf16 v[104:107], v[146:149], v[174:177], v[104:107]
	v_mfma_f32_16x16x32_bf16 v[96:99], v[132:135], v[182:185], v[96:99]
	v_mfma_f32_16x16x32_bf16 v[88:91], v[146:149], v[182:185], v[88:91]
	v_mfma_f32_16x16x32_bf16 v[84:87], v[132:135], v[210:213], v[84:87]
	v_mfma_f32_16x16x32_bf16 v[80:83], v[146:149], v[210:213], v[80:83]
	v_mfma_f32_16x16x32_bf16 v[116:119], v[214:217], v[162:165], v[116:119]
	v_mfma_f32_16x16x32_bf16 v[112:115], v[222:225], v[162:165], v[112:115]
	v_mfma_f32_16x16x32_bf16 v[100:103], v[214:217], v[170:173], v[100:103]
	v_mfma_f32_16x16x32_bf16 v[92:95], v[222:225], v[170:173], v[92:95]
	v_mfma_f32_16x16x32_bf16 v[76:79], v[214:217], v[178:181], v[76:79]
	v_mfma_f32_16x16x32_bf16 v[72:75], v[222:225], v[178:181], v[72:75]
	v_mfma_f32_16x16x32_bf16 v[68:71], v[214:217], v[194:197], v[68:71]
	v_mfma_f32_16x16x32_bf16 v[64:67], v[222:225], v[194:197], v[64:67]
	v_mfma_f32_16x16x32_bf16 v[116:119], v[218:221], v[166:169], v[116:119]
	v_mfma_f32_16x16x32_bf16 v[112:115], v[226:229], v[166:169], v[112:115]
	v_mfma_f32_16x16x32_bf16 v[100:103], v[218:221], v[174:177], v[100:103]
	v_mfma_f32_16x16x32_bf16 v[92:95], v[226:229], v[174:177], v[92:95]
	v_mfma_f32_16x16x32_bf16 v[76:79], v[218:221], v[182:185], v[76:79]
	v_mfma_f32_16x16x32_bf16 v[72:75], v[226:229], v[182:185], v[72:75]
	v_mfma_f32_16x16x32_bf16 v[68:71], v[218:221], v[210:213], v[68:71]
	v_mfma_f32_16x16x32_bf16 v[64:67], v[226:229], v[210:213], v[64:67]
	s_barrier
	s_add_i32 s6, s6, s57
	v_lshl_add_u64 v[230:231], v[230:231], 0, s[36:37]
	s_mov_b32 m0, s6
	s_nop 0
	global_load_lds_dwordx4 v[230:231], off
	v_lshl_add_u64 v[230:231], v[232:233], 0, s[36:37]
	s_add_i32 m0, s6, 0x2000
	s_nop 0
	global_load_lds_dwordx4 v[230:231], off
	s_mov_b32 m0, s70
	v_lshl_add_u64 v[230:231], v[234:235], 0, s[36:37]
	ds_read_b128 v[162:165], v208 offset:49152
	ds_read_b128 v[166:169], v208 offset:50176
	ds_read_b128 v[170:173], v208 offset:51200
	ds_read_b128 v[174:177], v208 offset:52224
	ds_read_b128 v[178:181], v208 offset:53248
	ds_read_b128 v[182:185], v208 offset:54272
	ds_read_b128 v[194:197], v208 offset:55296
	ds_read_b128 v[210:213], v208 offset:56320
	global_load_lds_dwordx4 v[230:231], off
	v_lshl_add_u64 v[230:231], v[236:237], 0, s[36:37]
	s_mov_b32 m0, s71
	s_nop 0
	global_load_lds_dwordx4 v[230:231], off
	s_add_u32 s48, s48, 0xb0080
	s_addc_u32 s49, s49, 0
	s_add_i32 s6, s19, s57
	v_lshl_add_u64 v[250:251], s[48:49], 0, v[140:141]
	s_mov_b32 m0, s6
	s_nop 0
	global_load_lds_dwordx4 v[250:251], off
	v_lshl_add_u64 v[250:251], s[48:49], 0, v[150:151]
	s_add_i32 m0, s6, 0x2000
	s_nop 0
	global_load_lds_dwordx4 v[250:251], off
	s_add_i32 s12, s12, 2
	s_add_u32 s10, s10, 0x100
	s_addc_u32 s11, s11, 0
	s_cmp_gt_u32 s12, 41
	s_mov_b64 s[50:51], s[46:47]
	s_waitcnt vmcnt(8)
	s_waitcnt lgkmcnt(0)
	s_barrier
	v_mfma_f32_16x16x32_bf16 v[60:63], v[128:131], v[162:165], v[60:63]
	v_mfma_f32_16x16x32_bf16 v[56:59], v[136:139], v[162:165], v[56:59]
	v_mfma_f32_16x16x32_bf16 v[48:51], v[128:131], v[170:173], v[48:51]
	v_mfma_f32_16x16x32_bf16 v[40:43], v[136:139], v[170:173], v[40:43]
	v_mfma_f32_16x16x32_bf16 v[32:35], v[128:131], v[178:181], v[32:35]
	v_mfma_f32_16x16x32_bf16 v[24:27], v[136:139], v[178:181], v[24:27]
	v_mfma_f32_16x16x32_bf16 v[16:19], v[128:131], v[194:197], v[16:19]
	v_mfma_f32_16x16x32_bf16 v[8:11], v[136:139], v[194:197], v[8:11]
	v_mfma_f32_16x16x32_bf16 v[60:63], v[132:135], v[166:169], v[60:63]
	v_mfma_f32_16x16x32_bf16 v[56:59], v[146:149], v[166:169], v[56:59]
	v_mfma_f32_16x16x32_bf16 v[48:51], v[132:135], v[174:177], v[48:51]
	v_mfma_f32_16x16x32_bf16 v[40:43], v[146:149], v[174:177], v[40:43]
	v_mfma_f32_16x16x32_bf16 v[32:35], v[132:135], v[182:185], v[32:35]
	v_mfma_f32_16x16x32_bf16 v[24:27], v[146:149], v[182:185], v[24:27]
	v_mfma_f32_16x16x32_bf16 v[16:19], v[132:135], v[210:213], v[16:19]
	v_mfma_f32_16x16x32_bf16 v[8:11], v[146:149], v[210:213], v[8:11]
	v_mfma_f32_16x16x32_bf16 v[52:55], v[214:217], v[162:165], v[52:55]
	v_mfma_f32_16x16x32_bf16 v[44:47], v[222:225], v[162:165], v[44:47]
	v_mfma_f32_16x16x32_bf16 v[36:39], v[214:217], v[170:173], v[36:39]
	v_mfma_f32_16x16x32_bf16 v[28:31], v[222:225], v[170:173], v[28:31]
	v_mfma_f32_16x16x32_bf16 v[20:23], v[214:217], v[178:181], v[20:23]
	v_mfma_f32_16x16x32_bf16 v[12:15], v[222:225], v[178:181], v[12:15]
	v_mfma_f32_16x16x32_bf16 v[4:7], v[214:217], v[194:197], v[4:7]
	v_mfma_f32_16x16x32_bf16 v[0:3], v[222:225], v[194:197], v[0:3]
	v_mfma_f32_16x16x32_bf16 v[52:55], v[218:221], v[166:169], v[52:55]
	v_mfma_f32_16x16x32_bf16 v[44:47], v[226:229], v[166:169], v[44:47]
	v_mfma_f32_16x16x32_bf16 v[36:39], v[218:221], v[174:177], v[36:39]
	v_mfma_f32_16x16x32_bf16 v[28:31], v[226:229], v[174:177], v[28:31]
	v_mfma_f32_16x16x32_bf16 v[20:23], v[218:221], v[182:185], v[20:23]
	v_mfma_f32_16x16x32_bf16 v[12:15], v[226:229], v[182:185], v[12:15]
	v_mfma_f32_16x16x32_bf16 v[4:7], v[218:221], v[210:213], v[4:7]
	v_mfma_f32_16x16x32_bf16 v[0:3], v[226:229], v[210:213], v[0:3]
	s_barrier
	s_cbranch_scc0 .LBB0_341
	s_mov_b32 s100, 1
	s_ashr_i32 s39, s38, 31
	v_lshl_or_b32 v128, s81, 8, v207
	s_lshl_b64 s[10:11], s[38:39], 8
	v_ashrrev_i32_e32 v129, 31, v128
	v_lshl_add_u64 v[168:169], s[10:11], 0, v[156:157]
	v_lshlrev_b64 v[170:171], 1, v[128:129]
	v_lshl_add_u64 v[174:175], s[26:27], 0, v[170:171]
	v_lshlrev_b64 v[172:173], 11, v[168:169]
	v_lshl_add_u64 v[128:129], v[174:175], 0, v[172:173]
	global_load_dwordx4 v[182:185], v[128:129], off
	global_load_dwordx4 v[210:213], v[128:129], off offset:256
	v_or_b32_e32 v166, 16, v168
	v_mov_b32_e32 v167, v169
	v_lshlrev_b64 v[176:177], 11, v[166:167]
	v_lshl_add_u64 v[128:129], v[174:175], 0, v[176:177]
	global_load_dwordx4 v[214:217], v[128:129], off
	global_load_dwordx4 v[218:221], v[128:129], off offset:256
	v_or_b32_e32 v164, 32, v168
	v_mov_b32_e32 v165, v169
	v_or_b32_e32 v162, 48, v168
	v_mov_b32_e32 v163, v169
	v_lshlrev_b64 v[180:181], 11, v[164:165]
	v_lshlrev_b64 v[178:179], 11, v[162:163]
	v_lshl_add_u64 v[128:129], v[174:175], 0, v[180:181]
	v_lshl_add_u64 v[130:131], v[174:175], 0, v[178:179]
	global_load_dwordx4 v[222:225], v[128:129], off
	global_load_dwordx4 v[136:139], v[128:129], off offset:256
	global_load_dwordx4 v[132:135], v[130:131], off
	s_nop 0
	global_load_dwordx4 v[128:131], v[130:131], off offset:256
	s_mov_b64 s[10:11], 0x90
	v_lshl_add_u64 v[172:173], s[28:29], 0, v[172:173]
	v_lshl_add_u64 v[172:173], v[172:173], 0, v[170:171]
	s_waitcnt vmcnt(0)
	v_lshlrev_b32_e32 v146, 16, v182
	v_and_b32_e32 v147, 0xffff0000, v182
	v_lshlrev_b32_e32 v148, 16, v184
	v_and_b32_e32 v149, 0xffff0000, v184
	v_lshlrev_b32_e32 v182, 16, v183
	v_and_b32_e32 v183, 0xffff0000, v183
	v_lshlrev_b32_e32 v194, 16, v210
	v_and_b32_e32 v195, 0xffff0000, v210
	v_lshlrev_b32_e32 v196, 16, v212
	v_and_b32_e32 v197, 0xffff0000, v212
	v_lshlrev_b32_e32 v210, 16, v211
	v_and_b32_e32 v211, 0xffff0000, v211
	v_lshlrev_b32_e32 v212, 16, v213
	v_and_b32_e32 v213, 0xffff0000, v213
	v_pk_fma_f32 v[124:125], v[124:125], 0.5, v[146:147] op_sel_hi:[1,0,1]
	v_pk_fma_f32 v[120:121], v[120:121], 0.5, v[148:149] op_sel_hi:[1,0,1]
	v_pk_fma_f32 v[126:127], v[126:127], 0.5, v[182:183] op_sel_hi:[1,0,1]
	v_pk_fma_f32 v[116:117], v[116:117], 0.5, v[194:195] op_sel_hi:[1,0,1]
	v_pk_fma_f32 v[146:147], v[112:113], 0.5, v[196:197] op_sel_hi:[1,0,1]
	v_pk_fma_f32 v[118:119], v[118:119], 0.5, v[210:211] op_sel_hi:[1,0,1]
	v_pk_fma_f32 v[148:149], v[114:115], 0.5, v[212:213] op_sel_hi:[1,0,1]
	v_pk_mul_f32 v[212:213], v[124:125], v[124:125]
	v_lshlrev_b32_e32 v182, 16, v214
	v_and_b32_e32 v183, 0xffff0000, v214
	v_lshlrev_b32_e32 v194, 16, v215
	v_and_b32_e32 v195, 0xffff0000, v215
	v_pk_mul_f32 v[214:215], v[126:127], v[126:127]
	v_cvt_pk_bf16_f32 v112, v124, v125
	v_cvt_pk_bf16_f32 v113, v126, v127
	v_pk_mul_f32 v[124:125], v[116:117], v[116:117]
	v_pk_mul_f32 v[126:127], v[118:119], v[118:119]
	v_pk_mul_f32 v[228:229], v[146:147], v[146:147]
	v_cvt_pk_bf16_f32 v116, v116, v117
	v_cvt_pk_bf16_f32 v117, v118, v119
	v_cvt_pk_bf16_f32 v118, v146, v147
	v_add_f32_e32 v146, v212, v213
	v_lshlrev_b32_e32 v184, 16, v185
	v_and_b32_e32 v185, 0xffff0000, v185
	v_add_f32_e32 v146, v214, v146
	v_pk_fma_f32 v[122:123], v[122:123], 0.5, v[184:185] op_sel_hi:[1,0,1]
	v_lshlrev_b32_e32 v184, 16, v216
	v_and_b32_e32 v185, 0xffff0000, v216
	v_lshlrev_b32_e32 v196, 16, v217
	v_and_b32_e32 v197, 0xffff0000, v217
	v_pk_mul_f32 v[216:217], v[120:121], v[120:121]
	v_add_f32_e32 v146, v215, v146
	v_add_f32_e32 v146, v216, v146
	v_pk_mul_f32 v[226:227], v[122:123], v[122:123]
	v_add_f32_e32 v146, v217, v146
	v_add_f32_e32 v146, v226, v146
	v_add_f32_e32 v146, v227, v146
	v_add_f32_e32 v124, v124, v146
	v_add_f32_e32 v124, v125, v124
	v_add_f32_e32 v124, v126, v124
	v_add_f32_e32 v124, v127, v124
	v_add_f32_e32 v124, v228, v124
	v_pk_mul_f32 v[230:231], v[148:149], v[148:149]
	v_add_f32_e32 v124, v229, v124
	v_add_f32_e32 v124, v230, v124
	v_add_f32_e32 v209, v231, v124
	v_lshlrev_b32_e32 v124, 16, v220
	v_and_b32_e32 v125, 0xffff0000, v220
	v_pk_fma_f32 v[124:125], v[92:93], 0.5, v[124:125] op_sel_hi:[1,0,1]
	v_lshlrev_b32_e32 v92, 16, v219
	v_and_b32_e32 v93, 0xffff0000, v219
	v_pk_fma_f32 v[102:103], v[102:103], 0.5, v[92:93] op_sel_hi:[1,0,1]
	v_lshlrev_b32_e32 v92, 16, v221
	v_and_b32_e32 v93, 0xffff0000, v221
	v_pk_fma_f32 v[126:127], v[94:95], 0.5, v[92:93] op_sel_hi:[1,0,1]
	v_lshlrev_b32_e32 v92, 16, v222
	v_and_b32_e32 v93, 0xffff0000, v222
	v_pk_fma_f32 v[92:93], v[96:97], 0.5, v[92:93] op_sel_hi:[1,0,1]
	v_lshlrev_b32_e32 v96, 16, v225
	v_and_b32_e32 v97, 0xffff0000, v225
	v_lshlrev_b32_e32 v94, 16, v224
	v_and_b32_e32 v95, 0xffff0000, v224
	v_pk_fma_f32 v[90:91], v[90:91], 0.5, v[96:97] op_sel_hi:[1,0,1]
	v_lshlrev_b32_e32 v96, 16, v136
	v_and_b32_e32 v97, 0xffff0000, v136
	v_pk_fma_f32 v[88:89], v[88:89], 0.5, v[94:95] op_sel_hi:[1,0,1]
	v_lshlrev_b32_e32 v94, 16, v223
	v_and_b32_e32 v95, 0xffff0000, v223
	v_pk_fma_f32 v[96:97], v[76:77], 0.5, v[96:97] op_sel_hi:[1,0,1]
	v_lshl_add_u64 v[76:77], v[168:169], 0, s[36:37]
	v_cvt_pk_bf16_f32 v114, v120, v121
	v_pk_fma_f32 v[120:121], v[108:109], 0.5, v[182:183] op_sel_hi:[1,0,1]
	v_pk_fma_f32 v[94:95], v[98:99], 0.5, v[94:95] op_sel_hi:[1,0,1]
	v_lshlrev_b64 v[182:183], 11, v[76:77]
	v_lshlrev_b32_e32 v98, 16, v138
	v_and_b32_e32 v99, 0xffff0000, v138
	v_lshl_add_u64 v[146:147], v[174:175], 0, v[182:183]
	v_pk_fma_f32 v[98:99], v[72:73], 0.5, v[98:99] op_sel_hi:[1,0,1]
	v_lshlrev_b32_e32 v72, 16, v137
	v_and_b32_e32 v73, 0xffff0000, v137
	v_lshlrev_b32_e32 v210, 16, v218
	v_and_b32_e32 v211, 0xffff0000, v218
	global_load_dwordx4 v[218:221], v[146:147], off
	global_load_dwordx4 v[226:229], v[146:147], off offset:256
	v_pk_fma_f32 v[136:137], v[78:79], 0.5, v[72:73] op_sel_hi:[1,0,1]
	v_lshlrev_b32_e32 v72, 16, v139
	v_and_b32_e32 v73, 0xffff0000, v139
	v_pk_fma_f32 v[138:139], v[74:75], 0.5, v[72:73] op_sel_hi:[1,0,1]
	v_lshlrev_b32_e32 v72, 16, v132
	v_and_b32_e32 v73, 0xffff0000, v132
	v_pk_fma_f32 v[74:75], v[84:85], 0.5, v[72:73] op_sel_hi:[1,0,1]
	v_lshlrev_b32_e32 v72, 16, v134
	v_and_b32_e32 v73, 0xffff0000, v134
	v_pk_fma_f32 v[78:79], v[80:81], 0.5, v[72:73] op_sel_hi:[1,0,1]
	v_lshlrev_b32_e32 v72, 16, v133
	v_and_b32_e32 v73, 0xffff0000, v133
	v_pk_fma_f32 v[80:81], v[86:87], 0.5, v[72:73] op_sel_hi:[1,0,1]
	v_lshlrev_b32_e32 v72, 16, v135
	v_and_b32_e32 v73, 0xffff0000, v135
	v_pk_fma_f32 v[82:83], v[82:83], 0.5, v[72:73] op_sel_hi:[1,0,1]
	v_lshl_add_u64 v[72:73], v[168:169], 0, s[10:11]
	v_lshlrev_b64 v[132:133], 11, v[72:73]
	v_lshl_add_u64 v[134:135], v[174:175], 0, v[132:133]
	global_load_dwordx4 v[234:237], v[134:135], off
	global_load_dwordx4 v[242:245], v[134:135], off offset:256
	v_lshlrev_b32_e32 v84, 16, v128
	v_and_b32_e32 v85, 0xffff0000, v128
	v_pk_fma_f32 v[84:85], v[68:69], 0.5, v[84:85] op_sel_hi:[1,0,1]
	v_lshlrev_b32_e32 v68, 16, v130
	v_and_b32_e32 v69, 0xffff0000, v130
	v_pk_fma_f32 v[86:87], v[64:65], 0.5, v[68:69] op_sel_hi:[1,0,1]
	v_lshlrev_b32_e32 v64, 16, v129
	v_and_b32_e32 v65, 0xffff0000, v129
	s_mov_b64 s[10:11], 0xa0
	v_pk_fma_f32 v[128:129], v[70:71], 0.5, v[64:65] op_sel_hi:[1,0,1]
	v_lshl_add_u64 v[70:71], v[168:169], 0, s[10:11]
	v_lshlrev_b32_e32 v64, 16, v131
	v_and_b32_e32 v65, 0xffff0000, v131
	v_lshlrev_b64 v[134:135], 11, v[70:71]
	v_pk_fma_f32 v[130:131], v[66:67], 0.5, v[64:65] op_sel_hi:[1,0,1]
	v_lshl_add_u64 v[64:65], v[174:175], 0, v[134:135]
	v_cvt_pk_bf16_f32 v115, v122, v123
	v_pk_fma_f32 v[122:123], v[110:111], 0.5, v[194:195] op_sel_hi:[1,0,1]
	v_pk_fma_f32 v[110:111], v[106:107], 0.5, v[196:197] op_sel_hi:[1,0,1]
	global_load_dwordx4 v[246:249], v[64:65], off
	global_load_dwordx4 v[194:197], v[64:65], off offset:256
	s_mov_b64 s[10:11], 0xb0
	v_lshl_add_u64 v[68:69], v[168:169], 0, s[10:11]
	v_pk_fma_f32 v[108:109], v[104:105], 0.5, v[184:185] op_sel_hi:[1,0,1]
	v_lshlrev_b64 v[184:185], 11, v[68:69]
	v_lshl_add_u64 v[64:65], v[174:175], 0, v[184:185]
	v_cvt_pk_bf16_f32 v119, v148, v149
	global_load_dwordx4 v[146:149], v[64:65], off
	s_nop 0
	global_load_dwordx4 v[64:67], v[64:65], off offset:256
	global_store_dwordx4 v[172:173], v[112:115], off
	global_store_dwordx4 v[172:173], v[116:119], off offset:256
	v_cvt_pk_bf16_f32 v104, v120, v121
	v_lshl_add_u64 v[112:113], s[28:29], 0, v[176:177]
	v_cvt_pk_bf16_f32 v105, v122, v123
	v_cvt_pk_bf16_f32 v106, v108, v109
	v_cvt_pk_bf16_f32 v107, v110, v111
	v_pk_fma_f32 v[100:101], v[100:101], 0.5, v[210:211] op_sel_hi:[1,0,1]
	v_lshl_add_u64 v[112:113], v[112:113], 0, v[170:171]
	v_cvt_pk_bf16_f32 v210, v100, v101
	v_cvt_pk_bf16_f32 v211, v102, v103
	v_cvt_pk_bf16_f32 v212, v124, v125
	v_cvt_pk_bf16_f32 v213, v126, v127
	global_store_dwordx4 v[112:113], v[104:107], off
	global_store_dwordx4 v[112:113], v[210:213], off offset:256
	v_cvt_pk_bf16_f32 v214, v92, v93
	v_lshl_add_u64 v[104:105], s[28:29], 0, v[180:181]
	v_cvt_pk_bf16_f32 v215, v94, v95
	v_cvt_pk_bf16_f32 v216, v88, v89
	v_cvt_pk_bf16_f32 v217, v90, v91
	v_lshl_add_u64 v[104:105], v[104:105], 0, v[170:171]
	v_cvt_pk_bf16_f32 v222, v96, v97
	v_cvt_pk_bf16_f32 v223, v136, v137
	v_cvt_pk_bf16_f32 v224, v98, v99
	v_cvt_pk_bf16_f32 v225, v138, v139
	global_store_dwordx4 v[104:105], v[214:217], off
	global_store_dwordx4 v[104:105], v[222:225], off offset:256
	v_lshl_add_u64 v[104:105], s[28:29], 0, v[178:179]
	v_cvt_pk_bf16_f32 v230, v74, v75
	v_cvt_pk_bf16_f32 v231, v80, v81
	v_cvt_pk_bf16_f32 v232, v78, v79
	v_cvt_pk_bf16_f32 v233, v82, v83
	v_lshl_add_u64 v[104:105], v[104:105], 0, v[170:171]
	v_cvt_pk_bf16_f32 v238, v84, v85
	v_cvt_pk_bf16_f32 v239, v128, v129
	v_cvt_pk_bf16_f32 v240, v86, v87
	v_cvt_pk_bf16_f32 v241, v130, v131
	global_store_dwordx4 v[104:105], v[230:233], off
	global_store_dwordx4 v[104:105], v[238:241], off offset:256
	s_waitcnt vmcnt(8)
	v_lshlrev_b32_e32 v104, 16, v218
	v_and_b32_e32 v105, 0xffff0000, v218
	v_pk_fma_f32 v[60:61], v[60:61], 0.5, v[104:105] op_sel_hi:[1,0,1]
	v_lshlrev_b32_e32 v104, 16, v220
	v_and_b32_e32 v105, 0xffff0000, v220
	v_pk_fma_f32 v[56:57], v[56:57], 0.5, v[104:105] op_sel_hi:[1,0,1]
	v_lshlrev_b32_e32 v104, 16, v219
	v_and_b32_e32 v105, 0xffff0000, v219
	v_pk_fma_f32 v[62:63], v[62:63], 0.5, v[104:105] op_sel_hi:[1,0,1]
	v_lshlrev_b32_e32 v104, 16, v221
	v_and_b32_e32 v105, 0xffff0000, v221
	v_pk_fma_f32 v[58:59], v[58:59], 0.5, v[104:105] op_sel_hi:[1,0,1]
	v_lshlrev_b32_e32 v104, 16, v226
	v_and_b32_e32 v105, 0xffff0000, v226
	v_pk_fma_f32 v[52:53], v[52:53], 0.5, v[104:105] op_sel_hi:[1,0,1]
	v_lshlrev_b32_e32 v104, 16, v228
	v_and_b32_e32 v105, 0xffff0000, v228
	v_pk_fma_f32 v[104:105], v[44:45], 0.5, v[104:105] op_sel_hi:[1,0,1]
	v_lshlrev_b32_e32 v44, 16, v227
	v_and_b32_e32 v45, 0xffff0000, v227
	v_pk_fma_f32 v[54:55], v[54:55], 0.5, v[44:45] op_sel_hi:[1,0,1]
	v_lshlrev_b32_e32 v44, 16, v229
	v_and_b32_e32 v45, 0xffff0000, v229
	v_pk_fma_f32 v[106:107], v[46:47], 0.5, v[44:45] op_sel_hi:[1,0,1]
	v_lshlrev_b32_e32 v44, 16, v234
	v_and_b32_e32 v45, 0xffff0000, v234
	v_pk_fma_f32 v[44:45], v[48:49], 0.5, v[44:45] op_sel_hi:[1,0,1]
	v_lshlrev_b32_e32 v48, 16, v237
	v_and_b32_e32 v49, 0xffff0000, v237
	v_pk_fma_f32 v[42:43], v[42:43], 0.5, v[48:49] op_sel_hi:[1,0,1]
	v_lshlrev_b32_e32 v48, 16, v242
	v_and_b32_e32 v49, 0xffff0000, v242
	v_pk_fma_f32 v[36:37], v[36:37], 0.5, v[48:49] op_sel_hi:[1,0,1]
	v_lshlrev_b32_e32 v48, 16, v244
	v_and_b32_e32 v49, 0xffff0000, v244
	v_lshlrev_b32_e32 v46, 16, v236
	v_and_b32_e32 v47, 0xffff0000, v236
	v_pk_fma_f32 v[48:49], v[28:29], 0.5, v[48:49] op_sel_hi:[1,0,1]
	v_lshlrev_b32_e32 v28, 16, v243
	v_and_b32_e32 v29, 0xffff0000, v243
	v_pk_fma_f32 v[40:41], v[40:41], 0.5, v[46:47] op_sel_hi:[1,0,1]
	v_lshlrev_b32_e32 v46, 16, v235
	v_and_b32_e32 v47, 0xffff0000, v235
	v_pk_fma_f32 v[38:39], v[38:39], 0.5, v[28:29] op_sel_hi:[1,0,1]
	v_lshlrev_b32_e32 v28, 16, v245
	v_and_b32_e32 v29, 0xffff0000, v245
	v_pk_fma_f32 v[46:47], v[50:51], 0.5, v[46:47] op_sel_hi:[1,0,1]
	v_pk_fma_f32 v[50:51], v[30:31], 0.5, v[28:29] op_sel_hi:[1,0,1]
	v_lshlrev_b32_e32 v28, 16, v246
	v_and_b32_e32 v29, 0xffff0000, v246
	v_pk_fma_f32 v[28:29], v[32:33], 0.5, v[28:29] op_sel_hi:[1,0,1]
	v_lshlrev_b32_e32 v32, 16, v249
	v_and_b32_e32 v33, 0xffff0000, v249
	v_pk_fma_f32 v[26:27], v[26:27], 0.5, v[32:33] op_sel_hi:[1,0,1]
	v_lshlrev_b32_e32 v32, 16, v194
	v_and_b32_e32 v33, 0xffff0000, v194
	v_pk_fma_f32 v[20:21], v[20:21], 0.5, v[32:33] op_sel_hi:[1,0,1]
	v_lshlrev_b32_e32 v32, 16, v196
	v_and_b32_e32 v33, 0xffff0000, v196
	v_lshlrev_b32_e32 v30, 16, v248
	v_and_b32_e32 v31, 0xffff0000, v248
	v_pk_fma_f32 v[32:33], v[12:13], 0.5, v[32:33] op_sel_hi:[1,0,1]
	v_lshlrev_b32_e32 v12, 16, v195
	v_and_b32_e32 v13, 0xffff0000, v195
	v_pk_fma_f32 v[24:25], v[24:25], 0.5, v[30:31] op_sel_hi:[1,0,1]
	v_lshlrev_b32_e32 v30, 16, v247
	v_and_b32_e32 v31, 0xffff0000, v247
	v_pk_fma_f32 v[22:23], v[22:23], 0.5, v[12:13] op_sel_hi:[1,0,1]
	v_lshlrev_b32_e32 v12, 16, v197
	v_and_b32_e32 v13, 0xffff0000, v197
	v_pk_fma_f32 v[30:31], v[34:35], 0.5, v[30:31] op_sel_hi:[1,0,1]
	v_pk_fma_f32 v[34:35], v[14:15], 0.5, v[12:13] op_sel_hi:[1,0,1]
	v_lshlrev_b32_e32 v14, 16, v148
	v_and_b32_e32 v15, 0xffff0000, v148
	v_lshlrev_b32_e32 v12, 16, v146
	v_and_b32_e32 v13, 0xffff0000, v146
	v_pk_fma_f32 v[8:9], v[8:9], 0.5, v[14:15] op_sel_hi:[1,0,1]
	v_lshlrev_b32_e32 v14, 16, v147
	v_and_b32_e32 v15, 0xffff0000, v147
	v_lshlrev_b32_e32 v146, 16, v64
	v_and_b32_e32 v147, 0xffff0000, v64
	v_pk_fma_f32 v[4:5], v[4:5], 0.5, v[146:147] op_sel_hi:[1,0,1]
	v_lshlrev_b32_e32 v146, 16, v66
	v_and_b32_e32 v147, 0xffff0000, v66
	v_pk_fma_f32 v[0:1], v[0:1], 0.5, v[146:147] op_sel_hi:[1,0,1]
	v_lshl_add_u64 v[146:147], s[28:29], 0, v[182:183]
	v_cvt_pk_bf16_f32 v112, v60, v61
	v_cvt_pk_bf16_f32 v113, v62, v63
	v_cvt_pk_bf16_f32 v114, v56, v57
	v_cvt_pk_bf16_f32 v115, v58, v59
	v_lshl_add_u64 v[146:147], v[146:147], 0, v[170:171]
	v_cvt_pk_bf16_f32 v116, v52, v53
	v_cvt_pk_bf16_f32 v117, v54, v55
	v_cvt_pk_bf16_f32 v118, v104, v105
	v_cvt_pk_bf16_f32 v119, v106, v107
	global_store_dwordx4 v[146:147], v[112:115], off
	global_store_dwordx4 v[146:147], v[116:119], off offset:256
	v_cvt_pk_bf16_f32 v172, v44, v45
	v_lshl_add_u64 v[112:113], s[28:29], 0, v[132:133]
	v_cvt_pk_bf16_f32 v173, v46, v47
	v_cvt_pk_bf16_f32 v174, v40, v41
	v_cvt_pk_bf16_f32 v175, v42, v43
	v_lshl_add_u64 v[112:113], v[112:113], 0, v[170:171]
	v_cvt_pk_bf16_f32 v176, v36, v37
	v_cvt_pk_bf16_f32 v177, v38, v39
	v_cvt_pk_bf16_f32 v178, v48, v49
	v_cvt_pk_bf16_f32 v179, v50, v51
	global_store_dwordx4 v[112:113], v[172:175], off
	global_store_dwordx4 v[112:113], v[176:179], off offset:256
	v_lshl_add_u64 v[112:113], s[28:29], 0, v[134:135]
	v_cvt_pk_bf16_f32 v210, v28, v29
	v_cvt_pk_bf16_f32 v211, v30, v31
	v_cvt_pk_bf16_f32 v212, v24, v25
	v_cvt_pk_bf16_f32 v213, v26, v27
	v_pk_fma_f32 v[12:13], v[16:17], 0.5, v[12:13] op_sel_hi:[1,0,1]
	v_lshlrev_b32_e32 v16, 16, v149
	v_and_b32_e32 v17, 0xffff0000, v149
	v_lshlrev_b32_e32 v64, 16, v65
	v_and_b32_e32 v65, 0xffff0000, v65
	v_lshl_add_u64 v[112:113], v[112:113], 0, v[170:171]
	v_cvt_pk_bf16_f32 v194, v20, v21
	v_cvt_pk_bf16_f32 v195, v22, v23
	v_cvt_pk_bf16_f32 v196, v32, v33
	v_cvt_pk_bf16_f32 v197, v34, v35
	v_pk_fma_f32 v[14:15], v[18:19], 0.5, v[14:15] op_sel_hi:[1,0,1]
	v_pk_fma_f32 v[10:11], v[10:11], 0.5, v[16:17] op_sel_hi:[1,0,1]
	v_pk_fma_f32 v[6:7], v[6:7], 0.5, v[64:65] op_sel_hi:[1,0,1]
	v_lshlrev_b32_e32 v64, 16, v67
	v_and_b32_e32 v65, 0xffff0000, v67
	global_store_dwordx4 v[112:113], v[210:213], off
	global_store_dwordx4 v[112:113], v[194:197], off offset:256
	v_lshl_add_u64 v[112:113], s[28:29], 0, v[184:185]
	v_cvt_pk_bf16_f32 v16, v12, v13
	v_cvt_pk_bf16_f32 v17, v14, v15
	v_cvt_pk_bf16_f32 v18, v8, v9
	v_cvt_pk_bf16_f32 v19, v10, v11
	v_pk_fma_f32 v[2:3], v[2:3], 0.5, v[64:65] op_sel_hi:[1,0,1]
	v_lshl_add_u64 v[112:113], v[112:113], 0, v[170:171]
	v_cvt_pk_bf16_f32 v64, v4, v5
	v_cvt_pk_bf16_f32 v65, v6, v7
	v_cvt_pk_bf16_f32 v66, v0, v1
	v_cvt_pk_bf16_f32 v67, v2, v3
	global_store_dwordx4 v[112:113], v[16:19], off
	global_store_dwordx4 v[112:113], v[64:67], off offset:256
	s_lshl_b32 s10, s81, 2
	v_and_b32_e32 v17, 64, v188
	v_xor_b32_e32 v16, 16, v188
	v_add_u32_e32 v17, 64, v17
	v_cmp_lt_i32_e32 vcc, v16, v17
	v_xor_b32_e32 v18, 32, v188
	s_ashr_i32 s11, s10, 31
	v_cndmask_b32_e32 v16, v188, v16, vcc
	v_lshlrev_b32_e32 v16, 2, v16
	v_mov_b32_e32 v132, v209
	v_cmp_lt_i32_e32 vcc, v18, v17
	s_lshl_b64 s[10:11], s[10:11], 2
	s_add_u32 s38, s73, s10
	v_cndmask_b32_e32 v17, v188, v18, vcc
	v_lshlrev_b32_e32 v17, 2, v17
	s_addc_u32 s39, s74, s11
	v_pk_mul_f32 v[18:19], v[120:121], v[120:121]
	v_pk_fma_f32 v[18:19], v[122:123], v[122:123], v[18:19]
	v_pk_fma_f32 v[18:19], v[108:109], v[108:109], v[18:19]
	v_pk_fma_f32 v[18:19], v[110:111], v[110:111], v[18:19]
	v_pk_fma_f32 v[18:19], v[100:101], v[100:101], v[18:19]
	v_pk_fma_f32 v[18:19], v[102:103], v[102:103], v[18:19]
	v_pk_fma_f32 v[18:19], v[124:125], v[124:125], v[18:19]
	v_pk_fma_f32 v[18:19], v[126:127], v[126:127], v[18:19]
	v_add_f32_e32 v18, v18, v19
	v_mov_b32_e32 v133, v18
	v_pk_mul_f32 v[18:19], v[92:93], v[92:93]
	v_pk_fma_f32 v[18:19], v[94:95], v[94:95], v[18:19]
	v_pk_fma_f32 v[18:19], v[88:89], v[88:89], v[18:19]
	v_pk_fma_f32 v[18:19], v[90:91], v[90:91], v[18:19]
	v_pk_fma_f32 v[18:19], v[96:97], v[96:97], v[18:19]
	v_pk_fma_f32 v[18:19], v[136:137], v[136:137], v[18:19]
	v_pk_fma_f32 v[18:19], v[98:99], v[98:99], v[18:19]
	v_pk_fma_f32 v[18:19], v[138:139], v[138:139], v[18:19]
	v_add_f32_e32 v18, v18, v19
	v_mov_b32_e32 v134, v18
	v_pk_mul_f32 v[18:19], v[74:75], v[74:75]
	v_pk_mul_f32 v[180:181], v[60:61], v[60:61]
	v_pk_fma_f32 v[18:19], v[80:81], v[80:81], v[18:19]
	v_pk_fma_f32 v[180:181], v[62:63], v[62:63], v[180:181]
	v_pk_fma_f32 v[18:19], v[78:79], v[78:79], v[18:19]
	v_pk_fma_f32 v[180:181], v[56:57], v[56:57], v[180:181]
	v_pk_fma_f32 v[18:19], v[82:83], v[82:83], v[18:19]
	v_pk_fma_f32 v[180:181], v[58:59], v[58:59], v[180:181]
	v_pk_fma_f32 v[18:19], v[84:85], v[84:85], v[18:19]
	v_pk_fma_f32 v[180:181], v[52:53], v[52:53], v[180:181]
	v_pk_fma_f32 v[18:19], v[128:129], v[128:129], v[18:19]
	v_pk_fma_f32 v[180:181], v[54:55], v[54:55], v[180:181]
	v_pk_fma_f32 v[18:19], v[86:87], v[86:87], v[18:19]
	v_pk_fma_f32 v[180:181], v[104:105], v[104:105], v[180:181]
	v_pk_fma_f32 v[18:19], v[130:131], v[130:131], v[18:19]
	v_pk_fma_f32 v[180:181], v[106:107], v[106:107], v[180:181]
	v_add_f32_e32 v18, v18, v19
	v_add_f32_e32 v180, v180, v181
	v_mov_b32_e32 v135, v18
	v_mov_b32_e32 v146, v180
	v_pk_mul_f32 v[18:19], v[44:45], v[44:45]
	v_pk_mul_f32 v[180:181], v[28:29], v[28:29]
	v_pk_fma_f32 v[18:19], v[46:47], v[46:47], v[18:19]
	v_pk_fma_f32 v[180:181], v[30:31], v[30:31], v[180:181]
	v_pk_fma_f32 v[18:19], v[40:41], v[40:41], v[18:19]
	v_pk_fma_f32 v[180:181], v[24:25], v[24:25], v[180:181]
	v_pk_fma_f32 v[18:19], v[42:43], v[42:43], v[18:19]
	v_pk_fma_f32 v[180:181], v[26:27], v[26:27], v[180:181]
	v_pk_fma_f32 v[18:19], v[36:37], v[36:37], v[18:19]
	v_pk_fma_f32 v[180:181], v[20:21], v[20:21], v[180:181]
	v_pk_fma_f32 v[18:19], v[38:39], v[38:39], v[18:19]
	v_pk_fma_f32 v[180:181], v[22:23], v[22:23], v[180:181]
	v_pk_fma_f32 v[18:19], v[48:49], v[48:49], v[18:19]
	v_pk_fma_f32 v[180:181], v[32:33], v[32:33], v[180:181]
	v_pk_fma_f32 v[18:19], v[50:51], v[50:51], v[18:19]
	v_pk_fma_f32 v[180:181], v[34:35], v[34:35], v[180:181]
	v_add_f32_e32 v18, v18, v19
	v_add_f32_e32 v180, v180, v181
	v_mov_b32_e32 v147, v18
	v_mov_b32_e32 v148, v180
	v_pk_mul_f32 v[18:19], v[12:13], v[12:13]
	v_pk_fma_f32 v[18:19], v[14:15], v[14:15], v[18:19]
	v_pk_fma_f32 v[18:19], v[8:9], v[8:9], v[18:19]
	v_pk_fma_f32 v[18:19], v[10:11], v[10:11], v[18:19]
	v_pk_fma_f32 v[18:19], v[4:5], v[4:5], v[18:19]
	v_pk_fma_f32 v[18:19], v[6:7], v[6:7], v[18:19]
	v_pk_fma_f32 v[18:19], v[0:1], v[0:1], v[18:19]
	v_pk_fma_f32 v[18:19], v[2:3], v[2:3], v[18:19]
	v_add_f32_e32 v0, v18, v19
	v_mov_b32_e32 v149, v0
	ds_bpermute_b32 v172, v16, v132
	ds_bpermute_b32 v173, v16, v133
	ds_bpermute_b32 v174, v16, v134
	ds_bpermute_b32 v175, v16, v135
	ds_bpermute_b32 v176, v16, v146
	ds_bpermute_b32 v177, v16, v147
	ds_bpermute_b32 v178, v16, v148
	ds_bpermute_b32 v179, v16, v149
	s_waitcnt lgkmcnt(0)
	v_add_f32_e32 v132, v132, v172
	v_add_f32_e32 v133, v133, v173
	v_add_f32_e32 v134, v134, v174
	v_add_f32_e32 v135, v135, v175
	v_add_f32_e32 v146, v146, v176
	v_add_f32_e32 v147, v147, v177
	v_add_f32_e32 v148, v148, v178
	v_add_f32_e32 v149, v149, v179
	ds_bpermute_b32 v172, v17, v132
	ds_bpermute_b32 v173, v17, v133
	ds_bpermute_b32 v174, v17, v134
	ds_bpermute_b32 v175, v17, v135
	ds_bpermute_b32 v176, v17, v146
	ds_bpermute_b32 v177, v17, v147
	ds_bpermute_b32 v178, v17, v148
	ds_bpermute_b32 v179, v17, v149
	s_and_saveexec_b64 s[46:47], s[42:43]
	s_cbranch_execz .LBB0_329
	s_waitcnt lgkmcnt(0)
	v_add_f32_e32 v132, v132, v172
	v_lshlrev_b64 v[18:19], 6, v[168:169]
	v_lshl_add_u64 v[18:19], s[38:39], 0, v[18:19]
	global_store_dword v[18:19], v132, off
	v_add_f32_e32 v133, v133, v173
	v_lshlrev_b64 v[18:19], 6, v[166:167]
	v_lshl_add_u64 v[18:19], s[38:39], 0, v[18:19]
	global_store_dword v[18:19], v133, off
	v_add_f32_e32 v134, v134, v174
	v_lshlrev_b64 v[18:19], 6, v[164:165]
	v_lshl_add_u64 v[18:19], s[38:39], 0, v[18:19]
	global_store_dword v[18:19], v134, off
	v_add_f32_e32 v135, v135, v175
	v_lshlrev_b64 v[18:19], 6, v[162:163]
	v_lshl_add_u64 v[18:19], s[38:39], 0, v[18:19]
	global_store_dword v[18:19], v135, off
	v_add_f32_e32 v146, v146, v176
	v_lshlrev_b64 v[18:19], 6, v[76:77]
	v_lshl_add_u64 v[18:19], s[38:39], 0, v[18:19]
	global_store_dword v[18:19], v146, off
	v_add_f32_e32 v147, v147, v177
	v_lshlrev_b64 v[18:19], 6, v[72:73]
	v_lshl_add_u64 v[18:19], s[38:39], 0, v[18:19]
	global_store_dword v[18:19], v147, off
	v_add_f32_e32 v148, v148, v178
	v_lshlrev_b64 v[18:19], 6, v[70:71]
	v_lshl_add_u64 v[18:19], s[38:39], 0, v[18:19]
	global_store_dword v[18:19], v148, off
	v_add_f32_e32 v149, v149, v179
	v_lshlrev_b64 v[18:19], 6, v[68:69]
	v_lshl_add_u64 v[18:19], s[38:39], 0, v[18:19]
	global_store_dword v[18:19], v149, off
	s_branch .LBB0_329
